# EpiResid ssq row-sum: xor16/xor32 lane exchange via v_permlane16/32_swap instead of two serialized ds_bpermute per row group (G2/G5/G7); on top of v51
# speedup vs baseline: 1.0001x; 1.0001x over previous
;     template <int QVV> __device__ __forceinline__ void run(f32x4 (&acc)[2][2][4][2], const Unit& u, int wr, int wc, int fr, int fq) const {
;         const bool qm = u.seg != 0; const int rq = qm ? 64 * (u.seg - 1) : 0;
;         const bool active = !(qm && wr == 1);
;         const int v = u.pm < 4 ? 4 : ((u.pm - 4) >> 5);
;         char* sb = (char*)(S + ((size_t)u.pm * BM + rq) * DM + u.pn * BM);
;         const char* gp = (const char*)(gate + (size_t)v * (NMOD * DM) + u.pn * BM);
;         const bool hasn = ng != nullptr;
;         const char* pgp = (const char*)(pg + u.pn * BM); const char* psp = (const char*)(psc + (size_t)v * (NMOD * DM) + u.pn * BM);
;         const char* ngp = (const char*)(ng + u.pn * BM); const char* nsp = (const char*)(nsc + (size_t)v * (NMOD * DM) + u.pn * BM);
;         unsigned co = (unsigned)(wc * 32 + 8 * fq);
;         asm volatile("" : "+v"(co));
;         unsigned lo = ((unsigned)((wr * 64 + fr) * DM) + co) * 2u;
;         asm volatile("" : "+v"(lo));
;         if (active) {
;         float ss[2][4];
; #pragma unroll
;         for (int ai = 0; ai < 2; ++ai)
; #pragma unroll
;             for (int m = 0; m < 4; ++m) ss[ai][m] = 0.f;
; #pragma unroll
;         for (int bj = 0; bj < 2; ++bj) {
;             const unsigned cb4 = (co + bj * HALF) * 4u;
;             f32x4 vg0 = *(const f32x4*)(gp + cb4), vg1 = *(const f32x4*)(gp + cb4 + 16), vp0 = *(const f32x4*)(pgp + cb4), vp1 = *(const f32x4*)(pgp + cb4 + 16), vs0 = *(const f32x4*)(psp + cb4), vs1 = *(const f32x4*)(psp + cb4 + 16);
;             f32x4 vn0 = {1.f, 1.f, 1.f, 1.f}, vn1 = vn0, vt0 = {0.f, 0.f, 0.f, 0.f}, vt1 = vt0;
;             if (hasn) { vn0 = *(const f32x4*)(ngp + cb4); vn1 = *(const f32x4*)(ngp + cb4 + 16); vt0 = *(const f32x4*)(nsp + cb4); vt1 = *(const f32x4*)(nsp + cb4 + 16); }
;             asm volatile("" : "+v"(vg0), "+v"(vg1), "+v"(vp0), "+v"(vp1), "+v"(vs0), "+v"(vs1), "+v"(vn0), "+v"(vn1), "+v"(vt0), "+v"(vt1));
;             const f32x4 g0 = vg0 * fac, g1 = vg1 * fac;
;             const f32x4 p0 = vp0 * (vs0 + 1.0f), p1 = vp1 * (vs1 + 1.0f);
;             f32x4 r0, r1;
; #pragma unroll
;             for (int i = 0; i < 4; ++i) { r0[i] = __builtin_amdgcn_rcpf(p0[i]); r1[i] = __builtin_amdgcn_rcpf(p1[i]); }
;             const f32x4 c0 = vn0 * (vt0 + 1.0f), c1 = vn1 * (vt1 + 1.0f);
;             u32x4 hin[2][4];
; #pragma unroll
.LBB0_328:
	s_ashr_i32 s51, s50, 31
	s_lshl_b64 s[42:43], s[50:51], 20
	s_add_u32 s51, s5, s42
	s_addc_u32 s58, s7, s43
	s_lshl_b32 s56, s56, 8
	s_ashr_i32 s57, s56, 31
	s_lshl_b64 s[42:43], s[56:57], 1
	s_add_u32 s42, s51, s42
	s_addc_u32 s43, s58, s43
	s_lshl_b64 s[30:31], s[30:31], 2
	s_add_u32 s51, s22, s30
	s_addc_u32 s58, s23, s31
	s_lshl_b64 s[64:65], s[56:57], 2
	s_add_u32 s56, s51, s64
	s_addc_u32 s57, s58, s65
	s_add_u32 s58, s8, s64
	s_addc_u32 s59, s9, s65
	s_add_u32 s51, s24, s30
	s_addc_u32 s61, s25, s31
	s_add_u32 s60, s51, s64
	s_addc_u32 s61, s61, s65
	s_add_u32 s62, s12, s64
	s_addc_u32 s63, s13, s65
	s_add_u32 s30, s26, s30
	s_addc_u32 s31, s27, s31
	v_mov_b32_e32 v106, v208
	s_add_u32 s64, s30, s64
	s_addc_u32 s65, s31, s65
	v_lshl_add_u32 v174, v106, 1, v209
	v_lshlrev_b32_e32 v212, 2, v106
	global_load_dwordx4 v[192:195], v212, s[56:57] offset:16
	global_load_dwordx4 v[106:109], v212, s[56:57]
	global_load_dwordx4 v[110:113], v212, s[58:59] offset:16
	global_load_dwordx4 v[114:117], v212, s[58:59]
	global_load_dwordx4 v[118:121], v212, s[60:61] offset:16
	global_load_dwordx4 v[122:125], v212, s[60:61]
	global_load_dwordx4 v[196:199], v212, s[62:63] offset:16
	global_load_dwordx4 v[200:203], v212, s[62:63]
	global_load_dwordx4 v[214:217], v212, s[64:65] offset:16
	global_load_dwordx4 v[218:221], v212, s[64:65]
	v_lshl_add_u64 v[164:165], s[42:43], 0, v[174:175]
	s_mov_b32 s30, 0x10000
	v_add_co_u32_e32 v168, vcc, s30, v164
	s_mov_b32 s30, 0x30000
	s_nop 0
	v_addc_co_u32_e32 v169, vcc, 0, v165, vcc
	v_add_co_u32_e32 v166, vcc, s79, v164
	s_waitcnt vmcnt(0)
	global_load_dwordx4 v[222:225], v174, s[42:43]
	v_pk_mul_f32 v[186:187], v[106:107], 0.5 op_sel_hi:[1,0]
	v_add_f32_e32 v106, 1.0, v122
	v_mul_f32_e32 v106, v114, v106
	v_rcp_f32_e32 v188, v106
	v_add_f32_e32 v106, 1.0, v118
	v_mul_f32_e32 v106, v110, v106
	v_rcp_f32_e32 v172, v106
	v_add_f32_e32 v106, 1.0, v123
	v_mul_f32_e32 v106, v115, v106
	global_load_dwordx4 v[226:229], v[168:169], off
	v_rcp_f32_e32 v189, v106
	v_add_f32_e32 v106, 1.0, v119
	v_mul_f32_e32 v106, v111, v106
	v_addc_co_u32_e32 v167, vcc, 0, v165, vcc
	v_rcp_f32_e32 v173, v106
	v_add_f32_e32 v106, 1.0, v124
	global_load_dwordx4 v[134:137], v[166:167], off
	v_mul_f32_e32 v106, v116, v106
	v_rcp_f32_e32 v182, v106
	v_add_f32_e32 v106, 1.0, v120
	v_add_co_u32_e32 v156, vcc, s30, v164
	v_mul_f32_e32 v106, v112, v106
	s_nop 0
	v_addc_co_u32_e32 v157, vcc, 0, v165, vcc
	v_rcp_f32_e32 v170, v106
	v_add_f32_e32 v106, 1.0, v125
	global_load_dwordx4 v[122:125], v[156:157], off
	s_mov_b32 s30, 0x80000
	v_add_co_u32_e32 v158, vcc, s30, v164
	v_mul_f32_e32 v106, v117, v106
	s_nop 0
	v_addc_co_u32_e32 v159, vcc, 0, v165, vcc
	v_rcp_f32_e32 v183, v106
	v_add_f32_e32 v106, 1.0, v121
	global_load_dwordx4 v[118:121], v[158:159], off
	s_mov_b32 s30, 0x90000
	v_add_co_u32_e32 v160, vcc, s30, v164
	s_mov_b32 s30, 0xa0000
	s_nop 0
	v_addc_co_u32_e32 v161, vcc, 0, v165, vcc
	global_load_dwordx4 v[114:117], v[160:161], off
	v_add_co_u32_e32 v162, vcc, s30, v164
	v_mul_f32_e32 v106, v113, v106
	s_nop 0
	v_addc_co_u32_e32 v163, vcc, 0, v165, vcc
	global_load_dwordx4 v[110:113], v[162:163], off
	s_mov_b32 s30, 0xb0000
	v_add_co_u32_e32 v164, vcc, s30, v164
	v_pk_mul_f32 v[184:185], v[108:109], 0.5 op_sel_hi:[1,0]
	s_nop 0
	v_addc_co_u32_e32 v165, vcc, 0, v165, vcc
	v_rcp_f32_e32 v171, v106
	global_load_dwordx4 v[106:109], v[164:165], off
	v_pk_mul_f32 v[150:151], v[150:151], v[186:187]
	v_pk_mul_f32 v[190:191], v[194:195], 0.5 op_sel_hi:[1,0]
	v_pk_mul_f32 v[192:193], v[192:193], 0.5 op_sel_hi:[1,0]
	v_pk_mul_f32 v[194:195], v[152:153], v[184:185]
	v_pk_mul_f32 v[146:147], v[146:147], v[192:193]
	v_pk_mul_f32 v[148:149], v[148:149], v[190:191]
	v_pk_mul_f32 v[144:145], v[144:145], v[184:185]
	v_pk_mul_f32 v[142:143], v[142:143], v[186:187]
	v_pk_mul_f32 v[138:139], v[138:139], v[192:193]
	v_pk_mul_f32 v[132:133], v[132:133], v[184:185]
	v_pk_mul_f32 v[130:131], v[130:131], v[186:187]
	v_pk_mul_f32 v[98:99], v[98:99], v[192:193]
	v_pk_mul_f32 v[126:127], v[126:127], v[192:193]
	v_pk_mul_f32 v[102:103], v[102:103], v[186:187]
	v_pk_mul_f32 v[100:101], v[100:101], v[190:191]
	v_pk_mul_f32 v[90:91], v[90:91], v[192:193]
	v_pk_mul_f32 v[96:97], v[96:97], v[184:185]
	v_pk_mul_f32 v[94:95], v[94:95], v[186:187]
	v_pk_mul_f32 v[92:93], v[92:93], v[190:191]
	v_pk_mul_f32 v[86:87], v[86:87], v[186:187]
	s_waitcnt vmcnt(7)
	v_lshlrev_b32_e32 v180, 16, v222
	v_and_b32_e32 v181, 0xffff0000, v222
	v_pk_fma_f32 v[152:153], v[188:189], v[180:181], v[150:151]
	v_pk_add_f32 v[150:151], v[218:219], 1.0 op_sel_hi:[1,0]
	v_lshlrev_b32_e32 v204, 16, v225
	v_pk_mul_f32 v[150:151], v[200:201], v[150:151]
	v_lshlrev_b32_e32 v200, 16, v224
	v_and_b32_e32 v201, 0xffff0000, v224
	v_pk_fma_f32 v[200:201], v[172:173], v[200:201], v[146:147]
	v_pk_mul_f32 v[180:181], v[150:151], v[152:153]
	v_pk_mul_f32 v[146:147], v[200:201], v[200:201]
	v_and_b32_e32 v205, 0xffff0000, v225
	v_pk_fma_f32 v[146:147], v[152:153], v[152:153], v[146:147]
	v_pk_add_f32 v[152:153], v[214:215], 1.0 op_sel_hi:[1,0]
	v_pk_fma_f32 v[204:205], v[170:171], v[204:205], v[148:149]
	v_pk_mul_f32 v[152:153], v[196:197], v[152:153]
	v_lshlrev_b32_e32 v196, 16, v223
	v_and_b32_e32 v197, 0xffff0000, v223
	v_pk_fma_f32 v[196:197], v[182:183], v[196:197], v[194:195]
	v_pk_add_f32 v[194:195], v[220:221], 1.0 op_sel_hi:[1,0]
	v_pk_mul_f32 v[148:149], v[204:205], v[204:205]
	v_pk_mul_f32 v[194:195], v[202:203], v[194:195]
	v_pk_fma_f32 v[148:149], v[196:197], v[196:197], v[148:149]
	v_pk_mul_f32 v[202:203], v[194:195], v[196:197]
	v_pk_add_f32 v[196:197], v[216:217], 1.0 op_sel_hi:[1,0]
	v_pk_mul_f32 v[200:201], v[152:153], v[200:201]
	v_pk_mul_f32 v[196:197], v[198:199], v[196:197]
	v_cvt_pk_bf16_f32 v198, v180, v181
	v_pk_mul_f32 v[204:205], v[196:197], v[204:205]
	v_cvt_pk_bf16_f32 v200, v200, v201
	v_cvt_pk_bf16_f32 v201, v204, v205
	s_waitcnt vmcnt(6)
; __device__ __forceinline__ void unpack8(const u32x4 w, float (&f)[8]) { f[0] = bflo(w.x); f[1] = bfhi(w.x); f[2] = bflo(w.y); f[3] = bfhi(w.y); f[4] = bflo(w.z); f[5] = bfhi(w.z); f[6] = bflo(w.w); f[7] = bfhi(w.w); }
; __device__ __forceinline__ u32x4 pack8(const float (&f)[8]) { u32x4 w; w.x = pk2(f[0], f[1]); w.y = pk2(f[2], f[3]); w.z = pk2(f[4], f[5]); w.w = pk2(f[6], f[7]); return w; }
;     template <int QVV> __device__ __forceinline__ void run(f32x4 (&acc)[2][2][4][2], const Unit& u, int wr, int wc, int fr, int fq) const {
;     ...
;                 for (int m = 0; m < 4; ++m) { if (ai == 1 && qm) continue; hin[ai][m] = *(const u32x4*)(sb + lo + (unsigned)((ai * HALF + m * 16) * DM + bj * HALF) * 2u); }
; #pragma unroll
;             for (int ai = 0; ai < 2; ++ai)
; #pragma unroll
;                 for (int m = 0; m < 4; ++m) { if (ai == 1 && qm) continue;
;                     const unsigned off = lo + (unsigned)((ai * HALF + m * 16) * DM + bj * HALF) * 2u;
;                     float hv[8]; unpack8(hin[ai][m], hv);
;                     float y[8]; float t = 0.f;
; #pragma unroll
;                     for (int i = 0; i < 4; ++i) { const float a0 = hv[i] * r0[i] + g0[i] * acc[ai][bj][m][0][i], a1 = hv[4 + i] * r1[i] + g1[i] * acc[ai][bj][m][1][i];
;                         t += a0 * a0 + a1 * a1; y[i] = a0 * c0[i]; y[4 + i] = a1 * c1[i]; }
;                     ss[ai][m] += t;
;                     *(u32x4*)(sb + off) = pack8(y); }
	v_lshlrev_b32_e32 v180, 16, v226
	v_and_b32_e32 v181, 0xffff0000, v226
	v_pk_mul_f32 v[204:205], v[140:141], v[190:191]
	v_lshlrev_b32_e32 v140, 16, v227
	v_and_b32_e32 v141, 0xffff0000, v227
	v_cvt_pk_bf16_f32 v199, v202, v203
	v_pk_fma_f32 v[142:143], v[188:189], v[180:181], v[142:143]
	v_lshlrev_b32_e32 v180, 16, v228
	v_and_b32_e32 v181, 0xffff0000, v228
	v_pk_fma_f32 v[140:141], v[182:183], v[140:141], v[144:145]
	v_lshlrev_b32_e32 v144, 16, v229
	v_and_b32_e32 v145, 0xffff0000, v229
	global_store_dwordx4 v174, v[198:201], s[42:43]
	v_pk_fma_f32 v[138:139], v[172:173], v[180:181], v[138:139]
	v_pk_mul_f32 v[202:203], v[194:195], v[140:141]
	v_pk_mul_f32 v[198:199], v[150:151], v[142:143]
	v_pk_fma_f32 v[144:145], v[170:171], v[144:145], v[204:205]
	v_pk_mul_f32 v[200:201], v[152:153], v[138:139]
	v_pk_mul_f32 v[204:205], v[196:197], v[144:145]
	v_cvt_pk_bf16_f32 v198, v198, v199
	v_cvt_pk_bf16_f32 v199, v202, v203
	v_pk_mul_f32 v[202:203], v[128:129], v[190:191]
	s_waitcnt vmcnt(6)
	v_lshlrev_b32_e32 v128, 16, v135
	v_and_b32_e32 v129, 0xffff0000, v135
	v_add_u32_e32 v180, 0x10000, v174
	v_cvt_pk_bf16_f32 v200, v200, v201
	v_cvt_pk_bf16_f32 v201, v204, v205
	v_pk_fma_f32 v[128:129], v[182:183], v[128:129], v[132:133]
	v_lshlrev_b32_e32 v132, 16, v137
	v_and_b32_e32 v133, 0xffff0000, v137
	global_store_dwordx4 v180, v[198:201], s[42:43]
	v_lshlrev_b32_e32 v180, 16, v134
	v_and_b32_e32 v181, 0xffff0000, v134
	v_pk_fma_f32 v[132:133], v[170:171], v[132:133], v[202:203]
	v_pk_fma_f32 v[130:131], v[188:189], v[180:181], v[130:131]
	v_lshlrev_b32_e32 v180, 16, v136
	v_and_b32_e32 v181, 0xffff0000, v136
	v_pk_mul_f32 v[136:137], v[196:197], v[132:133]
	v_pk_mul_f32 v[134:135], v[194:195], v[128:129]
	v_cvt_pk_bf16_f32 v217, v136, v137
	v_pk_mul_f32 v[136:137], v[104:105], v[184:185]
	s_waitcnt vmcnt(6)
	v_lshlrev_b32_e32 v104, 16, v124
	v_and_b32_e32 v105, 0xffff0000, v124
	v_pk_fma_f32 v[104:105], v[172:173], v[104:105], v[98:99]
	v_lshlrev_b32_e32 v98, 16, v123
	v_and_b32_e32 v99, 0xffff0000, v123
	v_pk_fma_f32 v[126:127], v[172:173], v[180:181], v[126:127]
	v_cvt_pk_bf16_f32 v215, v134, v135
	v_lshlrev_b32_e32 v134, 16, v122
	v_and_b32_e32 v135, 0xffff0000, v122
	v_pk_fma_f32 v[122:123], v[182:183], v[98:99], v[136:137]
	v_lshlrev_b32_e32 v98, 16, v125
	v_and_b32_e32 v99, 0xffff0000, v125
	v_pk_mul_f32 v[198:199], v[152:153], v[126:127]
	v_pk_fma_f32 v[102:103], v[188:189], v[134:135], v[102:103]
	v_pk_fma_f32 v[134:135], v[170:171], v[98:99], v[100:101]
	v_pk_mul_f32 v[200:201], v[150:151], v[130:131]
	v_cvt_pk_bf16_f32 v216, v198, v199
	v_pk_mul_f32 v[180:181], v[150:151], v[102:103]
	v_pk_mul_f32 v[198:199], v[152:153], v[104:105]
	v_pk_mul_f32 v[136:137], v[194:195], v[122:123]
	v_pk_mul_f32 v[124:125], v[196:197], v[134:135]
	v_cvt_pk_bf16_f32 v214, v200, v201
	v_add_u32_e32 v200, 0x30000, v174
	v_cvt_pk_bf16_f32 v98, v180, v181
	v_cvt_pk_bf16_f32 v99, v136, v137
	v_cvt_pk_bf16_f32 v100, v198, v199
	v_cvt_pk_bf16_f32 v101, v124, v125
	global_store_dwordx4 v200, v[98:101], s[42:43]
	v_add_u32_e32 v136, 0x80000, v174
	v_pk_mul_f32 v[82:83], v[82:83], v[192:193]
	s_waitcnt vmcnt(6)
	v_lshlrev_b32_e32 v100, 16, v120
	v_and_b32_e32 v101, 0xffff0000, v120
	v_pk_fma_f32 v[124:125], v[172:173], v[100:101], v[90:91]
	v_lshlrev_b32_e32 v90, 16, v119
	v_and_b32_e32 v91, 0xffff0000, v119
	v_lshlrev_b32_e32 v98, 16, v118
	v_and_b32_e32 v99, 0xffff0000, v118
	v_pk_fma_f32 v[118:119], v[182:183], v[90:91], v[96:97]
	v_lshlrev_b32_e32 v90, 16, v121
	v_and_b32_e32 v91, 0xffff0000, v121
	v_pk_fma_f32 v[98:99], v[188:189], v[98:99], v[94:95]
	v_pk_fma_f32 v[198:199], v[170:171], v[90:91], v[92:93]
	v_pk_mul_f32 v[94:95], v[150:151], v[98:99]
	v_pk_mul_f32 v[100:101], v[152:153], v[124:125]
	v_pk_mul_f32 v[96:97], v[194:195], v[118:119]
	v_pk_mul_f32 v[120:121], v[196:197], v[198:199]
	v_cvt_pk_bf16_f32 v90, v94, v95
	v_cvt_pk_bf16_f32 v91, v96, v97
	v_cvt_pk_bf16_f32 v92, v100, v101
	v_cvt_pk_bf16_f32 v93, v120, v121
	global_store_dwordx4 v136, v[90:93], s[42:43]
	v_pk_mul_f32 v[88:89], v[88:89], v[184:185]
	v_add_u32_e32 v202, 0x20000, v174
	s_waitcnt vmcnt(6)
	v_lshlrev_b32_e32 v90, 16, v114
	v_and_b32_e32 v91, 0xffff0000, v114
	v_pk_fma_f32 v[100:101], v[188:189], v[90:91], v[86:87]
	v_lshlrev_b32_e32 v90, 16, v116
	v_and_b32_e32 v91, 0xffff0000, v116
	v_pk_fma_f32 v[120:121], v[172:173], v[90:91], v[82:83]
	v_lshlrev_b32_e32 v82, 16, v115
	v_and_b32_e32 v83, 0xffff0000, v115
	v_pk_mul_f32 v[84:85], v[84:85], v[190:191]
	v_pk_fma_f32 v[136:137], v[182:183], v[82:83], v[88:89]
	v_lshlrev_b32_e32 v82, 16, v117
	v_and_b32_e32 v83, 0xffff0000, v117
	global_store_dwordx4 v202, v[214:217], s[42:43]
	v_pk_fma_f32 v[202:203], v[170:171], v[82:83], v[84:85]
	v_pk_mul_f32 v[86:87], v[150:151], v[100:101]
	v_pk_mul_f32 v[90:91], v[152:153], v[120:121]
	v_pk_mul_f32 v[88:89], v[194:195], v[136:137]
	v_pk_mul_f32 v[92:93], v[196:197], v[202:203]
	v_add_u32_e32 v94, 0x90000, v174
	v_cvt_pk_bf16_f32 v82, v86, v87
	v_cvt_pk_bf16_f32 v83, v88, v89
	v_cvt_pk_bf16_f32 v84, v90, v91
	v_cvt_pk_bf16_f32 v85, v92, v93
	global_store_dwordx4 v94, v[82:85], s[42:43]
	v_pk_mul_f32 v[78:79], v[78:79], v[186:187]
	v_pk_mul_f32 v[74:75], v[74:75], v[192:193]
	s_waitcnt vmcnt(7)
;     template <int QVV> __device__ __forceinline__ void run(f32x4 (&acc)[2][2][4][2], const Unit& u, int wr, int wc, int fr, int fq) const {
;     ...
;         for (int bj = 0; bj < 2; ++bj) {
;             const unsigned cb4 = (co + bj * HALF) * 4u;
;             f32x4 vg0 = *(const f32x4*)(gp + cb4), vg1 = *(const f32x4*)(gp + cb4 + 16), vp0 = *(const f32x4*)(pgp + cb4), vp1 = *(const f32x4*)(pgp + cb4 + 16), vs0 = *(const f32x4*)(psp + cb4), vs1 = *(const f32x4*)(psp + cb4 + 16);
;             f32x4 vn0 = {1.f, 1.f, 1.f, 1.f}, vn1 = vn0, vt0 = {0.f, 0.f, 0.f, 0.f}, vt1 = vt0;
;             if (hasn) { vn0 = *(const f32x4*)(ngp + cb4); vn1 = *(const f32x4*)(ngp + cb4 + 16); vt0 = *(const f32x4*)(nsp + cb4); vt1 = *(const f32x4*)(nsp + cb4 + 16); }
;             asm volatile("" : "+v"(vg0), "+v"(vg1), "+v"(vp0), "+v"(vp1), "+v"(vs0), "+v"(vs1), "+v"(vn0), "+v"(vn1), "+v"(vt0), "+v"(vt1));
;             const f32x4 g0 = vg0 * fac, g1 = vg1 * fac;
;             const f32x4 p0 = vp0 * (vs0 + 1.0f), p1 = vp1 * (vs1 + 1.0f);
;             f32x4 r0, r1;
; #pragma unroll
;             for (int i = 0; i < 4; ++i) { r0[i] = __builtin_amdgcn_rcpf(p0[i]); r1[i] = __builtin_amdgcn_rcpf(p1[i]); }
;             const f32x4 c0 = vn0 * (vt0 + 1.0f), c1 = vn1 * (vt1 + 1.0f);
;             u32x4 hin[2][4];
; #pragma unroll
;             for (int ai = 0; ai < 2; ++ai)
; #pragma unroll
;                 for (int m = 0; m < 4; ++m) { if (ai == 1 && qm) continue; hin[ai][m] = *(const u32x4*)(sb + lo + (unsigned)((ai * HALF + m * 16) * DM + bj * HALF) * 2u); }
; #pragma unroll
;             for (int ai = 0; ai < 2; ++ai)
; #pragma unroll
;                 for (int m = 0; m < 4; ++m) { if (ai == 1 && qm) continue;
;                     const unsigned off = lo + (unsigned)((ai * HALF + m * 16) * DM + bj * HALF) * 2u;
;                     float hv[8]; unpack8(hin[ai][m], hv);
;                     float y[8]; float t = 0.f;
; #pragma unroll
;                     for (int i = 0; i < 4; ++i) { const float a0 = hv[i] * r0[i] + g0[i] * acc[ai][bj][m][0][i], a1 = hv[4 + i] * r1[i] + g1[i] * acc[ai][bj][m][1][i];
;                         t += a0 * a0 + a1 * a1; y[i] = a0 * c0[i]; y[4 + i] = a1 * c1[i]; }
;                     ss[ai][m] += t;
;                     *(u32x4*)(sb + off) = pack8(y); }
	v_lshlrev_b32_e32 v82, 16, v110
	v_and_b32_e32 v83, 0xffff0000, v110
	v_pk_fma_f32 v[114:115], v[188:189], v[82:83], v[78:79]
	v_lshlrev_b32_e32 v82, 16, v112
	v_and_b32_e32 v83, 0xffff0000, v112
	v_pk_mul_f32 v[80:81], v[80:81], v[184:185]
	v_pk_fma_f32 v[116:117], v[172:173], v[82:83], v[74:75]
	v_lshlrev_b32_e32 v74, 16, v111
	v_and_b32_e32 v75, 0xffff0000, v111
	v_pk_mul_f32 v[76:77], v[76:77], v[190:191]
	v_pk_fma_f32 v[200:201], v[182:183], v[74:75], v[80:81]
	v_lshlrev_b32_e32 v74, 16, v113
	v_and_b32_e32 v75, 0xffff0000, v113
	v_pk_fma_f32 v[204:205], v[170:171], v[74:75], v[76:77]
	v_pk_mul_f32 v[78:79], v[150:151], v[114:115]
	v_pk_mul_f32 v[82:83], v[152:153], v[116:117]
	v_pk_mul_f32 v[80:81], v[194:195], v[200:201]
	v_pk_mul_f32 v[84:85], v[196:197], v[204:205]
	v_add_u32_e32 v86, 0xa0000, v174
	v_cvt_pk_bf16_f32 v74, v78, v79
	v_cvt_pk_bf16_f32 v75, v80, v81
	v_cvt_pk_bf16_f32 v76, v82, v83
	v_cvt_pk_bf16_f32 v77, v84, v85
	global_store_dwordx4 v86, v[74:77], s[42:43]
	v_pk_mul_f32 v[70:71], v[70:71], v[186:187]
	v_pk_mul_f32 v[66:67], v[66:67], v[192:193]
	s_waitcnt vmcnt(7)
	v_lshlrev_b32_e32 v74, 16, v106
	v_and_b32_e32 v75, 0xffff0000, v106
	v_pk_fma_f32 v[110:111], v[188:189], v[74:75], v[70:71]
	v_lshlrev_b32_e32 v74, 16, v108
	v_and_b32_e32 v75, 0xffff0000, v108
	v_pk_mul_f32 v[72:73], v[72:73], v[184:185]
	v_pk_fma_f32 v[112:113], v[172:173], v[74:75], v[66:67]
	v_lshlrev_b32_e32 v66, 16, v107
	v_and_b32_e32 v67, 0xffff0000, v107
	v_pk_mul_f32 v[68:69], v[68:69], v[190:191]
	v_pk_fma_f32 v[106:107], v[182:183], v[66:67], v[72:73]
	v_lshlrev_b32_e32 v66, 16, v109
	v_and_b32_e32 v67, 0xffff0000, v109
	v_pk_fma_f32 v[108:109], v[170:171], v[66:67], v[68:69]
	v_pk_mul_f32 v[70:71], v[150:151], v[110:111]
	v_pk_mul_f32 v[74:75], v[152:153], v[112:113]
	v_pk_mul_f32 v[72:73], v[194:195], v[106:107]
	v_pk_mul_f32 v[76:77], v[196:197], v[108:109]
	v_add_u32_e32 v78, 0xb0000, v174
	v_cvt_pk_bf16_f32 v66, v70, v71
	v_cvt_pk_bf16_f32 v67, v72, v73
	v_cvt_pk_bf16_f32 v68, v74, v75
	v_cvt_pk_bf16_f32 v69, v76, v77
	global_store_dwordx4 v78, v[66:69], s[42:43]
	v_add_u32_e32 v82, 0x200, v212
	global_load_dwordx4 v[90:93], v82, s[56:57] offset:16
	global_load_dwordx4 v[66:69], v82, s[56:57]
	global_load_dwordx4 v[86:89], v82, s[58:59] offset:16
	global_load_dwordx4 v[94:97], v82, s[58:59]
	global_load_dwordx4 v[186:189], v82, s[60:61] offset:16
	global_load_dwordx4 v[190:193], v82, s[60:61]
	global_load_dwordx4 v[70:73], v82, s[62:63] offset:16
	global_load_dwordx4 v[78:81], v82, s[62:63]
	global_load_dwordx4 v[74:77], v82, s[64:65] offset:16
	s_nop 0
	global_load_dwordx4 v[82:85], v82, s[64:65]
	s_waitcnt vmcnt(0)
	s_nop 0
	v_pk_mul_f32 v[182:183], v[66:67], 0.5 op_sel_hi:[1,0]
	v_add_f32_e32 v66, 1.0, v190
	v_mul_f32_e32 v66, v94, v66
	v_rcp_f32_e32 v184, v66
	v_add_f32_e32 v66, 1.0, v186
	v_mul_f32_e32 v66, v86, v66
	v_rcp_f32_e32 v152, v66
	v_add_f32_e32 v66, 1.0, v191
	v_mul_f32_e32 v66, v95, v66
	v_rcp_f32_e32 v185, v66
	v_add_f32_e32 v66, 1.0, v187
	v_mul_f32_e32 v66, v87, v66
	v_rcp_f32_e32 v153, v66
	v_add_f32_e32 v66, 1.0, v192
	v_mul_f32_e32 v66, v96, v66
	v_rcp_f32_e32 v170, v66
	v_add_f32_e32 v66, 1.0, v188
	v_mul_f32_e32 v66, v88, v66
	v_rcp_f32_e32 v150, v66
	v_add_f32_e32 v66, 1.0, v193
	v_mul_f32_e32 v66, v97, v66
	v_rcp_f32_e32 v171, v66
	v_add_f32_e32 v66, 1.0, v189
	v_mul_f32_e32 v66, v89, v66
	v_pk_mul_f32 v[172:173], v[68:69], 0.5 op_sel_hi:[1,0]
	v_rcp_f32_e32 v151, v66
	global_load_dwordx4 v[186:189], v174, s[42:43] offset:256
	global_load_dwordx4 v[190:193], v[168:169], off offset:256
	s_nop 0
	global_load_dwordx4 v[166:169], v[166:167], off offset:256
	s_nop 0
	global_load_dwordx4 v[194:197], v[156:157], off offset:256
	s_nop 0
	global_load_dwordx4 v[156:159], v[158:159], off offset:256
	s_nop 0
	global_load_dwordx4 v[94:97], v[160:161], off offset:256
	global_load_dwordx4 v[86:89], v[162:163], off offset:256
	global_load_dwordx4 v[66:69], v[164:165], off offset:256
	v_pk_mul_f32 v[92:93], v[92:93], 0.5 op_sel_hi:[1,0]
	v_pk_mul_f32 v[64:65], v[64:65], v[172:173]
	v_pk_mul_f32 v[162:163], v[60:61], v[92:93]
	v_pk_add_f32 v[60:61], v[74:75], 1.0 op_sel_hi:[1,0]
	v_pk_mul_f32 v[90:91], v[90:91], 0.5 op_sel_hi:[1,0]
	v_pk_mul_f32 v[70:71], v[70:71], v[60:61]
	v_pk_mul_f32 v[62:63], v[62:63], v[182:183]
	v_pk_add_f32 v[82:83], v[82:83], 1.0 op_sel_hi:[1,0]
	v_pk_mul_f32 v[58:59], v[58:59], v[90:91]
	v_pk_add_f32 v[76:77], v[76:77], 1.0 op_sel_hi:[1,0]
	v_pk_mul_f32 v[78:79], v[78:79], v[82:83]
	v_pk_mul_f32 v[72:73], v[72:73], v[76:77]
	v_pk_mul_f32 v[56:57], v[56:57], v[172:173]
	v_pk_mul_f32 v[54:55], v[54:55], v[182:183]
	v_pk_mul_f32 v[50:51], v[50:51], v[90:91]
	v_add_u32_e32 v164, 0x10100, v174
	v_pk_mul_f32 v[48:49], v[48:49], v[172:173]
	v_pk_mul_f32 v[46:47], v[46:47], v[182:183]
	v_pk_mul_f32 v[42:43], v[42:43], v[90:91]
	v_pk_mul_f32 v[40:41], v[40:41], v[172:173]
	v_pk_mul_f32 v[38:39], v[38:39], v[182:183]
	v_pk_mul_f32 v[34:35], v[34:35], v[90:91]
	v_pk_mul_f32 v[32:33], v[32:33], v[172:173]
	v_pk_mul_f32 v[30:31], v[30:31], v[182:183]
	v_pk_mul_f32 v[26:27], v[26:27], v[90:91]
	v_pk_mul_f32 v[24:25], v[24:25], v[172:173]
	v_pk_mul_f32 v[22:23], v[22:23], v[182:183]
	v_pk_mul_f32 v[18:19], v[18:19], v[90:91]
	v_pk_mul_f32 v[16:17], v[16:17], v[172:173]
	v_pk_mul_f32 v[14:15], v[14:15], v[182:183]
	v_pk_mul_f32 v[10:11], v[10:11], v[90:91]
	v_pk_mul_f32 v[6:7], v[6:7], v[182:183]
	v_pk_mul_f32 v[8:9], v[8:9], v[172:173]
	v_pk_mul_f32 v[2:3], v[2:3], v[90:91]
	s_lshl_b32 s30, s50, 8
	s_ashr_i32 s31, s30, 31
	s_waitcnt vmcnt(7)
; __device__ __forceinline__ void unpack8(const u32x4 w, float (&f)[8]) { f[0] = bflo(w.x); f[1] = bfhi(w.x); f[2] = bflo(w.y); f[3] = bfhi(w.y); f[4] = bflo(w.z); f[5] = bfhi(w.z); f[6] = bflo(w.w); f[7] = bfhi(w.w); }
; __device__ __forceinline__ u32x4 pack8(const float (&f)[8]) { u32x4 w; w.x = pk2(f[0], f[1]); w.y = pk2(f[2], f[3]); w.z = pk2(f[4], f[5]); w.w = pk2(f[6], f[7]); return w; }
;     template <int QVV> __device__ __forceinline__ void run(f32x4 (&acc)[2][2][4][2], const Unit& u, int wr, int wc, int fr, int fq) const {
;     ...
;                 for (int m = 0; m < 4; ++m) { if (ai == 1 && qm) continue; hin[ai][m] = *(const u32x4*)(sb + lo + (unsigned)((ai * HALF + m * 16) * DM + bj * HALF) * 2u); }
; #pragma unroll
;             for (int ai = 0; ai < 2; ++ai)
; #pragma unroll
;                 for (int m = 0; m < 4; ++m) { if (ai == 1 && qm) continue;
;                     const unsigned off = lo + (unsigned)((ai * HALF + m * 16) * DM + bj * HALF) * 2u;
;                     float hv[8]; unpack8(hin[ai][m], hv);
;                     float y[8]; float t = 0.f;
; #pragma unroll
;                     for (int i = 0; i < 4; ++i) { const float a0 = hv[i] * r0[i] + g0[i] * acc[ai][bj][m][0][i], a1 = hv[4 + i] * r1[i] + g1[i] * acc[ai][bj][m][1][i];
;                         t += a0 * a0 + a1 * a1; y[i] = a0 * c0[i]; y[4 + i] = a1 * c1[i]; }
;                     ss[ai][m] += t;
;                     *(u32x4*)(sb + off) = pack8(y); }
	v_lshlrev_b32_e32 v60, 16, v187
	v_and_b32_e32 v61, 0xffff0000, v187
	v_lshlrev_b32_e32 v160, 16, v186
	v_and_b32_e32 v161, 0xffff0000, v186
	v_pk_fma_f32 v[60:61], v[170:171], v[60:61], v[64:65]
	v_pk_add_f32 v[64:65], v[84:85], 1.0 op_sel_hi:[1,0]
	v_pk_fma_f32 v[62:63], v[184:185], v[160:161], v[62:63]
	v_lshlrev_b32_e32 v160, 16, v188
	v_and_b32_e32 v161, 0xffff0000, v188
	v_pk_mul_f32 v[74:75], v[80:81], v[64:65]
	v_lshlrev_b32_e32 v64, 16, v189
	v_and_b32_e32 v65, 0xffff0000, v189
	v_pk_fma_f32 v[58:59], v[152:153], v[160:161], v[58:59]
	v_pk_fma_f32 v[64:65], v[150:151], v[64:65], v[162:163]
	v_pk_mul_f32 v[82:83], v[78:79], v[62:63]
	v_pk_mul_f32 v[160:161], v[70:71], v[58:59]
	v_pk_mul_f32 v[84:85], v[74:75], v[60:61]
	v_pk_mul_f32 v[76:77], v[72:73], v[64:65]
	v_add_u32_e32 v162, 0x100, v174
	v_cvt_pk_bf16_f32 v80, v82, v83
	v_cvt_pk_bf16_f32 v81, v84, v85
	v_cvt_pk_bf16_f32 v82, v160, v161
	v_cvt_pk_bf16_f32 v83, v76, v77
	global_store_dwordx4 v162, v[80:83], s[42:43]
	s_waitcnt vmcnt(7)
	v_lshlrev_b32_e32 v76, 16, v190
	v_and_b32_e32 v77, 0xffff0000, v190
	v_pk_mul_f32 v[82:83], v[52:53], v[92:93]
	v_lshlrev_b32_e32 v52, 16, v191
	v_and_b32_e32 v53, 0xffff0000, v191
	v_lshlrev_b32_e32 v80, 16, v192
	v_and_b32_e32 v81, 0xffff0000, v192
	v_pk_fma_f32 v[52:53], v[170:171], v[52:53], v[56:57]
	v_lshlrev_b32_e32 v56, 16, v193
	v_and_b32_e32 v57, 0xffff0000, v193
	v_pk_fma_f32 v[54:55], v[184:185], v[76:77], v[54:55]
	v_pk_fma_f32 v[50:51], v[152:153], v[80:81], v[50:51]
	v_pk_fma_f32 v[56:57], v[150:151], v[56:57], v[82:83]
	v_pk_mul_f32 v[76:77], v[78:79], v[54:55]
	v_pk_mul_f32 v[84:85], v[70:71], v[50:51]
	v_pk_mul_f32 v[160:161], v[74:75], v[52:53]
	v_pk_mul_f32 v[162:163], v[72:73], v[56:57]
	v_cvt_pk_bf16_f32 v80, v76, v77
	v_cvt_pk_bf16_f32 v81, v160, v161
	v_cvt_pk_bf16_f32 v82, v84, v85
	v_cvt_pk_bf16_f32 v83, v162, v163
	global_store_dwordx4 v164, v[80:83], s[42:43]
	s_waitcnt vmcnt(7)
	v_lshlrev_b32_e32 v76, 16, v166
	v_and_b32_e32 v77, 0xffff0000, v166
	v_pk_mul_f32 v[82:83], v[44:45], v[92:93]
	v_lshlrev_b32_e32 v44, 16, v167
	v_and_b32_e32 v45, 0xffff0000, v167
	v_lshlrev_b32_e32 v80, 16, v168
	v_and_b32_e32 v81, 0xffff0000, v168
	v_pk_fma_f32 v[44:45], v[170:171], v[44:45], v[48:49]
	v_lshlrev_b32_e32 v48, 16, v169
	v_and_b32_e32 v49, 0xffff0000, v169
	v_pk_fma_f32 v[46:47], v[184:185], v[76:77], v[46:47]
	v_pk_fma_f32 v[42:43], v[152:153], v[80:81], v[42:43]
	v_pk_fma_f32 v[48:49], v[150:151], v[48:49], v[82:83]
	v_pk_mul_f32 v[76:77], v[78:79], v[46:47]
	v_pk_mul_f32 v[84:85], v[70:71], v[42:43]
	v_pk_mul_f32 v[160:161], v[74:75], v[44:45]
	v_pk_mul_f32 v[162:163], v[72:73], v[48:49]
	v_add_u32_e32 v164, 0x20100, v174
	v_cvt_pk_bf16_f32 v80, v76, v77
	v_cvt_pk_bf16_f32 v81, v160, v161
	v_cvt_pk_bf16_f32 v82, v84, v85
	v_cvt_pk_bf16_f32 v83, v162, v163
	global_store_dwordx4 v164, v[80:83], s[42:43]
	s_waitcnt vmcnt(7)
	v_lshlrev_b32_e32 v76, 16, v194
	v_and_b32_e32 v77, 0xffff0000, v194
	v_pk_mul_f32 v[82:83], v[36:37], v[92:93]
	v_lshlrev_b32_e32 v36, 16, v195
	v_and_b32_e32 v37, 0xffff0000, v195
	v_lshlrev_b32_e32 v80, 16, v196
	v_and_b32_e32 v81, 0xffff0000, v196
	v_pk_fma_f32 v[36:37], v[170:171], v[36:37], v[40:41]
	v_lshlrev_b32_e32 v40, 16, v197
	v_and_b32_e32 v41, 0xffff0000, v197
	v_pk_fma_f32 v[38:39], v[184:185], v[76:77], v[38:39]
	v_pk_fma_f32 v[34:35], v[152:153], v[80:81], v[34:35]
	v_pk_fma_f32 v[40:41], v[150:151], v[40:41], v[82:83]
	v_pk_mul_f32 v[76:77], v[78:79], v[38:39]
	v_pk_mul_f32 v[84:85], v[70:71], v[34:35]
	v_pk_mul_f32 v[160:161], v[74:75], v[36:37]
	v_pk_mul_f32 v[162:163], v[72:73], v[40:41]
	v_add_u32_e32 v164, 0x30100, v174
	v_cvt_pk_bf16_f32 v80, v76, v77
	v_cvt_pk_bf16_f32 v81, v160, v161
	v_cvt_pk_bf16_f32 v82, v84, v85
	v_cvt_pk_bf16_f32 v83, v162, v163
	global_store_dwordx4 v164, v[80:83], s[42:43]
	s_waitcnt vmcnt(7)
	v_lshlrev_b32_e32 v76, 16, v156
	v_and_b32_e32 v77, 0xffff0000, v156
	v_pk_mul_f32 v[82:83], v[28:29], v[92:93]
	v_lshlrev_b32_e32 v28, 16, v157
	v_and_b32_e32 v29, 0xffff0000, v157
	v_lshlrev_b32_e32 v80, 16, v158
	v_and_b32_e32 v81, 0xffff0000, v158
	v_pk_fma_f32 v[28:29], v[170:171], v[28:29], v[32:33]
	v_lshlrev_b32_e32 v32, 16, v159
	v_and_b32_e32 v33, 0xffff0000, v159
	v_pk_fma_f32 v[30:31], v[184:185], v[76:77], v[30:31]
	v_pk_fma_f32 v[26:27], v[152:153], v[80:81], v[26:27]
	v_pk_fma_f32 v[32:33], v[150:151], v[32:33], v[82:83]
	v_pk_mul_f32 v[76:77], v[78:79], v[30:31]
	v_pk_mul_f32 v[84:85], v[70:71], v[26:27]
	v_pk_mul_f32 v[156:157], v[74:75], v[28:29]
	v_pk_mul_f32 v[158:159], v[72:73], v[32:33]
	v_pk_mul_f32 v[58:59], v[58:59], v[58:59]
	v_add_u32_e32 v160, 0x80100, v174
	v_cvt_pk_bf16_f32 v80, v76, v77
	v_cvt_pk_bf16_f32 v81, v156, v157
	v_cvt_pk_bf16_f32 v82, v84, v85
	v_cvt_pk_bf16_f32 v83, v158, v159
	v_pk_mul_f32 v[64:65], v[64:65], v[64:65]
	v_pk_fma_f32 v[58:59], v[62:63], v[62:63], v[58:59]
	global_store_dwordx4 v160, v[80:83], s[42:43]
	v_pk_fma_f32 v[60:61], v[60:61], v[60:61], v[64:65]
	v_add_f32_e32 v58, v58, v59
	v_pk_mul_f32 v[82:83], v[20:21], v[92:93]
	s_waitcnt vmcnt(7)
; __device__ __forceinline__ void unpack8(const u32x4 w, float (&f)[8]) { f[0] = bflo(w.x); f[1] = bfhi(w.x); f[2] = bflo(w.y); f[3] = bfhi(w.y); f[4] = bflo(w.z); f[5] = bfhi(w.z); f[6] = bflo(w.w); f[7] = bfhi(w.w); }
; __device__ __forceinline__ u32x4 pack8(const float (&f)[8]) { u32x4 w; w.x = pk2(f[0], f[1]); w.y = pk2(f[2], f[3]); w.z = pk2(f[4], f[5]); w.w = pk2(f[6], f[7]); return w; }
;     template <int QVV> __device__ __forceinline__ void run(f32x4 (&acc)[2][2][4][2], const Unit& u, int wr, int wc, int fr, int fq) const {
;     ...
;             for (int ai = 0; ai < 2; ++ai)
; #pragma unroll
;                 for (int m = 0; m < 4; ++m) { if (ai == 1 && qm) continue;
;                     const unsigned off = lo + (unsigned)((ai * HALF + m * 16) * DM + bj * HALF) * 2u;
;                     float hv[8]; unpack8(hin[ai][m], hv);
;                     float y[8]; float t = 0.f;
; #pragma unroll
;                     for (int i = 0; i < 4; ++i) { const float a0 = hv[i] * r0[i] + g0[i] * acc[ai][bj][m][0][i], a1 = hv[4 + i] * r1[i] + g1[i] * acc[ai][bj][m][1][i];
;                         t += a0 * a0 + a1 * a1; y[i] = a0 * c0[i]; y[4 + i] = a1 * c1[i]; }
;                     ss[ai][m] += t;
;                     *(u32x4*)(sb + off) = pack8(y); }
;             asm volatile("" ::: "memory");
;         }
;         if (hasn) {
;             unsigned long long* sp = ssq + u.pm * BM + rq + wr * 64 + fr;
; #pragma unroll
;             for (int ai = 0; ai < 2; ++ai)
; #pragma unroll
;                 for (int m = 0; m < 4; ++m) { if (ai == 1 && qm) continue; float t = ss[ai][m]; t += __shfl_xor(t, 16); t += __shfl_xor(t, 32);
;                     const float xs = t * SSQ_SCALE; const unsigned xh = (unsigned)(xs * 2.3283064365386963e-10f), xl = (unsigned)__builtin_fmaf(-(float)xh, 4294967296.0f, xs);
;                     if (fq == 0) atomicAdd(sp + ai * HALF + m * 16, ((unsigned long long)xh << 32) | xl); }
	v_lshlrev_b32_e32 v20, 16, v95
	v_and_b32_e32 v21, 0xffff0000, v95
	v_lshlrev_b32_e32 v76, 16, v94
	v_and_b32_e32 v77, 0xffff0000, v94
	v_lshlrev_b32_e32 v80, 16, v96
	v_and_b32_e32 v81, 0xffff0000, v96
	v_pk_fma_f32 v[20:21], v[170:171], v[20:21], v[24:25]
	v_lshlrev_b32_e32 v24, 16, v97
	v_and_b32_e32 v25, 0xffff0000, v97
	v_add_f32_e32 v62, v146, v147
	v_add_f32_e32 v58, v60, v58
	v_xor_b32_e32 v60, 16, v230
	v_pk_fma_f32 v[22:23], v[184:185], v[76:77], v[22:23]
	v_pk_fma_f32 v[18:19], v[152:153], v[80:81], v[18:19]
	v_pk_fma_f32 v[24:25], v[150:151], v[24:25], v[82:83]
	v_add_f32_e32 v62, v148, v62
	v_cmp_lt_i32_e32 vcc, v60, v232
	v_pk_mul_f32 v[76:77], v[78:79], v[22:23]
	v_pk_mul_f32 v[84:85], v[70:71], v[18:19]
	v_pk_mul_f32 v[94:95], v[74:75], v[20:21]
	v_pk_mul_f32 v[96:97], v[72:73], v[24:25]
	v_add_f32_e32 v62, v149, v62
	v_add_f32_e32 v58, v61, v58
	v_cndmask_b32_e32 v60, v230, v60, vcc
	v_add_u32_e32 v156, 0x90100, v174
	v_cvt_pk_bf16_f32 v80, v76, v77
	v_cvt_pk_bf16_f32 v81, v94, v95
	v_cvt_pk_bf16_f32 v82, v84, v85
	v_cvt_pk_bf16_f32 v83, v96, v97
	v_add_f32_e32 v61, v62, v58
	v_lshlrev_b32_e32 v60, 2, v60
	global_store_dwordx4 v156, v[80:83], s[42:43]
	v_mov_b32_e32 v62, v61
	s_nop 1
	v_permlane16_swap_b32 v61, v62
	s_waitcnt vmcnt(7)
	v_lshlrev_b32_e32 v76, 16, v86
	v_pk_mul_f32 v[82:83], v[12:13], v[92:93]
	v_lshlrev_b32_e32 v12, 16, v87
	v_and_b32_e32 v13, 0xffff0000, v87
	v_and_b32_e32 v77, 0xffff0000, v86
	v_lshlrev_b32_e32 v80, 16, v88
	v_and_b32_e32 v81, 0xffff0000, v88
	v_pk_fma_f32 v[12:13], v[170:171], v[12:13], v[16:17]
	v_lshlrev_b32_e32 v16, 16, v89
	v_and_b32_e32 v17, 0xffff0000, v89
	v_pk_fma_f32 v[14:15], v[184:185], v[76:77], v[14:15]
	v_pk_fma_f32 v[10:11], v[152:153], v[80:81], v[10:11]
	v_pk_fma_f32 v[16:17], v[150:151], v[16:17], v[82:83]
	v_pk_mul_f32 v[76:77], v[78:79], v[14:15]
	v_pk_mul_f32 v[84:85], v[70:71], v[10:11]
	v_pk_mul_f32 v[86:87], v[74:75], v[12:13]
	v_pk_mul_f32 v[88:89], v[72:73], v[16:17]
	v_add_u32_e32 v94, 0xa0100, v174
	v_cvt_pk_bf16_f32 v80, v76, v77
	v_cvt_pk_bf16_f32 v81, v86, v87
	v_cvt_pk_bf16_f32 v82, v84, v85
	v_cvt_pk_bf16_f32 v83, v88, v89
	s_waitcnt vmcnt(6)
	v_lshlrev_b32_e32 v76, 16, v66
	v_and_b32_e32 v77, 0xffff0000, v66
	global_store_dwordx4 v94, v[80:83], s[42:43]
	v_pk_fma_f32 v[6:7], v[184:185], v[76:77], v[6:7]
	s_waitcnt lgkmcnt(0)
	v_add_f32_e32 v62, v61, v62
	v_pk_mul_f32 v[80:81], v[4:5], v[92:93]
	v_lshlrev_b32_e32 v4, 16, v67
	v_and_b32_e32 v5, 0xffff0000, v67
	v_xor_b32_e32 v61, 32, v230
	v_pk_mul_f32 v[76:77], v[78:79], v[6:7]
	v_lshlrev_b32_e32 v78, 16, v68
	v_and_b32_e32 v79, 0xffff0000, v68
	v_pk_fma_f32 v[4:5], v[170:171], v[4:5], v[8:9]
	v_lshlrev_b32_e32 v8, 16, v69
	v_and_b32_e32 v9, 0xffff0000, v69
	v_cmp_lt_i32_e32 vcc, v61, v232
	v_pk_fma_f32 v[2:3], v[152:153], v[78:79], v[2:3]
	v_pk_fma_f32 v[8:9], v[150:151], v[8:9], v[80:81]
	v_cndmask_b32_e32 v61, v230, v61, vcc
	v_pk_mul_f32 v[70:71], v[70:71], v[2:3]
	v_pk_mul_f32 v[74:75], v[74:75], v[4:5]
	v_pk_mul_f32 v[72:73], v[72:73], v[8:9]
	v_lshlrev_b32_e32 v61, 2, v61
	v_add_u32_e32 v78, 0xb0100, v174
	v_cvt_pk_bf16_f32 v66, v76, v77
	v_cvt_pk_bf16_f32 v67, v74, v75
	v_cvt_pk_bf16_f32 v68, v70, v71
	v_cvt_pk_bf16_f32 v69, v72, v73
	v_mov_b32_e32 v63, v62
	s_nop 1
	v_permlane32_swap_b32 v62, v63
	global_store_dwordx4 v78, v[66:69], s[42:43]
	v_lshl_add_u64 v[58:59], s[30:31], 3, v[154:155]
	s_and_saveexec_b64 s[30:31], s[38:39]
	s_cbranch_execz .LBB0_330
	s_waitcnt lgkmcnt(0)
	v_add_f32_e32 v62, v62, v63
	v_mul_f32_e32 v62, 0x49800000, v62
	v_mul_f32_e32 v63, 0x2f800000, v62
	v_cvt_u32_f32_e32 v63, v63
	v_cvt_f32_u32_e32 v64, v63
	v_fmac_f32_e32 v62, 0xcf800000, v64
	v_cvt_u32_f32_e32 v62, v62
	global_atomic_add_x2 v[58:59], v[62:63], off
.LBB0_330:
	s_or_b64 exec, exec, s[30:31]
	s_waitcnt lgkmcnt(0)
	v_pk_mul_f32 v[62:63], v[138:139], v[138:139]
	v_pk_mul_f32 v[50:51], v[50:51], v[50:51]
	v_pk_fma_f32 v[62:63], v[142:143], v[142:143], v[62:63]
	v_pk_mul_f32 v[64:65], v[144:145], v[144:145]
	v_pk_fma_f32 v[50:51], v[54:55], v[54:55], v[50:51]
	v_pk_mul_f32 v[54:55], v[56:57], v[56:57]
	v_pk_fma_f32 v[64:65], v[140:141], v[140:141], v[64:65]
	v_pk_fma_f32 v[52:53], v[52:53], v[52:53], v[54:55]
	v_add_f32_e32 v50, v50, v51
	v_add_f32_e32 v51, v62, v63
	v_add_f32_e32 v50, v52, v50
	v_add_f32_e32 v51, v64, v51
	v_add_f32_e32 v50, v53, v50
	v_add_f32_e32 v51, v65, v51
	v_add_f32_e32 v50, v51, v50
	v_mov_b32_e32 v51, v50
	s_nop 1
	v_permlane16_swap_b32 v50, v51
	s_waitcnt lgkmcnt(0)
	v_add_f32_e32 v50, v50, v51
	v_mov_b32_e32 v51, v50
	s_nop 1
	v_permlane32_swap_b32 v50, v51
	s_and_saveexec_b64 s[30:31], s[38:39]
	v_readlane_b32 s58, v254, 35
	v_readlane_b32 s59, v254, 36
	s_mov_b32 s62, 0xff61b1e6
	s_cbranch_execz .LBB0_332
	s_waitcnt lgkmcnt(0)
	v_add_f32_e32 v50, v50, v51
	v_mul_f32_e32 v50, 0x49800000, v50
	v_mul_f32_e32 v51, 0x2f800000, v50
	v_cvt_u32_f32_e32 v51, v51
	v_cvt_f32_u32_e32 v52, v51
	v_fmac_f32_e32 v50, 0xcf800000, v52
	v_cvt_u32_f32_e32 v50, v50
	global_atomic_add_x2 v[58:59], v[50:51], off offset:128
;     template <int QVV> __device__ __forceinline__ void run(f32x4 (&acc)[2][2][4][2], const Unit& u, int wr, int wc, int fr, int fq) const {
;     ...
;         if (hasn) {
;             unsigned long long* sp = ssq + u.pm * BM + rq + wr * 64 + fr;
; #pragma unroll
;             for (int ai = 0; ai < 2; ++ai)
; #pragma unroll
;                 for (int m = 0; m < 4; ++m) { if (ai == 1 && qm) continue; float t = ss[ai][m]; t += __shfl_xor(t, 16); t += __shfl_xor(t, 32);
;                     const float xs = t * SSQ_SCALE; const unsigned xh = (unsigned)(xs * 2.3283064365386963e-10f), xl = (unsigned)__builtin_fmaf(-(float)xh, 4294967296.0f, xs);
;                     if (fq == 0) atomicAdd(sp + ai * HALF + m * 16, ((unsigned long long)xh << 32) | xl); }
.LBB0_332:
	s_or_b64 exec, exec, s[30:31]
	s_waitcnt lgkmcnt(0)
	v_pk_mul_f32 v[50:51], v[126:127], v[126:127]
	v_pk_mul_f32 v[42:43], v[42:43], v[42:43]
	v_pk_fma_f32 v[50:51], v[130:131], v[130:131], v[50:51]
	v_pk_mul_f32 v[52:53], v[132:133], v[132:133]
	v_pk_fma_f32 v[42:43], v[46:47], v[46:47], v[42:43]
	v_pk_mul_f32 v[46:47], v[48:49], v[48:49]
	v_pk_fma_f32 v[52:53], v[128:129], v[128:129], v[52:53]
	v_pk_fma_f32 v[44:45], v[44:45], v[44:45], v[46:47]
	v_add_f32_e32 v42, v42, v43
	v_add_f32_e32 v43, v50, v51
	v_add_f32_e32 v42, v44, v42
	v_add_f32_e32 v43, v52, v43
	v_add_f32_e32 v42, v45, v42
	v_add_f32_e32 v43, v53, v43
	v_add_f32_e32 v42, v43, v42
	v_mov_b32_e32 v43, v42
	s_nop 1
	v_permlane16_swap_b32 v42, v43
	s_waitcnt lgkmcnt(0)
	v_add_f32_e32 v42, v42, v43
	v_mov_b32_e32 v43, v42
	s_nop 1
	v_permlane32_swap_b32 v42, v43
	s_and_saveexec_b64 s[30:31], s[38:39]
	s_mov_b32 s63, 0x41000000
	s_cbranch_execz .LBB0_334
	s_waitcnt lgkmcnt(0)
	v_add_f32_e32 v42, v42, v43
	v_mul_f32_e32 v42, 0x49800000, v42
	v_mul_f32_e32 v43, 0x2f800000, v42
	v_cvt_u32_f32_e32 v43, v43
	v_cvt_f32_u32_e32 v44, v43
	v_fmac_f32_e32 v42, 0xcf800000, v44
	v_cvt_u32_f32_e32 v42, v42
	global_atomic_add_x2 v[58:59], v[42:43], off offset:256
.LBB0_334:
	s_or_b64 exec, exec, s[30:31]
	s_waitcnt lgkmcnt(0)
	v_pk_mul_f32 v[42:43], v[104:105], v[104:105]
	v_pk_mul_f32 v[34:35], v[34:35], v[34:35]
	v_pk_fma_f32 v[42:43], v[102:103], v[102:103], v[42:43]
	v_pk_mul_f32 v[44:45], v[134:135], v[134:135]
	v_pk_fma_f32 v[34:35], v[38:39], v[38:39], v[34:35]
	v_pk_mul_f32 v[38:39], v[40:41], v[40:41]
	v_pk_fma_f32 v[44:45], v[122:123], v[122:123], v[44:45]
	v_pk_fma_f32 v[36:37], v[36:37], v[36:37], v[38:39]
	v_add_f32_e32 v34, v34, v35
	v_add_f32_e32 v35, v42, v43
	v_add_f32_e32 v34, v36, v34
	v_add_f32_e32 v35, v44, v35
	v_add_f32_e32 v34, v37, v34
	v_add_f32_e32 v35, v45, v35
	v_add_f32_e32 v34, v35, v34
	v_mov_b32_e32 v35, v34
	s_nop 1
	v_permlane16_swap_b32 v34, v35
	s_waitcnt lgkmcnt(0)
	v_add_f32_e32 v34, v34, v35
	v_mov_b32_e32 v35, v34
	s_nop 1
	v_permlane32_swap_b32 v34, v35
	s_and_saveexec_b64 s[30:31], s[38:39]
	s_cbranch_execz .LBB0_336
	s_waitcnt lgkmcnt(0)
	v_add_f32_e32 v34, v34, v35
	v_mul_f32_e32 v34, 0x49800000, v34
	v_mul_f32_e32 v35, 0x2f800000, v34
	v_cvt_u32_f32_e32 v35, v35
	v_cvt_f32_u32_e32 v36, v35
	v_fmac_f32_e32 v34, 0xcf800000, v36
	v_cvt_u32_f32_e32 v34, v34
	global_atomic_add_x2 v[58:59], v[34:35], off offset:384
.LBB0_336:
	s_or_b64 exec, exec, s[30:31]
	s_waitcnt lgkmcnt(0)
	v_pk_mul_f32 v[34:35], v[124:125], v[124:125]
	v_pk_mul_f32 v[26:27], v[26:27], v[26:27]
	v_pk_fma_f32 v[34:35], v[98:99], v[98:99], v[34:35]
	v_pk_mul_f32 v[36:37], v[198:199], v[198:199]
	v_pk_fma_f32 v[26:27], v[30:31], v[30:31], v[26:27]
	v_pk_mul_f32 v[30:31], v[32:33], v[32:33]
	v_pk_fma_f32 v[36:37], v[118:119], v[118:119], v[36:37]
	v_pk_fma_f32 v[28:29], v[28:29], v[28:29], v[30:31]
	v_add_f32_e32 v26, v26, v27
	v_add_f32_e32 v27, v34, v35
	v_add_f32_e32 v26, v28, v26
	v_add_f32_e32 v27, v36, v27
	v_add_f32_e32 v26, v29, v26
	v_add_f32_e32 v27, v37, v27
	v_add_f32_e32 v26, v27, v26
	v_mov_b32_e32 v27, v26
	s_nop 1
	v_permlane16_swap_b32 v26, v27
	s_waitcnt lgkmcnt(0)
	v_add_f32_e32 v26, v26, v27
	v_mov_b32_e32 v27, v26
	s_nop 1
	v_permlane32_swap_b32 v26, v27
	s_and_saveexec_b64 s[30:31], s[38:39]
	s_cbranch_execz .LBB0_338
	s_waitcnt lgkmcnt(0)
	v_add_f32_e32 v26, v26, v27
	v_mul_f32_e32 v26, 0x49800000, v26
	v_mul_f32_e32 v27, 0x2f800000, v26
	v_cvt_u32_f32_e32 v27, v27
	v_cvt_f32_u32_e32 v28, v27
	v_fmac_f32_e32 v26, 0xcf800000, v28
	v_cvt_u32_f32_e32 v26, v26
	global_atomic_add_x2 v[58:59], v[26:27], off offset:1024
;     template <int QVV> __device__ __forceinline__ void run(f32x4 (&acc)[2][2][4][2], const Unit& u, int wr, int wc, int fr, int fq) const {
;     ...
;         if (hasn) {
;             unsigned long long* sp = ssq + u.pm * BM + rq + wr * 64 + fr;
; #pragma unroll
;             for (int ai = 0; ai < 2; ++ai)
; #pragma unroll
;                 for (int m = 0; m < 4; ++m) { if (ai == 1 && qm) continue; float t = ss[ai][m]; t += __shfl_xor(t, 16); t += __shfl_xor(t, 32);
;                     const float xs = t * SSQ_SCALE; const unsigned xh = (unsigned)(xs * 2.3283064365386963e-10f), xl = (unsigned)__builtin_fmaf(-(float)xh, 4294967296.0f, xs);
;                     if (fq == 0) atomicAdd(sp + ai * HALF + m * 16, ((unsigned long long)xh << 32) | xl); }
.LBB0_338:
	s_or_b64 exec, exec, s[30:31]
	s_waitcnt lgkmcnt(0)
	v_pk_mul_f32 v[26:27], v[120:121], v[120:121]
	v_pk_mul_f32 v[18:19], v[18:19], v[18:19]
	v_pk_fma_f32 v[26:27], v[100:101], v[100:101], v[26:27]
	v_pk_mul_f32 v[28:29], v[202:203], v[202:203]
	v_pk_fma_f32 v[18:19], v[22:23], v[22:23], v[18:19]
	v_pk_mul_f32 v[22:23], v[24:25], v[24:25]
	v_pk_fma_f32 v[28:29], v[136:137], v[136:137], v[28:29]
	v_pk_fma_f32 v[20:21], v[20:21], v[20:21], v[22:23]
	v_add_f32_e32 v18, v18, v19
	v_add_f32_e32 v19, v26, v27
	v_add_f32_e32 v18, v20, v18
	v_add_f32_e32 v19, v28, v19
	v_add_f32_e32 v18, v21, v18
	v_add_f32_e32 v19, v29, v19
	v_add_f32_e32 v18, v19, v18
	v_mov_b32_e32 v19, v18
	s_nop 1
	v_permlane16_swap_b32 v18, v19
	s_waitcnt lgkmcnt(0)
	v_add_f32_e32 v18, v18, v19
	v_mov_b32_e32 v19, v18
	s_nop 1
	v_permlane32_swap_b32 v18, v19
	s_and_saveexec_b64 s[30:31], s[38:39]
	s_cbranch_execz .LBB0_340
	s_waitcnt lgkmcnt(0)
	v_add_f32_e32 v18, v18, v19
	v_mul_f32_e32 v18, 0x49800000, v18
	v_mul_f32_e32 v19, 0x2f800000, v18
	v_cvt_u32_f32_e32 v19, v19
	v_cvt_f32_u32_e32 v20, v19
	v_fmac_f32_e32 v18, 0xcf800000, v20
	v_cvt_u32_f32_e32 v18, v18
	global_atomic_add_x2 v[58:59], v[18:19], off offset:1152
.LBB0_340:
	s_or_b64 exec, exec, s[30:31]
	s_waitcnt lgkmcnt(0)
	v_pk_mul_f32 v[18:19], v[116:117], v[116:117]
	v_pk_mul_f32 v[10:11], v[10:11], v[10:11]
	v_pk_fma_f32 v[18:19], v[114:115], v[114:115], v[18:19]
	v_pk_mul_f32 v[20:21], v[204:205], v[204:205]
	v_pk_fma_f32 v[10:11], v[14:15], v[14:15], v[10:11]
	v_pk_mul_f32 v[14:15], v[16:17], v[16:17]
	v_pk_fma_f32 v[20:21], v[200:201], v[200:201], v[20:21]
	v_pk_fma_f32 v[12:13], v[12:13], v[12:13], v[14:15]
	v_add_f32_e32 v10, v10, v11
	v_add_f32_e32 v11, v18, v19
	v_add_f32_e32 v10, v12, v10
	v_add_f32_e32 v11, v20, v11
	v_add_f32_e32 v10, v13, v10
	v_add_f32_e32 v11, v21, v11
	v_add_f32_e32 v10, v11, v10
	v_mov_b32_e32 v11, v10
	s_nop 1
	v_permlane16_swap_b32 v10, v11
	s_waitcnt lgkmcnt(0)
	v_add_f32_e32 v10, v10, v11
	v_mov_b32_e32 v11, v10
	s_nop 1
	v_permlane32_swap_b32 v10, v11
	s_and_saveexec_b64 s[30:31], s[38:39]
	s_cbranch_execz .LBB0_342
	s_waitcnt lgkmcnt(0)
	v_add_f32_e32 v10, v10, v11
	v_mul_f32_e32 v10, 0x49800000, v10
	v_mul_f32_e32 v11, 0x2f800000, v10
	v_cvt_u32_f32_e32 v11, v11
	v_cvt_f32_u32_e32 v12, v11
	v_fmac_f32_e32 v10, 0xcf800000, v12
	v_cvt_u32_f32_e32 v10, v10
	global_atomic_add_x2 v[58:59], v[10:11], off offset:1280
.LBB0_342:
	s_or_b64 exec, exec, s[30:31]
	s_waitcnt lgkmcnt(0)
	v_pk_mul_f32 v[10:11], v[112:113], v[112:113]
	v_pk_mul_f32 v[2:3], v[2:3], v[2:3]
	v_pk_fma_f32 v[10:11], v[110:111], v[110:111], v[10:11]
	v_pk_mul_f32 v[12:13], v[108:109], v[108:109]
	v_pk_fma_f32 v[2:3], v[6:7], v[6:7], v[2:3]
	v_pk_mul_f32 v[6:7], v[8:9], v[8:9]
	v_pk_fma_f32 v[12:13], v[106:107], v[106:107], v[12:13]
	v_pk_fma_f32 v[4:5], v[4:5], v[4:5], v[6:7]
	v_add_f32_e32 v2, v2, v3
	v_add_f32_e32 v3, v10, v11
	v_add_f32_e32 v2, v4, v2
	v_add_f32_e32 v3, v12, v3
	v_add_f32_e32 v2, v5, v2
	v_add_f32_e32 v3, v13, v3
	v_add_f32_e32 v2, v3, v2
	v_mov_b32_e32 v3, v2
	s_nop 1
	v_permlane16_swap_b32 v2, v3
	s_waitcnt lgkmcnt(0)
	v_add_f32_e32 v2, v2, v3
	v_mov_b32_e32 v3, v2
	s_nop 1
	v_permlane32_swap_b32 v2, v3
	s_and_saveexec_b64 s[30:31], s[38:39]
	s_cbranch_execz .LBB0_344
	s_waitcnt lgkmcnt(0)
	v_add_f32_e32 v2, v2, v3
	v_mul_f32_e32 v2, 0x49800000, v2
	v_mul_f32_e32 v3, 0x2f800000, v2
	v_cvt_u32_f32_e32 v3, v3
	v_cvt_f32_u32_e32 v4, v3
	v_fmac_f32_e32 v2, 0xcf800000, v4
	v_cvt_u32_f32_e32 v2, v2
	global_atomic_add_x2 v[58:59], v[2:3], off offset:1408

;     template <int QVV> __device__ __forceinline__ void run(f32x4 (&acc)[2][2][4][2], const Unit& u, int wr, int wc, int fr, int fq) const {
;         const bool qm = u.seg != 0; const int rq = qm ? 64 * (u.seg - 1) : 0;
;         const bool active = !(qm && wr == 1);
;         const int v = u.pm < 4 ? 4 : ((u.pm - 4) >> 5);
;         char* sb = (char*)(S + ((size_t)u.pm * BM + rq) * DM + u.pn * BM);
;         const char* gp = (const char*)(gate + (size_t)v * (NMOD * DM) + u.pn * BM);
;         const bool hasn = ng != nullptr;
;         const char* pgp = (const char*)(pg + u.pn * BM); const char* psp = (const char*)(psc + (size_t)v * (NMOD * DM) + u.pn * BM);
;         const char* ngp = (const char*)(ng + u.pn * BM); const char* nsp = (const char*)(nsc + (size_t)v * (NMOD * DM) + u.pn * BM);
;         unsigned co = (unsigned)(wc * 32 + 8 * fq);
;         asm volatile("" : "+v"(co));
;         unsigned lo = ((unsigned)((wr * 64 + fr) * DM) + co) * 2u;
;         asm volatile("" : "+v"(lo));
;         if (active) {
;         float ss[2][4];
; #pragma unroll
;         for (int ai = 0; ai < 2; ++ai)
; #pragma unroll
;             for (int m = 0; m < 4; ++m) ss[ai][m] = 0.f;
; #pragma unroll
;         for (int bj = 0; bj < 2; ++bj) {
;             const unsigned cb4 = (co + bj * HALF) * 4u;
;             f32x4 vg0 = *(const f32x4*)(gp + cb4), vg1 = *(const f32x4*)(gp + cb4 + 16), vp0 = *(const f32x4*)(pgp + cb4), vp1 = *(const f32x4*)(pgp + cb4 + 16), vs0 = *(const f32x4*)(psp + cb4), vs1 = *(const f32x4*)(psp + cb4 + 16);
;             f32x4 vn0 = {1.f, 1.f, 1.f, 1.f}, vn1 = vn0, vt0 = {0.f, 0.f, 0.f, 0.f}, vt1 = vt0;
;             if (hasn) { vn0 = *(const f32x4*)(ngp + cb4); vn1 = *(const f32x4*)(ngp + cb4 + 16); vt0 = *(const f32x4*)(nsp + cb4); vt1 = *(const f32x4*)(nsp + cb4 + 16); }
;             asm volatile("" : "+v"(vg0), "+v"(vg1), "+v"(vp0), "+v"(vp1), "+v"(vs0), "+v"(vs1), "+v"(vn0), "+v"(vn1), "+v"(vt0), "+v"(vt1));
;             const f32x4 g0 = vg0 * fac, g1 = vg1 * fac;
;             const f32x4 p0 = vp0 * (vs0 + 1.0f), p1 = vp1 * (vs1 + 1.0f);
;             f32x4 r0, r1;
; #pragma unroll
;             for (int i = 0; i < 4; ++i) { r0[i] = __builtin_amdgcn_rcpf(p0[i]); r1[i] = __builtin_amdgcn_rcpf(p1[i]); }
;             const f32x4 c0 = vn0 * (vt0 + 1.0f), c1 = vn1 * (vt1 + 1.0f);
;             u32x4 hin[2][4];
; #pragma unroll
.LBB0_363:
	s_waitcnt lgkmcnt(14)
	v_lshl_or_b32 v66, v131, 3, s26
	v_lshlrev_b32_e32 v67, 12, v136
	s_andn2_b64 vcc, exec, s[30:31]
	v_lshl_add_u32 v174, v66, 1, v67
	s_movk_i32 s22, 0x25ff
	s_mov_b32 s26, 0xffff
	s_mov_b32 s27, 0xac00
	s_mov_b32 s28, 0x70000
	s_cbranch_vccnz .LBB0_373
	v_readlane_b32 s15, v253, 22
	s_ashr_i32 s35, s34, 31
	s_lshl_b32 s14, s15, 2
	s_add_u32 s10, s10, s14
	s_addc_u32 s11, s11, 0
	s_add_u32 s38, s10, 0x50000
	s_addc_u32 s39, s11, 0
	s_add_u32 s40, s12, s14
	s_addc_u32 s41, s13, 0
	s_add_u32 s42, s10, 0x4a000
	s_addc_u32 s43, s11, 0
	s_add_u32 s44, s8, s14
	s_addc_u32 s45, s9, 0
	s_add_u32 s46, s10, 0x4c000
	s_waitcnt lgkmcnt(0)
	v_lshlrev_b32_e32 v128, 2, v66
	s_addc_u32 s47, s11, 0
	global_load_dwordx4 v[82:85], v128, s[44:45] offset:16
	global_load_dwordx4 v[92:95], v128, s[44:45]
	global_load_dwordx4 v[96:99], v128, s[42:43] offset:16
	global_load_dwordx4 v[100:103], v128, s[42:43]
	global_load_dwordx4 v[70:73], v128, s[40:41] offset:16
	global_load_dwordx4 v[74:77], v128, s[40:41]
	global_load_dwordx4 v[104:107], v128, s[38:39] offset:16
	global_load_dwordx4 v[108:111], v128, s[38:39]
	global_load_dwordx4 v[112:115], v128, s[46:47] offset:16
	global_load_dwordx4 v[116:119], v128, s[46:47]
	v_readlane_b32 s8, v253, 24
	v_readlane_b32 s9, v253, 25
	s_add_u32 s5, s5, s8
	s_addc_u32 s7, s7, s9
	v_readlane_b32 s8, v253, 46
	s_add_u32 s5, s5, s8
	s_addc_u32 s7, s7, 0
	s_lshl_b32 s8, s15, 1
	s_add_u32 s30, s5, s8
	s_addc_u32 s31, s7, 0
	v_lshl_add_u64 v[66:67], s[30:31], 0, v[174:175]
	s_mov_b32 s5, 0x10000
	v_add_co_u32_e32 v88, vcc, s5, v66
	s_mov_b32 s5, 0x30000
	s_nop 0
	v_addc_co_u32_e32 v89, vcc, 0, v67, vcc
	v_add_co_u32_e32 v90, vcc, s79, v66
	v_add_u32_e32 v129, 0x10000, v174
	s_nop 0
	v_addc_co_u32_e32 v91, vcc, 0, v67, vcc
	v_add_co_u32_e32 v86, vcc, s5, v66
	v_add_u32_e32 v132, 0x20000, v174
	s_nop 0
	v_addc_co_u32_e32 v87, vcc, 0, v67, vcc
	v_cmp_eq_u32_e32 vcc, 0, v131
	v_add_u32_e32 v131, 0x20100, v174
	v_readlane_b32 s8, v253, 13
	v_readlane_b32 s9, v253, 14
	s_lshl_b64 s[8:9], s[8:9], 3
	s_add_u32 s2, s2, s8
	v_readlane_b32 s5, v253, 45
	s_addc_u32 s3, s3, s9
	s_lshl_b32 s5, s5, 3
	s_add_u32 s5, s2, s5
	s_addc_u32 s7, s3, 0
	s_lshl_b64 s[2:3], s[34:35], 3
	s_add_u32 s2, s5, s2
	s_addc_u32 s3, s7, s3
	s_waitcnt vmcnt(0)
	global_load_dwordx4 v[120:123], v174, s[30:31]
	global_load_dwordx4 v[66:69], v[86:87], off
	global_load_dwordx4 v[124:127], v[88:89], off
	global_load_dwordx4 v[78:81], v[90:91], off
	v_add_f32_e32 v133, 1.0, v100
	v_add_f32_e32 v134, 1.0, v96
	v_add_f32_e32 v135, 1.0, v101
	v_add_f32_e32 v136, 1.0, v97
	v_add_f32_e32 v137, 1.0, v102
	v_add_f32_e32 v138, 1.0, v98
	v_add_f32_e32 v139, 1.0, v103
	v_add_f32_e32 v140, 1.0, v99
	v_pk_mul_f32 v[118:119], v[118:119], 0.5 op_sel_hi:[1,0]
	v_pk_mul_f32 v[96:97], v[114:115], 0.5 op_sel_hi:[1,0]
	v_pk_mul_f32 v[98:99], v[112:113], 0.5 op_sel_hi:[1,0]
	v_pk_add_f32 v[100:101], v[108:109], 1.0 op_sel_hi:[1,0]
	v_pk_add_f32 v[102:103], v[104:105], 1.0 op_sel_hi:[1,0]
	v_pk_add_f32 v[104:105], v[110:111], 1.0 op_sel_hi:[1,0]
	v_mul_f32_e32 v108, v92, v133
	v_mul_f32_e32 v109, v82, v134
	v_mul_f32_e32 v110, v93, v135
	v_mul_f32_e32 v111, v83, v136
	v_mul_f32_e32 v112, v94, v137
	v_mul_f32_e32 v113, v84, v138
	v_mul_f32_e32 v114, v95, v139
	v_mul_f32_e32 v115, v85, v140
	v_pk_mul_f32 v[74:75], v[74:75], v[100:101]
	v_pk_mul_f32 v[60:61], v[60:61], v[96:97]
	v_pk_mul_f32 v[58:59], v[58:59], v[98:99]
	v_pk_mul_f32 v[84:85], v[76:77], v[104:105]
	v_pk_mul_f32 v[52:53], v[52:53], v[96:97]
	v_pk_mul_f32 v[50:51], v[50:51], v[98:99]
	v_pk_mul_f32 v[76:77], v[44:45], v[96:97]
	v_pk_mul_f32 v[42:43], v[42:43], v[98:99]
	v_pk_mul_f32 v[94:95], v[40:41], v[118:119]
	v_pk_mul_f32 v[96:97], v[36:37], v[96:97]
	v_pk_mul_f32 v[34:35], v[34:35], v[98:99]
	v_rcp_f32_e32 v36, v108
	v_rcp_f32_e32 v40, v109
	v_rcp_f32_e32 v37, v110
	v_rcp_f32_e32 v41, v111
	v_rcp_f32_e32 v98, v112
	v_rcp_f32_e32 v100, v113
	v_rcp_f32_e32 v99, v114
	v_rcp_f32_e32 v101, v115
	v_pk_mul_f32 v[116:117], v[116:117], 0.5 op_sel_hi:[1,0]
	v_pk_add_f32 v[106:107], v[106:107], 1.0 op_sel_hi:[1,0]
	v_pk_mul_f32 v[64:65], v[64:65], v[118:119]
	v_pk_mul_f32 v[62:63], v[62:63], v[116:117]
	v_pk_mul_f32 v[82:83], v[70:71], v[102:103]
	v_pk_mul_f32 v[92:93], v[72:73], v[106:107]
	v_pk_mul_f32 v[72:73], v[48:49], v[118:119]
	v_pk_mul_f32 v[56:57], v[56:57], v[118:119]
	v_pk_mul_f32 v[54:55], v[54:55], v[116:117]
	v_pk_mul_f32 v[46:47], v[46:47], v[116:117]
	v_pk_mul_f32 v[38:39], v[38:39], v[116:117]
	s_waitcnt vmcnt(3)
	v_lshlrev_b32_e32 v44, 16, v120
	v_and_b32_e32 v45, 0xffff0000, v120
	v_lshlrev_b32_e32 v48, 16, v122
	v_and_b32_e32 v49, 0xffff0000, v122
	v_lshlrev_b32_e32 v70, 16, v121
	v_and_b32_e32 v71, 0xffff0000, v121
	v_lshlrev_b32_e32 v102, 16, v123
	v_and_b32_e32 v103, 0xffff0000, v123
	s_waitcnt vmcnt(1)
	v_lshlrev_b32_e32 v104, 16, v124
	v_and_b32_e32 v105, 0xffff0000, v124
	v_lshlrev_b32_e32 v106, 16, v126
	v_and_b32_e32 v107, 0xffff0000, v126
	v_lshlrev_b32_e32 v108, 16, v125
	v_and_b32_e32 v109, 0xffff0000, v125
	v_lshlrev_b32_e32 v110, 16, v127
	v_and_b32_e32 v111, 0xffff0000, v127
	s_waitcnt vmcnt(0)
;     template <int QVV> __device__ __forceinline__ void run(f32x4 (&acc)[2][2][4][2], const Unit& u, int wr, int wc, int fr, int fq) const {
;     ...
;         for (int bj = 0; bj < 2; ++bj) {
;             const unsigned cb4 = (co + bj * HALF) * 4u;
;             f32x4 vg0 = *(const f32x4*)(gp + cb4), vg1 = *(const f32x4*)(gp + cb4 + 16), vp0 = *(const f32x4*)(pgp + cb4), vp1 = *(const f32x4*)(pgp + cb4 + 16), vs0 = *(const f32x4*)(psp + cb4), vs1 = *(const f32x4*)(psp + cb4 + 16);
;             f32x4 vn0 = {1.f, 1.f, 1.f, 1.f}, vn1 = vn0, vt0 = {0.f, 0.f, 0.f, 0.f}, vt1 = vt0;
;             if (hasn) { vn0 = *(const f32x4*)(ngp + cb4); vn1 = *(const f32x4*)(ngp + cb4 + 16); vt0 = *(const f32x4*)(nsp + cb4); vt1 = *(const f32x4*)(nsp + cb4 + 16); }
;             asm volatile("" : "+v"(vg0), "+v"(vg1), "+v"(vp0), "+v"(vp1), "+v"(vs0), "+v"(vs1), "+v"(vn0), "+v"(vn1), "+v"(vt0), "+v"(vt1));
;             const f32x4 g0 = vg0 * fac, g1 = vg1 * fac;
;             const f32x4 p0 = vp0 * (vs0 + 1.0f), p1 = vp1 * (vs1 + 1.0f);
;             f32x4 r0, r1;
; #pragma unroll
;             for (int i = 0; i < 4; ++i) { r0[i] = __builtin_amdgcn_rcpf(p0[i]); r1[i] = __builtin_amdgcn_rcpf(p1[i]); }
;             const f32x4 c0 = vn0 * (vt0 + 1.0f), c1 = vn1 * (vt1 + 1.0f);
;             u32x4 hin[2][4];
; #pragma unroll
;             for (int ai = 0; ai < 2; ++ai)
; #pragma unroll
;                 for (int m = 0; m < 4; ++m) { if (ai == 1 && qm) continue; hin[ai][m] = *(const u32x4*)(sb + lo + (unsigned)((ai * HALF + m * 16) * DM + bj * HALF) * 2u); }
; #pragma unroll
;             for (int ai = 0; ai < 2; ++ai)
; #pragma unroll
;                 for (int m = 0; m < 4; ++m) { if (ai == 1 && qm) continue;
;                     const unsigned off = lo + (unsigned)((ai * HALF + m * 16) * DM + bj * HALF) * 2u;
;                     float hv[8]; unpack8(hin[ai][m], hv);
;                     float y[8]; float t = 0.f;
; #pragma unroll
;                     for (int i = 0; i < 4; ++i) { const float a0 = hv[i] * r0[i] + g0[i] * acc[ai][bj][m][0][i], a1 = hv[4 + i] * r1[i] + g1[i] * acc[ai][bj][m][1][i];
;                         t += a0 * a0 + a1 * a1; y[i] = a0 * c0[i]; y[4 + i] = a1 * c1[i]; }
;                     ss[ai][m] += t;
;                     *(u32x4*)(sb + off) = pack8(y); }
	v_lshlrev_b32_e32 v112, 16, v78
	v_and_b32_e32 v113, 0xffff0000, v78
	v_lshlrev_b32_e32 v114, 16, v80
	v_and_b32_e32 v115, 0xffff0000, v80
	v_lshlrev_b32_e32 v78, 16, v79
	v_and_b32_e32 v79, 0xffff0000, v79
	v_lshlrev_b32_e32 v80, 16, v81
	v_and_b32_e32 v81, 0xffff0000, v81
	v_lshlrev_b32_e32 v116, 16, v66
	v_and_b32_e32 v117, 0xffff0000, v66
	v_lshlrev_b32_e32 v118, 16, v68
	v_and_b32_e32 v119, 0xffff0000, v68
	v_lshlrev_b32_e32 v120, 16, v67
	v_and_b32_e32 v121, 0xffff0000, v67
	v_pk_fma_f32 v[62:63], v[36:37], v[44:45], v[62:63]
	v_pk_fma_f32 v[66:67], v[40:41], v[48:49], v[58:59]
	v_pk_fma_f32 v[64:65], v[98:99], v[70:71], v[64:65]
	v_pk_fma_f32 v[70:71], v[100:101], v[102:103], v[60:61]
	v_pk_fma_f32 v[54:55], v[36:37], v[104:105], v[54:55]
	v_pk_fma_f32 v[58:59], v[40:41], v[106:107], v[50:51]
	v_pk_fma_f32 v[56:57], v[98:99], v[108:109], v[56:57]
	v_pk_fma_f32 v[60:61], v[100:101], v[110:111], v[52:53]
	v_pk_fma_f32 v[44:45], v[36:37], v[112:113], v[46:47]
	v_pk_fma_f32 v[48:49], v[40:41], v[114:115], v[42:43]
	v_pk_fma_f32 v[46:47], v[98:99], v[78:79], v[72:73]
	v_pk_fma_f32 v[50:51], v[100:101], v[80:81], v[76:77]
	v_pk_fma_f32 v[38:39], v[36:37], v[116:117], v[38:39]
	v_pk_fma_f32 v[40:41], v[40:41], v[118:119], v[34:35]
	v_pk_mul_f32 v[34:35], v[74:75], v[62:63]
	v_pk_mul_f32 v[36:37], v[82:83], v[66:67]
	v_pk_mul_f32 v[52:53], v[84:85], v[64:65]
	v_pk_mul_f32 v[72:73], v[92:93], v[70:71]
	v_pk_fma_f32 v[42:43], v[98:99], v[120:121], v[94:95]
	v_pk_mul_f32 v[76:77], v[74:75], v[54:55]
	v_pk_mul_f32 v[78:79], v[82:83], v[58:59]
	v_pk_mul_f32 v[80:81], v[84:85], v[56:57]
	v_pk_mul_f32 v[94:95], v[92:93], v[60:61]
	v_pk_mul_f32 v[98:99], v[74:75], v[44:45]
	v_pk_mul_f32 v[102:103], v[82:83], v[48:49]
	v_pk_mul_f32 v[104:105], v[84:85], v[46:47]
	v_pk_mul_f32 v[106:107], v[92:93], v[50:51]
	v_cvt_pk_bf16_f32 v34, v34, v35
	v_cvt_pk_bf16_f32 v35, v52, v53
	v_cvt_pk_bf16_f32 v36, v36, v37
	v_cvt_pk_bf16_f32 v37, v72, v73
	v_pk_mul_f32 v[108:109], v[74:75], v[38:39]
	v_cvt_pk_bf16_f32 v72, v76, v77
	v_cvt_pk_bf16_f32 v73, v80, v81
	v_cvt_pk_bf16_f32 v74, v78, v79
	v_cvt_pk_bf16_f32 v75, v94, v95
	v_cvt_pk_bf16_f32 v76, v98, v99
	v_cvt_pk_bf16_f32 v77, v104, v105
	v_cvt_pk_bf16_f32 v78, v102, v103
	v_cvt_pk_bf16_f32 v79, v106, v107
	global_store_dwordx4 v174, v[34:37], s[30:31]
	global_store_dwordx4 v129, v[72:75], s[30:31]
	global_store_dwordx4 v132, v[76:79], s[30:31]
	v_lshlrev_b32_e32 v34, 16, v69
	v_and_b32_e32 v35, 0xffff0000, v69
	v_pk_fma_f32 v[52:53], v[100:101], v[34:35], v[96:97]
	v_pk_mul_f32 v[82:83], v[82:83], v[40:41]
	v_pk_mul_f32 v[36:37], v[84:85], v[42:43]
	v_pk_mul_f32 v[68:69], v[92:93], v[52:53]
	v_add_u32_e32 v72, 0x30000, v174
	v_cvt_pk_bf16_f32 v34, v108, v109
	v_cvt_pk_bf16_f32 v35, v36, v37
	v_cvt_pk_bf16_f32 v36, v82, v83
	v_cvt_pk_bf16_f32 v37, v68, v69
	global_store_dwordx4 v72, v[34:37], s[30:31]
	v_pk_mul_f32 v[84:85], v[66:67], v[66:67]
	v_pk_mul_f32 v[70:71], v[70:71], v[70:71]
	v_add_u32_e32 v34, 0x200, v128
	global_load_dwordx4 v[72:75], v34, s[46:47] offset:16
	global_load_dwordx4 v[76:79], v34, s[46:47]
	global_load_dwordx4 v[80:83], v34, s[44:45] offset:16
	global_load_dwordx4 v[92:95], v34, s[44:45]
	global_load_dwordx4 v[96:99], v34, s[42:43] offset:16
	global_load_dwordx4 v[100:103], v34, s[42:43]
	global_load_dwordx4 v[104:107], v34, s[40:41] offset:16
	global_load_dwordx4 v[108:111], v34, s[40:41]
	global_load_dwordx4 v[112:115], v34, s[38:39] offset:16
	global_load_dwordx4 v[116:119], v34, s[38:39]
	s_waitcnt vmcnt(0)
	global_load_dwordx4 v[120:123], v174, s[30:31] offset:256
	global_load_dwordx4 v[124:127], v[88:89], off offset:256
	global_load_dwordx4 v[34:37], v[90:91], off offset:256
	global_load_dwordx4 v[66:69], v[86:87], off offset:256
	v_add_f32_e32 v90, 1.0, v100
	v_add_f32_e32 v91, 1.0, v96
	v_add_f32_e32 v96, 1.0, v101
	v_add_f32_e32 v97, 1.0, v97
	v_add_f32_e32 v100, 1.0, v102
	v_add_f32_e32 v98, 1.0, v98
	v_add_f32_e32 v101, 1.0, v103
	v_add_f32_e32 v99, 1.0, v99
	v_pk_fma_f32 v[84:85], v[62:63], v[62:63], v[84:85]
	v_pk_fma_f32 v[70:71], v[64:65], v[64:65], v[70:71]
	v_pk_mul_f32 v[62:63], v[78:79], 0.5 op_sel_hi:[1,0]
	v_pk_mul_f32 v[64:65], v[76:77], 0.5 op_sel_hi:[1,0]
	v_pk_mul_f32 v[74:75], v[74:75], 0.5 op_sel_hi:[1,0]
	v_pk_mul_f32 v[72:73], v[72:73], 0.5 op_sel_hi:[1,0]
	v_pk_add_f32 v[86:87], v[118:119], 1.0 op_sel_hi:[1,0]
	v_pk_add_f32 v[88:89], v[114:115], 1.0 op_sel_hi:[1,0]
	v_mul_f32_e32 v92, v92, v90
	v_mul_f32_e32 v102, v80, v91
	v_mul_f32_e32 v93, v93, v96
	v_mul_f32_e32 v96, v81, v97
	v_mul_f32_e32 v94, v94, v100
	v_mul_f32_e32 v97, v82, v98
	v_mul_f32_e32 v95, v95, v101
	v_mul_f32_e32 v98, v83, v99
	v_pk_mul_f32 v[32:33], v[32:33], v[62:63]
	v_pk_mul_f32 v[30:31], v[30:31], v[64:65]
	v_pk_mul_f32 v[28:29], v[28:29], v[74:75]
	v_pk_mul_f32 v[26:27], v[26:27], v[72:73]
	v_pk_mul_f32 v[80:81], v[110:111], v[86:87]
	v_pk_mul_f32 v[82:83], v[106:107], v[88:89]
	v_pk_mul_f32 v[86:87], v[24:25], v[62:63]
	v_pk_mul_f32 v[22:23], v[22:23], v[64:65]
	v_pk_mul_f32 v[88:89], v[20:21], v[74:75]
	v_pk_mul_f32 v[20:21], v[18:19], v[72:73]
	v_pk_mul_f32 v[16:17], v[16:17], v[62:63]
	v_pk_mul_f32 v[14:15], v[14:15], v[64:65]
	v_pk_mul_f32 v[90:91], v[12:13], v[74:75]
	v_pk_mul_f32 v[12:13], v[10:11], v[72:73]
	v_pk_mul_f32 v[8:9], v[8:9], v[62:63]
	v_pk_mul_f32 v[6:7], v[6:7], v[64:65]
	v_pk_mul_f32 v[62:63], v[4:5], v[74:75]
	v_pk_mul_f32 v[4:5], v[2:3], v[72:73]
	v_rcp_f32_e32 v2, v92
	v_rcp_f32_e32 v64, v102
	v_rcp_f32_e32 v3, v93
	v_rcp_f32_e32 v65, v96
	v_rcp_f32_e32 v72, v94
	v_rcp_f32_e32 v74, v97
	v_rcp_f32_e32 v73, v95
	v_rcp_f32_e32 v75, v98
	v_pk_add_f32 v[76:77], v[116:117], 1.0 op_sel_hi:[1,0]
	v_pk_add_f32 v[78:79], v[112:113], 1.0 op_sel_hi:[1,0]
	v_pk_mul_f32 v[76:77], v[108:109], v[76:77]
	v_pk_mul_f32 v[78:79], v[104:105], v[78:79]
	v_add_u32_e32 v128, 0x100, v174
	v_add_u32_e32 v129, 0x10100, v174
	s_waitcnt vmcnt(3)
; __device__ __forceinline__ void unpack8(const u32x4 w, float (&f)[8]) { f[0] = bflo(w.x); f[1] = bfhi(w.x); f[2] = bflo(w.y); f[3] = bfhi(w.y); f[4] = bflo(w.z); f[5] = bfhi(w.z); f[6] = bflo(w.w); f[7] = bfhi(w.w); }
; __device__ __forceinline__ u32x4 pack8(const float (&f)[8]) { u32x4 w; w.x = pk2(f[0], f[1]); w.y = pk2(f[2], f[3]); w.z = pk2(f[4], f[5]); w.w = pk2(f[6], f[7]); return w; }
;     template <int QVV> __device__ __forceinline__ void run(f32x4 (&acc)[2][2][4][2], const Unit& u, int wr, int wc, int fr, int fq) const {
;     ...
;             for (int ai = 0; ai < 2; ++ai)
; #pragma unroll
;                 for (int m = 0; m < 4; ++m) { if (ai == 1 && qm) continue;
;                     const unsigned off = lo + (unsigned)((ai * HALF + m * 16) * DM + bj * HALF) * 2u;
;                     float hv[8]; unpack8(hin[ai][m], hv);
;                     float y[8]; float t = 0.f;
; #pragma unroll
;                     for (int i = 0; i < 4; ++i) { const float a0 = hv[i] * r0[i] + g0[i] * acc[ai][bj][m][0][i], a1 = hv[4 + i] * r1[i] + g1[i] * acc[ai][bj][m][1][i];
;                         t += a0 * a0 + a1 * a1; y[i] = a0 * c0[i]; y[4 + i] = a1 * c1[i]; }
;                     ss[ai][m] += t;
;                     *(u32x4*)(sb + off) = pack8(y); }
;             asm volatile("" ::: "memory");
;         }
;         if (hasn) {
;             unsigned long long* sp = ssq + u.pm * BM + rq + wr * 64 + fr;
; #pragma unroll
;             for (int ai = 0; ai < 2; ++ai)
; #pragma unroll
;                 for (int m = 0; m < 4; ++m) { if (ai == 1 && qm) continue; float t = ss[ai][m]; t += __shfl_xor(t, 16); t += __shfl_xor(t, 32);
;                     const float xs = t * SSQ_SCALE; const unsigned xh = (unsigned)(xs * 2.3283064365386963e-10f), xl = (unsigned)__builtin_fmaf(-(float)xh, 4294967296.0f, xs);
;                     if (fq == 0) atomicAdd(sp + ai * HALF + m * 16, ((unsigned long long)xh << 32) | xl); }
	v_lshlrev_b32_e32 v10, 16, v120
	v_and_b32_e32 v11, 0xffff0000, v120
	v_lshlrev_b32_e32 v18, 16, v122
	v_and_b32_e32 v19, 0xffff0000, v122
	v_lshlrev_b32_e32 v24, 16, v121
	v_and_b32_e32 v25, 0xffff0000, v121
	v_lshlrev_b32_e32 v92, 16, v123
	v_and_b32_e32 v93, 0xffff0000, v123
	s_waitcnt vmcnt(2)
	v_lshlrev_b32_e32 v94, 16, v124
	v_and_b32_e32 v95, 0xffff0000, v124
	v_lshlrev_b32_e32 v96, 16, v126
	v_and_b32_e32 v97, 0xffff0000, v126
	v_lshlrev_b32_e32 v98, 16, v125
	v_and_b32_e32 v99, 0xffff0000, v125
	v_lshlrev_b32_e32 v100, 16, v127
	v_and_b32_e32 v101, 0xffff0000, v127
	s_waitcnt vmcnt(1)
	v_lshlrev_b32_e32 v102, 16, v34
	v_and_b32_e32 v103, 0xffff0000, v34
	v_lshlrev_b32_e32 v104, 16, v36
	v_and_b32_e32 v105, 0xffff0000, v36
	v_lshlrev_b32_e32 v34, 16, v35
	v_and_b32_e32 v35, 0xffff0000, v35
	v_lshlrev_b32_e32 v36, 16, v37
	v_and_b32_e32 v37, 0xffff0000, v37
	s_waitcnt vmcnt(0)
	v_lshlrev_b32_e32 v106, 16, v66
	v_and_b32_e32 v107, 0xffff0000, v66
	v_lshlrev_b32_e32 v108, 16, v68
	v_and_b32_e32 v109, 0xffff0000, v68
	v_lshlrev_b32_e32 v66, 16, v67
	v_and_b32_e32 v67, 0xffff0000, v67
	v_lshlrev_b32_e32 v68, 16, v69
	v_and_b32_e32 v69, 0xffff0000, v69
	v_pk_fma_f32 v[110:111], v[2:3], v[10:11], v[30:31]
	v_pk_fma_f32 v[112:113], v[64:65], v[18:19], v[26:27]
	v_pk_fma_f32 v[114:115], v[72:73], v[24:25], v[32:33]
	v_pk_fma_f32 v[92:93], v[74:75], v[92:93], v[28:29]
	v_pk_fma_f32 v[18:19], v[2:3], v[94:95], v[22:23]
	v_pk_fma_f32 v[24:25], v[64:65], v[96:97], v[20:21]
	v_pk_fma_f32 v[20:21], v[72:73], v[98:99], v[86:87]
	v_pk_fma_f32 v[26:27], v[74:75], v[100:101], v[88:89]
	v_pk_fma_f32 v[10:11], v[2:3], v[102:103], v[14:15]
	v_pk_fma_f32 v[14:15], v[64:65], v[104:105], v[12:13]
	v_pk_fma_f32 v[12:13], v[72:73], v[34:35], v[16:17]
	v_pk_fma_f32 v[16:17], v[74:75], v[36:37], v[90:91]
	v_pk_fma_f32 v[2:3], v[2:3], v[106:107], v[6:7]
	v_pk_fma_f32 v[6:7], v[64:65], v[108:109], v[4:5]
	v_pk_fma_f32 v[4:5], v[72:73], v[66:67], v[8:9]
	v_pk_fma_f32 v[8:9], v[74:75], v[68:69], v[62:63]
	v_pk_mul_f32 v[22:23], v[76:77], v[110:111]
	v_pk_mul_f32 v[30:31], v[78:79], v[112:113]
	v_pk_mul_f32 v[32:33], v[80:81], v[114:115]
	v_pk_mul_f32 v[34:35], v[82:83], v[92:93]
	v_pk_mul_f32 v[36:37], v[76:77], v[18:19]
	v_pk_mul_f32 v[62:63], v[78:79], v[24:25]
	v_pk_mul_f32 v[64:65], v[80:81], v[20:21]
	v_pk_mul_f32 v[66:67], v[82:83], v[26:27]
	v_pk_mul_f32 v[68:69], v[76:77], v[10:11]
	v_pk_mul_f32 v[72:73], v[78:79], v[14:15]
	v_pk_mul_f32 v[74:75], v[80:81], v[12:13]
	v_pk_mul_f32 v[86:87], v[82:83], v[16:17]
	v_pk_mul_f32 v[76:77], v[76:77], v[2:3]
	v_pk_mul_f32 v[78:79], v[78:79], v[6:7]
	v_pk_mul_f32 v[80:81], v[80:81], v[4:5]
	v_cvt_pk_bf16_f32 v28, v22, v23
	v_cvt_pk_bf16_f32 v29, v32, v33
	v_cvt_pk_bf16_f32 v30, v30, v31
	v_cvt_pk_bf16_f32 v31, v34, v35
	v_cvt_pk_bf16_f32 v32, v36, v37
	v_pk_mul_f32 v[22:23], v[82:83], v[8:9]
	v_cvt_pk_bf16_f32 v33, v64, v65
	v_cvt_pk_bf16_f32 v34, v62, v63
	v_cvt_pk_bf16_f32 v35, v66, v67
	v_cvt_pk_bf16_f32 v62, v68, v69
	v_cvt_pk_bf16_f32 v63, v74, v75
	v_cvt_pk_bf16_f32 v64, v72, v73
	v_cvt_pk_bf16_f32 v65, v86, v87
	global_store_dwordx4 v128, v[28:31], s[30:31]
	global_store_dwordx4 v129, v[32:35], s[30:31]
	global_store_dwordx4 v131, v[62:65], s[30:31]
	v_cvt_pk_bf16_f32 v28, v76, v77
	v_add_u32_e32 v32, 0x30100, v174
	v_cvt_pk_bf16_f32 v29, v80, v81
	v_cvt_pk_bf16_f32 v30, v78, v79
	v_cvt_pk_bf16_f32 v31, v22, v23
	global_store_dwordx4 v32, v[28:31], s[30:31]
	v_pk_mul_f32 v[22:23], v[92:93], v[92:93]
	v_lshlrev_b32_e32 v174, 3, v130
	v_pk_mul_f32 v[28:29], v[112:113], v[112:113]
	v_pk_fma_f32 v[22:23], v[114:115], v[114:115], v[22:23]
	v_pk_fma_f32 v[28:29], v[110:111], v[110:111], v[28:29]
	v_add_f32_e32 v30, v84, v85
	v_add_f32_e32 v28, v28, v29
	v_add_f32_e32 v22, v22, v28
	v_add_f32_e32 v22, v23, v22
	v_xor_b32_e32 v23, 16, v230
	v_add_f32_e32 v30, v70, v30
	v_cmp_lt_i32_e64 s[38:39], v23, v232
	v_add_f32_e32 v30, v71, v30
	v_add_f32_e32 v22, v30, v22
	v_cndmask_b32_e64 v23, v230, v23, s[38:39]
	v_lshlrev_b32_e32 v28, 2, v23
	v_mov_b32_e32 v23, v22
	s_nop 1
	v_permlane16_swap_b32 v22, v23
	s_waitcnt lgkmcnt(0)
	v_add_f32_e32 v30, v22, v23
	v_xor_b32_e32 v22, 32, v230
	v_cmp_lt_i32_e64 s[38:39], v22, v232
	s_nop 1
	v_cndmask_b32_e64 v22, v230, v22, s[38:39]
	v_lshlrev_b32_e32 v29, 2, v22
	v_mov_b32_e32 v31, v30
	s_nop 1
	v_permlane32_swap_b32 v30, v31
	v_lshl_add_u64 v[22:23], s[2:3], 0, v[174:175]
	s_and_saveexec_b64 s[30:31], vcc
	s_cbranch_execz .LBB0_366
	s_waitcnt lgkmcnt(0)
	v_add_f32_e32 v30, v30, v31
	v_mul_f32_e32 v30, 0x49800000, v30
	v_mul_f32_e32 v31, 0x2f800000, v30
	v_cvt_u32_f32_e32 v31, v31
	v_cvt_f32_u32_e32 v32, v31
	v_fmac_f32_e32 v30, 0xcf800000, v32
	v_cvt_u32_f32_e32 v30, v30
	global_atomic_add_x2 v[22:23], v[30:31], off
;     template <int QVV> __device__ __forceinline__ void run(f32x4 (&acc)[2][2][4][2], const Unit& u, int wr, int wc, int fr, int fq) const {
;     ...
;         if (hasn) {
;             unsigned long long* sp = ssq + u.pm * BM + rq + wr * 64 + fr;
; #pragma unroll
;             for (int ai = 0; ai < 2; ++ai)
; #pragma unroll
;                 for (int m = 0; m < 4; ++m) { if (ai == 1 && qm) continue; float t = ss[ai][m]; t += __shfl_xor(t, 16); t += __shfl_xor(t, 32);
;                     const float xs = t * SSQ_SCALE; const unsigned xh = (unsigned)(xs * 2.3283064365386963e-10f), xl = (unsigned)__builtin_fmaf(-(float)xh, 4294967296.0f, xs);
;                     if (fq == 0) atomicAdd(sp + ai * HALF + m * 16, ((unsigned long long)xh << 32) | xl); }
.LBB0_366:
	s_or_b64 exec, exec, s[30:31]
	s_waitcnt lgkmcnt(0)
	v_pk_mul_f32 v[30:31], v[58:59], v[58:59]
	v_pk_mul_f32 v[24:25], v[24:25], v[24:25]
	v_pk_fma_f32 v[30:31], v[54:55], v[54:55], v[30:31]
	v_pk_mul_f32 v[32:33], v[60:61], v[60:61]
	v_pk_fma_f32 v[18:19], v[18:19], v[18:19], v[24:25]
	v_pk_mul_f32 v[24:25], v[26:27], v[26:27]
	v_pk_fma_f32 v[32:33], v[56:57], v[56:57], v[32:33]
	v_pk_fma_f32 v[20:21], v[20:21], v[20:21], v[24:25]
	v_add_f32_e32 v18, v18, v19
	v_add_f32_e32 v19, v30, v31
	v_add_f32_e32 v18, v20, v18
	v_add_f32_e32 v19, v32, v19
	v_add_f32_e32 v18, v21, v18
	v_add_f32_e32 v19, v33, v19
	v_add_f32_e32 v18, v19, v18
	v_mov_b32_e32 v19, v18
	s_nop 1
	v_permlane16_swap_b32 v18, v19
	s_waitcnt lgkmcnt(0)
	v_add_f32_e32 v18, v18, v19
	v_mov_b32_e32 v19, v18
	s_nop 1
	v_permlane32_swap_b32 v18, v19
	s_and_saveexec_b64 s[30:31], vcc
	s_cbranch_execz .LBB0_368
	s_waitcnt lgkmcnt(0)
	v_add_f32_e32 v18, v18, v19
	v_mul_f32_e32 v18, 0x49800000, v18
	v_mul_f32_e32 v19, 0x2f800000, v18
	v_cvt_u32_f32_e32 v19, v19
	v_cvt_f32_u32_e32 v20, v19
	v_fmac_f32_e32 v18, 0xcf800000, v20
	v_cvt_u32_f32_e32 v18, v18
	global_atomic_add_x2 v[22:23], v[18:19], off offset:128
.LBB0_368:
	s_or_b64 exec, exec, s[30:31]
	s_waitcnt lgkmcnt(0)
	v_pk_mul_f32 v[18:19], v[48:49], v[48:49]
	v_pk_mul_f32 v[14:15], v[14:15], v[14:15]
	v_pk_fma_f32 v[18:19], v[44:45], v[44:45], v[18:19]
	v_pk_mul_f32 v[20:21], v[50:51], v[50:51]
	v_pk_fma_f32 v[10:11], v[10:11], v[10:11], v[14:15]
	v_pk_mul_f32 v[14:15], v[16:17], v[16:17]
	v_pk_fma_f32 v[20:21], v[46:47], v[46:47], v[20:21]
	v_pk_fma_f32 v[12:13], v[12:13], v[12:13], v[14:15]
	v_add_f32_e32 v10, v10, v11
	v_add_f32_e32 v11, v18, v19
	v_add_f32_e32 v10, v12, v10
	v_add_f32_e32 v11, v20, v11
	v_add_f32_e32 v10, v13, v10
	v_add_f32_e32 v11, v21, v11
	v_add_f32_e32 v10, v11, v10
	v_mov_b32_e32 v11, v10
	s_nop 1
	v_permlane16_swap_b32 v10, v11
	s_waitcnt lgkmcnt(0)
	v_add_f32_e32 v10, v10, v11
	v_mov_b32_e32 v11, v10
	s_nop 1
	v_permlane32_swap_b32 v10, v11
	s_and_saveexec_b64 s[30:31], vcc
	s_cbranch_execz .LBB0_370
	s_waitcnt lgkmcnt(0)
	v_add_f32_e32 v10, v10, v11
	v_mul_f32_e32 v10, 0x49800000, v10
	v_mul_f32_e32 v11, 0x2f800000, v10
	v_cvt_u32_f32_e32 v11, v11
	v_cvt_f32_u32_e32 v12, v11
	v_fmac_f32_e32 v10, 0xcf800000, v12
	v_cvt_u32_f32_e32 v10, v10
	global_atomic_add_x2 v[22:23], v[10:11], off offset:256
.LBB0_370:
	s_or_b64 exec, exec, s[30:31]
	s_waitcnt lgkmcnt(0)
	v_pk_mul_f32 v[10:11], v[40:41], v[40:41]
	v_pk_mul_f32 v[6:7], v[6:7], v[6:7]
	v_pk_fma_f32 v[10:11], v[38:39], v[38:39], v[10:11]
	v_pk_mul_f32 v[12:13], v[52:53], v[52:53]
	v_pk_fma_f32 v[2:3], v[2:3], v[2:3], v[6:7]
	v_pk_mul_f32 v[6:7], v[8:9], v[8:9]
	v_pk_fma_f32 v[12:13], v[42:43], v[42:43], v[12:13]
	v_pk_fma_f32 v[4:5], v[4:5], v[4:5], v[6:7]
	v_add_f32_e32 v2, v2, v3
	v_add_f32_e32 v3, v10, v11
	v_add_f32_e32 v2, v4, v2
	v_add_f32_e32 v3, v12, v3
	v_add_f32_e32 v2, v5, v2
	v_add_f32_e32 v3, v13, v3
	v_add_f32_e32 v2, v3, v2
	v_mov_b32_e32 v3, v2
	s_nop 1
	v_permlane16_swap_b32 v2, v3
	s_waitcnt lgkmcnt(0)
	v_add_f32_e32 v2, v2, v3
	v_mov_b32_e32 v3, v2
	s_nop 1
	v_permlane32_swap_b32 v2, v3
	s_and_saveexec_b64 s[30:31], vcc
	s_cbranch_execz .LBB0_372
	s_waitcnt lgkmcnt(0)
	v_add_f32_e32 v2, v2, v3
	v_mul_f32_e32 v2, 0x49800000, v2
	v_mul_f32_e32 v3, 0x2f800000, v2
	v_cvt_u32_f32_e32 v3, v3
	v_cvt_f32_u32_e32 v4, v3
	v_fmac_f32_e32 v2, 0xcf800000, v4
	v_cvt_u32_f32_e32 v2, v2
	global_atomic_add_x2 v[22:23], v[2:3], off offset:384

;     template <int QVV> __device__ __forceinline__ void run(f32x4 (&acc)[2][2][4][2], const Unit& u, int wr, int wc, int fr, int fq) const {
;         const bool qm = u.seg != 0; const int rq = qm ? 64 * (u.seg - 1) : 0;
;         const bool active = !(qm && wr == 1);
;         const int v = u.pm < 4 ? 4 : ((u.pm - 4) >> 5);
;         char* sb = (char*)(S + ((size_t)u.pm * BM + rq) * DM + u.pn * BM);
;         const char* gp = (const char*)(gate + (size_t)v * (NMOD * DM) + u.pn * BM);
;         const bool hasn = ng != nullptr;
;         const char* pgp = (const char*)(pg + u.pn * BM); const char* psp = (const char*)(psc + (size_t)v * (NMOD * DM) + u.pn * BM);
;         const char* ngp = (const char*)(ng + u.pn * BM); const char* nsp = (const char*)(nsc + (size_t)v * (NMOD * DM) + u.pn * BM);
;         unsigned co = (unsigned)(wc * 32 + 8 * fq);
;         asm volatile("" : "+v"(co));
;         unsigned lo = ((unsigned)((wr * 64 + fr) * DM) + co) * 2u;
;         asm volatile("" : "+v"(lo));
;         if (active) {
;         float ss[2][4];
; #pragma unroll
;         for (int ai = 0; ai < 2; ++ai)
; #pragma unroll
;             for (int m = 0; m < 4; ++m) ss[ai][m] = 0.f;
; #pragma unroll
;         for (int bj = 0; bj < 2; ++bj) {
;             const unsigned cb4 = (co + bj * HALF) * 4u;
;             f32x4 vg0 = *(const f32x4*)(gp + cb4), vg1 = *(const f32x4*)(gp + cb4 + 16), vp0 = *(const f32x4*)(pgp + cb4), vp1 = *(const f32x4*)(pgp + cb4 + 16), vs0 = *(const f32x4*)(psp + cb4), vs1 = *(const f32x4*)(psp + cb4 + 16);
;             f32x4 vn0 = {1.f, 1.f, 1.f, 1.f}, vn1 = vn0, vt0 = {0.f, 0.f, 0.f, 0.f}, vt1 = vt0;
;             if (hasn) { vn0 = *(const f32x4*)(ngp + cb4); vn1 = *(const f32x4*)(ngp + cb4 + 16); vt0 = *(const f32x4*)(nsp + cb4); vt1 = *(const f32x4*)(nsp + cb4 + 16); }
;             asm volatile("" : "+v"(vg0), "+v"(vg1), "+v"(vp0), "+v"(vp1), "+v"(vs0), "+v"(vs1), "+v"(vn0), "+v"(vn1), "+v"(vt0), "+v"(vt1));
;             const f32x4 g0 = vg0 * fac, g1 = vg1 * fac;
;             const f32x4 p0 = vp0 * (vs0 + 1.0f), p1 = vp1 * (vs1 + 1.0f);
;             f32x4 r0, r1;
; #pragma unroll
;             for (int i = 0; i < 4; ++i) { r0[i] = __builtin_amdgcn_rcpf(p0[i]); r1[i] = __builtin_amdgcn_rcpf(p1[i]); }
;             const f32x4 c0 = vn0 * (vt0 + 1.0f), c1 = vn1 * (vt1 + 1.0f);
;             u32x4 hin[2][4];
; #pragma unroll
.LBB0_1534:
	s_ashr_i32 s59, s58, 31
	s_lshl_b64 s[46:47], s[58:59], 20
	s_add_u32 s59, s5, s46
	s_addc_u32 s64, s7, s47
	s_lshl_b32 s62, s62, 8
	s_ashr_i32 s63, s62, 31
	s_lshl_b64 s[46:47], s[62:63], 1
	s_add_u32 s46, s59, s46
	s_addc_u32 s47, s64, s47
	s_lshl_b64 s[30:31], s[30:31], 2
	s_add_u32 s59, s24, s30
	s_addc_u32 s64, s25, s31
	s_lshl_b64 s[70:71], s[62:63], 2
	s_add_u32 s62, s59, s70
	s_addc_u32 s63, s64, s71
	s_add_u32 s64, s8, s70
	s_addc_u32 s65, s9, s71
	s_add_u32 s59, s26, s30
	s_addc_u32 s67, s27, s31
	s_add_u32 s66, s59, s70
	s_addc_u32 s67, s67, s71
	s_add_u32 s68, s12, s70
	s_addc_u32 s69, s13, s71
	s_add_u32 s30, s28, s30
	s_addc_u32 s31, s29, s31
	v_mov_b32_e32 v106, v208
	s_add_u32 s70, s30, s70
	s_addc_u32 s71, s31, s71
	v_lshl_add_u32 v174, v106, 1, v209
	v_lshlrev_b32_e32 v212, 2, v106
	global_load_dwordx4 v[106:109], v212, s[62:63] offset:16
	global_load_dwordx4 v[110:113], v212, s[62:63]
	global_load_dwordx4 v[114:117], v212, s[64:65] offset:16
	global_load_dwordx4 v[118:121], v212, s[64:65]
	global_load_dwordx4 v[122:125], v212, s[66:67] offset:16
	global_load_dwordx4 v[126:129], v212, s[66:67]
	global_load_dwordx4 v[194:197], v212, s[68:69] offset:16
	global_load_dwordx4 v[198:201], v212, s[68:69]
	global_load_dwordx4 v[202:205], v212, s[70:71] offset:16
	global_load_dwordx4 v[214:217], v212, s[70:71]
	v_lshl_add_u64 v[172:173], s[46:47], 0, v[174:175]
	s_mov_b32 s30, 0x10000
	v_add_co_u32_e32 v184, vcc, s30, v172
	s_mov_b32 s30, 0x30000
	s_nop 0
	v_addc_co_u32_e32 v185, vcc, 0, v173, vcc
	v_add_co_u32_e32 v182, vcc, s79, v172
	s_waitcnt vmcnt(0)
	global_load_dwordx4 v[218:221], v174, s[46:47]
	global_load_dwordx4 v[222:225], v[184:185], off
	v_add_f32_e32 v126, 1.0, v126
	v_mul_f32_e32 v118, v118, v126
	v_addc_co_u32_e32 v183, vcc, 0, v173, vcc
	v_rcp_f32_e32 v192, v118
	v_add_f32_e32 v118, 1.0, v122
	global_load_dwordx4 v[142:145], v[182:183], off
	v_mul_f32_e32 v114, v114, v118
	v_add_co_u32_e32 v164, vcc, s30, v172
	v_rcp_f32_e32 v188, v114
	v_add_f32_e32 v114, 1.0, v127
	v_addc_co_u32_e32 v165, vcc, 0, v173, vcc
	v_mul_f32_e32 v114, v119, v114
	global_load_dwordx4 v[130:133], v[164:165], off
	v_rcp_f32_e32 v193, v114
	v_add_f32_e32 v114, 1.0, v123
	v_mul_f32_e32 v114, v115, v114
	v_rcp_f32_e32 v189, v114
	v_add_f32_e32 v114, 1.0, v128
	v_mul_f32_e32 v114, v120, v114
	s_mov_b32 s30, 0x80000
	v_rcp_f32_e32 v190, v114
	v_add_f32_e32 v114, 1.0, v124
	v_add_co_u32_e32 v166, vcc, s30, v172
	v_mul_f32_e32 v114, v116, v114
	s_nop 0
	v_addc_co_u32_e32 v167, vcc, 0, v173, vcc
	v_rcp_f32_e32 v186, v114
	v_add_f32_e32 v114, 1.0, v129
	global_load_dwordx4 v[126:129], v[166:167], off
	s_mov_b32 s30, 0x90000
	v_add_co_u32_e32 v168, vcc, s30, v172
	v_mul_f32_e32 v114, v121, v114
	s_nop 0
	v_addc_co_u32_e32 v169, vcc, 0, v173, vcc
	v_rcp_f32_e32 v191, v114
	v_add_f32_e32 v114, 1.0, v125
	global_load_dwordx4 v[122:125], v[168:169], off
	s_mov_b32 s30, 0xa0000
	v_add_co_u32_e32 v170, vcc, s30, v172
	s_mov_b32 s30, 0xb0000
	s_nop 0
	v_addc_co_u32_e32 v171, vcc, 0, v173, vcc
	global_load_dwordx4 v[118:121], v[170:171], off
	v_add_co_u32_e32 v172, vcc, s30, v172
	v_mul_f32_e32 v114, v117, v114
	s_nop 0
	v_addc_co_u32_e32 v173, vcc, 0, v173, vcc
	v_rcp_f32_e32 v187, v114
	global_load_dwordx4 v[114:117], v[172:173], off
	v_pk_mul_f32 v[158:159], v[158:159], v[110:111]
	v_pk_mul_f32 v[226:227], v[160:161], v[112:113]
	v_pk_mul_f32 v[154:155], v[154:155], v[106:107]
	v_pk_mul_f32 v[156:157], v[156:157], v[108:109]
	v_pk_mul_f32 v[152:153], v[152:153], v[112:113]
	v_pk_mul_f32 v[150:151], v[150:151], v[110:111]
	v_pk_mul_f32 v[146:147], v[146:147], v[106:107]
	v_pk_mul_f32 v[140:141], v[140:141], v[112:113]
	v_pk_mul_f32 v[138:139], v[138:139], v[110:111]
	v_pk_mul_f32 v[134:135], v[134:135], v[106:107]
	v_pk_mul_f32 v[102:103], v[102:103], v[110:111]
	v_pk_mul_f32 v[98:99], v[98:99], v[106:107]
	v_pk_mul_f32 v[104:105], v[104:105], v[112:113]
	v_pk_mul_f32 v[100:101], v[100:101], v[108:109]
	v_pk_mul_f32 v[94:95], v[94:95], v[110:111]
	v_pk_mul_f32 v[90:91], v[90:91], v[106:107]
	v_pk_mul_f32 v[96:97], v[96:97], v[112:113]
	v_pk_mul_f32 v[92:93], v[92:93], v[108:109]
	v_pk_mul_f32 v[86:87], v[86:87], v[110:111]
	v_pk_mul_f32 v[82:83], v[82:83], v[106:107]
	v_pk_mul_f32 v[88:89], v[88:89], v[112:113]
	v_pk_mul_f32 v[84:85], v[84:85], v[108:109]
	s_waitcnt vmcnt(7)
	v_lshlrev_b32_e32 v180, 16, v218
	v_and_b32_e32 v181, 0xffff0000, v218
	v_pk_fma_f32 v[160:161], v[192:193], v[180:181], v[158:159]
	v_pk_add_f32 v[158:159], v[214:215], 1.0 op_sel_hi:[1,0]
	v_lshlrev_b32_e32 v214, 16, v221
	v_pk_mul_f32 v[158:159], v[198:199], v[158:159]
	v_lshlrev_b32_e32 v198, 16, v220
	v_and_b32_e32 v199, 0xffff0000, v220
	v_pk_fma_f32 v[198:199], v[188:189], v[198:199], v[154:155]
	v_pk_mul_f32 v[180:181], v[158:159], v[160:161]
	v_pk_mul_f32 v[154:155], v[198:199], v[198:199]
	v_and_b32_e32 v215, 0xffff0000, v221
	v_pk_fma_f32 v[154:155], v[160:161], v[160:161], v[154:155]
	v_pk_add_f32 v[160:161], v[202:203], 1.0 op_sel_hi:[1,0]
	v_pk_fma_f32 v[214:215], v[186:187], v[214:215], v[156:157]
	v_pk_mul_f32 v[160:161], v[194:195], v[160:161]
	v_lshlrev_b32_e32 v194, 16, v219
	v_and_b32_e32 v195, 0xffff0000, v219
	v_pk_mul_f32 v[202:203], v[160:161], v[198:199]
	v_pk_fma_f32 v[198:199], v[190:191], v[194:195], v[226:227]
	v_pk_add_f32 v[194:195], v[216:217], 1.0 op_sel_hi:[1,0]
	v_pk_mul_f32 v[156:157], v[214:215], v[214:215]
	v_pk_mul_f32 v[194:195], v[200:201], v[194:195]
	v_pk_fma_f32 v[156:157], v[198:199], v[198:199], v[156:157]
	v_pk_mul_f32 v[200:201], v[194:195], v[198:199]
	v_pk_add_f32 v[198:199], v[204:205], 1.0 op_sel_hi:[1,0]
	v_pk_mul_f32 v[78:79], v[78:79], v[110:111]
	v_pk_mul_f32 v[196:197], v[196:197], v[198:199]
	v_cvt_pk_bf16_f32 v198, v180, v181
	v_pk_mul_f32 v[204:205], v[196:197], v[214:215]
	v_cvt_pk_bf16_f32 v199, v200, v201
	v_cvt_pk_bf16_f32 v201, v204, v205
	s_waitcnt vmcnt(6)
; __device__ __forceinline__ void unpack8(const u32x4 w, float (&f)[8]) { f[0] = bflo(w.x); f[1] = bfhi(w.x); f[2] = bflo(w.y); f[3] = bfhi(w.y); f[4] = bflo(w.z); f[5] = bfhi(w.z); f[6] = bflo(w.w); f[7] = bfhi(w.w); }
; __device__ __forceinline__ u32x4 pack8(const float (&f)[8]) { u32x4 w; w.x = pk2(f[0], f[1]); w.y = pk2(f[2], f[3]); w.z = pk2(f[4], f[5]); w.w = pk2(f[6], f[7]); return w; }
;     template <int QVV> __device__ __forceinline__ void run(f32x4 (&acc)[2][2][4][2], const Unit& u, int wr, int wc, int fr, int fq) const {
;     ...
;                 for (int m = 0; m < 4; ++m) { if (ai == 1 && qm) continue; hin[ai][m] = *(const u32x4*)(sb + lo + (unsigned)((ai * HALF + m * 16) * DM + bj * HALF) * 2u); }
; #pragma unroll
;             for (int ai = 0; ai < 2; ++ai)
; #pragma unroll
;                 for (int m = 0; m < 4; ++m) { if (ai == 1 && qm) continue;
;                     const unsigned off = lo + (unsigned)((ai * HALF + m * 16) * DM + bj * HALF) * 2u;
;                     float hv[8]; unpack8(hin[ai][m], hv);
;                     float y[8]; float t = 0.f;
; #pragma unroll
;                     for (int i = 0; i < 4; ++i) { const float a0 = hv[i] * r0[i] + g0[i] * acc[ai][bj][m][0][i], a1 = hv[4 + i] * r1[i] + g1[i] * acc[ai][bj][m][1][i];
;                         t += a0 * a0 + a1 * a1; y[i] = a0 * c0[i]; y[4 + i] = a1 * c1[i]; }
;                     ss[ai][m] += t;
;                     *(u32x4*)(sb + off) = pack8(y); }
	v_lshlrev_b32_e32 v180, 16, v222
	v_and_b32_e32 v181, 0xffff0000, v222
	v_pk_mul_f32 v[204:205], v[148:149], v[108:109]
	v_lshlrev_b32_e32 v148, 16, v223
	v_and_b32_e32 v149, 0xffff0000, v223
	v_pk_fma_f32 v[150:151], v[192:193], v[180:181], v[150:151]
	v_lshlrev_b32_e32 v180, 16, v224
	v_and_b32_e32 v181, 0xffff0000, v224
	v_pk_fma_f32 v[148:149], v[190:191], v[148:149], v[152:153]
	v_lshlrev_b32_e32 v152, 16, v225
	v_and_b32_e32 v153, 0xffff0000, v225
	v_cvt_pk_bf16_f32 v200, v202, v203
	v_pk_fma_f32 v[146:147], v[188:189], v[180:181], v[146:147]
	v_pk_fma_f32 v[152:153], v[186:187], v[152:153], v[204:205]
	global_store_dwordx4 v174, v[198:201], s[46:47]
	v_pk_mul_f32 v[202:203], v[194:195], v[148:149]
	v_pk_mul_f32 v[204:205], v[196:197], v[152:153]
	v_pk_mul_f32 v[198:199], v[158:159], v[150:151]
	v_pk_mul_f32 v[200:201], v[160:161], v[146:147]
	v_add_u32_e32 v180, 0x10000, v174
	v_cvt_pk_bf16_f32 v198, v198, v199
	v_cvt_pk_bf16_f32 v199, v202, v203
	v_cvt_pk_bf16_f32 v200, v200, v201
	v_cvt_pk_bf16_f32 v201, v204, v205
	global_store_dwordx4 v180, v[198:201], s[46:47]
	s_waitcnt vmcnt(7)
	v_lshlrev_b32_e32 v180, 16, v142
	v_and_b32_e32 v181, 0xffff0000, v142
	v_pk_mul_f32 v[202:203], v[136:137], v[108:109]
	v_lshlrev_b32_e32 v136, 16, v143
	v_and_b32_e32 v137, 0xffff0000, v143
	v_pk_fma_f32 v[138:139], v[192:193], v[180:181], v[138:139]
	v_pk_fma_f32 v[136:137], v[190:191], v[136:137], v[140:141]
	v_pk_mul_f32 v[198:199], v[158:159], v[138:139]
	v_pk_mul_f32 v[142:143], v[194:195], v[136:137]
	v_lshlrev_b32_e32 v180, 16, v144
	v_and_b32_e32 v181, 0xffff0000, v144
	v_lshlrev_b32_e32 v140, 16, v145
	v_and_b32_e32 v141, 0xffff0000, v145
	v_cvt_pk_bf16_f32 v198, v198, v199
	v_cvt_pk_bf16_f32 v199, v142, v143
	s_waitcnt vmcnt(6)
	v_lshlrev_b32_e32 v142, 16, v130
	v_and_b32_e32 v143, 0xffff0000, v130
	v_pk_fma_f32 v[134:135], v[188:189], v[180:181], v[134:135]
	v_pk_fma_f32 v[140:141], v[186:187], v[140:141], v[202:203]
	v_pk_fma_f32 v[102:103], v[192:193], v[142:143], v[102:103]
	v_lshlrev_b32_e32 v142, 16, v132
	v_and_b32_e32 v143, 0xffff0000, v132
	v_pk_mul_f32 v[200:201], v[160:161], v[134:135]
	v_pk_mul_f32 v[144:145], v[196:197], v[140:141]
	v_pk_fma_f32 v[142:143], v[188:189], v[142:143], v[98:99]
	v_lshlrev_b32_e32 v98, 16, v131
	v_and_b32_e32 v99, 0xffff0000, v131
	v_add_u32_e32 v202, 0x20000, v174
	v_cvt_pk_bf16_f32 v200, v200, v201
	v_cvt_pk_bf16_f32 v201, v144, v145
	v_pk_fma_f32 v[130:131], v[190:191], v[98:99], v[104:105]
	v_lshlrev_b32_e32 v98, 16, v133
	v_and_b32_e32 v99, 0xffff0000, v133
	global_store_dwordx4 v202, v[198:201], s[46:47]
	v_pk_mul_f32 v[144:145], v[158:159], v[102:103]
	v_pk_mul_f32 v[180:181], v[160:161], v[142:143]
	v_pk_fma_f32 v[198:199], v[186:187], v[98:99], v[100:101]
	v_pk_mul_f32 v[104:105], v[194:195], v[130:131]
	v_pk_mul_f32 v[132:133], v[196:197], v[198:199]
	v_add_u32_e32 v200, 0x30000, v174
	v_cvt_pk_bf16_f32 v98, v144, v145
	v_cvt_pk_bf16_f32 v99, v104, v105
	v_cvt_pk_bf16_f32 v100, v180, v181
	v_cvt_pk_bf16_f32 v101, v132, v133
	global_store_dwordx4 v200, v[98:101], s[46:47]
	v_pk_mul_f32 v[74:75], v[74:75], v[106:107]
	v_pk_mul_f32 v[80:81], v[80:81], v[112:113]
	s_waitcnt vmcnt(7)
	v_lshlrev_b32_e32 v98, 16, v126
	v_and_b32_e32 v99, 0xffff0000, v126
	v_pk_fma_f32 v[104:105], v[192:193], v[98:99], v[94:95]
	v_lshlrev_b32_e32 v98, 16, v128
	v_and_b32_e32 v99, 0xffff0000, v128
	v_pk_fma_f32 v[132:133], v[188:189], v[98:99], v[90:91]
	v_lshlrev_b32_e32 v90, 16, v127
	v_and_b32_e32 v91, 0xffff0000, v127
	v_pk_fma_f32 v[144:145], v[190:191], v[90:91], v[96:97]
	v_lshlrev_b32_e32 v90, 16, v129
	v_and_b32_e32 v91, 0xffff0000, v129
	v_pk_fma_f32 v[202:203], v[186:187], v[90:91], v[92:93]
	v_pk_mul_f32 v[94:95], v[158:159], v[104:105]
	v_pk_mul_f32 v[98:99], v[160:161], v[132:133]
	v_pk_mul_f32 v[96:97], v[194:195], v[144:145]
	v_pk_mul_f32 v[100:101], v[196:197], v[202:203]
	v_add_u32_e32 v126, 0x80000, v174
	v_cvt_pk_bf16_f32 v90, v94, v95
	v_cvt_pk_bf16_f32 v91, v96, v97
	v_cvt_pk_bf16_f32 v92, v98, v99
	v_cvt_pk_bf16_f32 v93, v100, v101
	global_store_dwordx4 v126, v[90:93], s[46:47]
	v_add_u32_e32 v94, 0x90000, v174
	v_pk_mul_f32 v[76:77], v[76:77], v[108:109]
	s_waitcnt vmcnt(7)
	v_lshlrev_b32_e32 v90, 16, v122
	v_and_b32_e32 v91, 0xffff0000, v122
	v_pk_fma_f32 v[126:127], v[192:193], v[90:91], v[86:87]
	v_lshlrev_b32_e32 v90, 16, v124
	v_and_b32_e32 v91, 0xffff0000, v124
	v_pk_fma_f32 v[128:129], v[188:189], v[90:91], v[82:83]
	v_lshlrev_b32_e32 v82, 16, v123
	v_and_b32_e32 v83, 0xffff0000, v123
	v_pk_fma_f32 v[200:201], v[190:191], v[82:83], v[88:89]
	v_lshlrev_b32_e32 v82, 16, v125
	v_and_b32_e32 v83, 0xffff0000, v125
	v_pk_fma_f32 v[204:205], v[186:187], v[82:83], v[84:85]
	v_pk_mul_f32 v[86:87], v[158:159], v[126:127]
	v_pk_mul_f32 v[90:91], v[160:161], v[128:129]
	v_pk_mul_f32 v[88:89], v[194:195], v[200:201]
	v_pk_mul_f32 v[92:93], v[196:197], v[204:205]
	v_cvt_pk_bf16_f32 v82, v86, v87
	v_cvt_pk_bf16_f32 v83, v88, v89
	v_cvt_pk_bf16_f32 v84, v90, v91
	v_cvt_pk_bf16_f32 v85, v92, v93
	global_store_dwordx4 v94, v[82:85], s[46:47]
	v_add_u32_e32 v86, 0xa0000, v174
	v_pk_mul_f32 v[70:71], v[70:71], v[110:111]
	s_waitcnt vmcnt(7)
;     template <int QVV> __device__ __forceinline__ void run(f32x4 (&acc)[2][2][4][2], const Unit& u, int wr, int wc, int fr, int fq) const {
;     ...
;         for (int bj = 0; bj < 2; ++bj) {
;             const unsigned cb4 = (co + bj * HALF) * 4u;
;             f32x4 vg0 = *(const f32x4*)(gp + cb4), vg1 = *(const f32x4*)(gp + cb4 + 16), vp0 = *(const f32x4*)(pgp + cb4), vp1 = *(const f32x4*)(pgp + cb4 + 16), vs0 = *(const f32x4*)(psp + cb4), vs1 = *(const f32x4*)(psp + cb4 + 16);
;             f32x4 vn0 = {1.f, 1.f, 1.f, 1.f}, vn1 = vn0, vt0 = {0.f, 0.f, 0.f, 0.f}, vt1 = vt0;
;             if (hasn) { vn0 = *(const f32x4*)(ngp + cb4); vn1 = *(const f32x4*)(ngp + cb4 + 16); vt0 = *(const f32x4*)(nsp + cb4); vt1 = *(const f32x4*)(nsp + cb4 + 16); }
;             asm volatile("" : "+v"(vg0), "+v"(vg1), "+v"(vp0), "+v"(vp1), "+v"(vs0), "+v"(vs1), "+v"(vn0), "+v"(vn1), "+v"(vt0), "+v"(vt1));
;             const f32x4 g0 = vg0 * fac, g1 = vg1 * fac;
;             const f32x4 p0 = vp0 * (vs0 + 1.0f), p1 = vp1 * (vs1 + 1.0f);
;             f32x4 r0, r1;
; #pragma unroll
;             for (int i = 0; i < 4; ++i) { r0[i] = __builtin_amdgcn_rcpf(p0[i]); r1[i] = __builtin_amdgcn_rcpf(p1[i]); }
;             const f32x4 c0 = vn0 * (vt0 + 1.0f), c1 = vn1 * (vt1 + 1.0f);
;             u32x4 hin[2][4];
; #pragma unroll
;             for (int ai = 0; ai < 2; ++ai)
; #pragma unroll
;                 for (int m = 0; m < 4; ++m) { if (ai == 1 && qm) continue; hin[ai][m] = *(const u32x4*)(sb + lo + (unsigned)((ai * HALF + m * 16) * DM + bj * HALF) * 2u); }
; #pragma unroll
;             for (int ai = 0; ai < 2; ++ai)
; #pragma unroll
;                 for (int m = 0; m < 4; ++m) { if (ai == 1 && qm) continue;
;                     const unsigned off = lo + (unsigned)((ai * HALF + m * 16) * DM + bj * HALF) * 2u;
;                     float hv[8]; unpack8(hin[ai][m], hv);
;                     float y[8]; float t = 0.f;
; #pragma unroll
;                     for (int i = 0; i < 4; ++i) { const float a0 = hv[i] * r0[i] + g0[i] * acc[ai][bj][m][0][i], a1 = hv[4 + i] * r1[i] + g1[i] * acc[ai][bj][m][1][i];
;                         t += a0 * a0 + a1 * a1; y[i] = a0 * c0[i]; y[4 + i] = a1 * c1[i]; }
;                     ss[ai][m] += t;
;                     *(u32x4*)(sb + off) = pack8(y); }
	v_lshlrev_b32_e32 v82, 16, v118
	v_and_b32_e32 v83, 0xffff0000, v118
	v_pk_fma_f32 v[122:123], v[192:193], v[82:83], v[78:79]
	v_lshlrev_b32_e32 v82, 16, v120
	v_and_b32_e32 v83, 0xffff0000, v120
	v_pk_fma_f32 v[124:125], v[188:189], v[82:83], v[74:75]
	v_lshlrev_b32_e32 v74, 16, v119
	v_and_b32_e32 v75, 0xffff0000, v119
	v_pk_fma_f32 v[118:119], v[190:191], v[74:75], v[80:81]
	v_lshlrev_b32_e32 v74, 16, v121
	v_and_b32_e32 v75, 0xffff0000, v121
	v_pk_fma_f32 v[120:121], v[186:187], v[74:75], v[76:77]
	v_pk_mul_f32 v[78:79], v[158:159], v[122:123]
	v_pk_mul_f32 v[82:83], v[160:161], v[124:125]
	v_pk_mul_f32 v[80:81], v[194:195], v[118:119]
	v_pk_mul_f32 v[84:85], v[196:197], v[120:121]
	v_cvt_pk_bf16_f32 v74, v78, v79
	v_cvt_pk_bf16_f32 v75, v80, v81
	v_cvt_pk_bf16_f32 v76, v82, v83
	v_cvt_pk_bf16_f32 v77, v84, v85
	global_store_dwordx4 v86, v[74:77], s[46:47]
	v_pk_mul_f32 v[66:67], v[66:67], v[106:107]
	v_pk_mul_f32 v[72:73], v[72:73], v[112:113]
	s_waitcnt vmcnt(7)
	v_lshlrev_b32_e32 v74, 16, v114
	v_and_b32_e32 v75, 0xffff0000, v114
	v_pk_fma_f32 v[110:111], v[192:193], v[74:75], v[70:71]
	v_lshlrev_b32_e32 v74, 16, v116
	v_and_b32_e32 v75, 0xffff0000, v116
	v_pk_fma_f32 v[106:107], v[188:189], v[74:75], v[66:67]
	v_lshlrev_b32_e32 v66, 16, v115
	v_and_b32_e32 v67, 0xffff0000, v115
	v_pk_mul_f32 v[68:69], v[68:69], v[108:109]
	v_pk_fma_f32 v[108:109], v[190:191], v[66:67], v[72:73]
	v_lshlrev_b32_e32 v66, 16, v117
	v_and_b32_e32 v67, 0xffff0000, v117
	v_pk_fma_f32 v[112:113], v[186:187], v[66:67], v[68:69]
	v_pk_mul_f32 v[70:71], v[158:159], v[110:111]
	v_pk_mul_f32 v[74:75], v[160:161], v[106:107]
	v_pk_mul_f32 v[72:73], v[194:195], v[108:109]
	v_pk_mul_f32 v[76:77], v[196:197], v[112:113]
	v_add_u32_e32 v78, 0xb0000, v174
	v_cvt_pk_bf16_f32 v66, v70, v71
	v_cvt_pk_bf16_f32 v67, v72, v73
	v_cvt_pk_bf16_f32 v68, v74, v75
	v_cvt_pk_bf16_f32 v69, v76, v77
	global_store_dwordx4 v78, v[66:69], s[46:47]
	v_add_u32_e32 v94, 0x200, v212
	global_load_dwordx4 v[66:69], v94, s[62:63] offset:16
	global_load_dwordx4 v[70:73], v94, s[62:63]
	global_load_dwordx4 v[74:77], v94, s[64:65] offset:16
	global_load_dwordx4 v[82:85], v94, s[64:65]
	global_load_dwordx4 v[98:101], v94, s[66:67] offset:16
	global_load_dwordx4 v[186:189], v94, s[66:67]
	global_load_dwordx4 v[78:81], v94, s[68:69] offset:16
	global_load_dwordx4 v[90:93], v94, s[68:69]
	global_load_dwordx4 v[86:89], v94, s[70:71] offset:16
	s_nop 0
	global_load_dwordx4 v[94:97], v94, s[70:71]
	s_waitcnt vmcnt(0)
	s_nop 0
	v_add_f32_e32 v114, 1.0, v186
	v_mul_f32_e32 v82, v82, v114
	v_rcp_f32_e32 v160, v82
	v_add_f32_e32 v82, 1.0, v98
	v_mul_f32_e32 v74, v74, v82
	v_rcp_f32_e32 v116, v74
	v_add_f32_e32 v74, 1.0, v187
	v_mul_f32_e32 v74, v83, v74
	v_rcp_f32_e32 v161, v74
	v_add_f32_e32 v74, 1.0, v99
	v_mul_f32_e32 v74, v75, v74
	v_rcp_f32_e32 v117, v74
	v_add_f32_e32 v74, 1.0, v188
	v_mul_f32_e32 v74, v84, v74
	v_rcp_f32_e32 v158, v74
	v_add_f32_e32 v74, 1.0, v100
	v_mul_f32_e32 v74, v76, v74
	v_rcp_f32_e32 v114, v74
	v_add_f32_e32 v74, 1.0, v189
	v_mul_f32_e32 v74, v85, v74
	v_rcp_f32_e32 v159, v74
	v_add_f32_e32 v74, 1.0, v101
	v_mul_f32_e32 v74, v77, v74
	v_rcp_f32_e32 v115, v74
	global_load_dwordx4 v[186:189], v174, s[46:47] offset:256
	global_load_dwordx4 v[190:193], v[184:185], off offset:256
	s_nop 0
	global_load_dwordx4 v[182:185], v[182:183], off offset:256
	s_nop 0
	global_load_dwordx4 v[194:197], v[164:165], off offset:256
	s_nop 0
	global_load_dwordx4 v[164:167], v[166:167], off offset:256
	s_nop 0
	global_load_dwordx4 v[98:101], v[168:169], off offset:256
	global_load_dwordx4 v[82:85], v[170:171], off offset:256
	global_load_dwordx4 v[74:77], v[172:173], off offset:256
	v_pk_mul_f32 v[170:171], v[60:61], v[68:69]
	v_pk_add_f32 v[60:61], v[86:87], 1.0 op_sel_hi:[1,0]
	v_pk_mul_f32 v[64:65], v[64:65], v[72:73]
	v_pk_mul_f32 v[78:79], v[78:79], v[60:61]
	v_pk_mul_f32 v[62:63], v[62:63], v[70:71]
	v_pk_add_f32 v[94:95], v[94:95], 1.0 op_sel_hi:[1,0]
	v_pk_mul_f32 v[58:59], v[58:59], v[66:67]
	v_pk_add_f32 v[88:89], v[88:89], 1.0 op_sel_hi:[1,0]
	v_pk_mul_f32 v[90:91], v[90:91], v[94:95]
	v_pk_mul_f32 v[80:81], v[80:81], v[88:89]
	v_pk_mul_f32 v[56:57], v[56:57], v[72:73]
	v_pk_mul_f32 v[54:55], v[54:55], v[70:71]
	v_pk_mul_f32 v[50:51], v[50:51], v[66:67]
	v_add_u32_e32 v172, 0x10100, v174
	v_pk_mul_f32 v[48:49], v[48:49], v[72:73]
	v_pk_mul_f32 v[46:47], v[46:47], v[70:71]
	v_pk_mul_f32 v[42:43], v[42:43], v[66:67]
	v_pk_mul_f32 v[40:41], v[40:41], v[72:73]
	v_pk_mul_f32 v[38:39], v[38:39], v[70:71]
	v_pk_mul_f32 v[34:35], v[34:35], v[66:67]
	v_pk_mul_f32 v[32:33], v[32:33], v[72:73]
	v_pk_mul_f32 v[30:31], v[30:31], v[70:71]
	v_pk_mul_f32 v[26:27], v[26:27], v[66:67]
	v_pk_mul_f32 v[24:25], v[24:25], v[72:73]
	v_pk_mul_f32 v[22:23], v[22:23], v[70:71]
	v_pk_mul_f32 v[18:19], v[18:19], v[66:67]
	v_pk_mul_f32 v[16:17], v[16:17], v[72:73]
	v_pk_mul_f32 v[14:15], v[14:15], v[70:71]
	v_pk_mul_f32 v[10:11], v[10:11], v[66:67]
	v_pk_mul_f32 v[8:9], v[8:9], v[72:73]
	v_pk_mul_f32 v[6:7], v[6:7], v[70:71]
	v_pk_mul_f32 v[2:3], v[2:3], v[66:67]
	s_lshl_b32 s30, s58, 8
	s_ashr_i32 s31, s30, 31
	s_waitcnt vmcnt(7)
; __device__ __forceinline__ void unpack8(const u32x4 w, float (&f)[8]) { f[0] = bflo(w.x); f[1] = bfhi(w.x); f[2] = bflo(w.y); f[3] = bfhi(w.y); f[4] = bflo(w.z); f[5] = bfhi(w.z); f[6] = bflo(w.w); f[7] = bfhi(w.w); }
; __device__ __forceinline__ u32x4 pack8(const float (&f)[8]) { u32x4 w; w.x = pk2(f[0], f[1]); w.y = pk2(f[2], f[3]); w.z = pk2(f[4], f[5]); w.w = pk2(f[6], f[7]); return w; }
;     template <int QVV> __device__ __forceinline__ void run(f32x4 (&acc)[2][2][4][2], const Unit& u, int wr, int wc, int fr, int fq) const {
;     ...
;                 for (int m = 0; m < 4; ++m) { if (ai == 1 && qm) continue; hin[ai][m] = *(const u32x4*)(sb + lo + (unsigned)((ai * HALF + m * 16) * DM + bj * HALF) * 2u); }
; #pragma unroll
;             for (int ai = 0; ai < 2; ++ai)
; #pragma unroll
;                 for (int m = 0; m < 4; ++m) { if (ai == 1 && qm) continue;
;                     const unsigned off = lo + (unsigned)((ai * HALF + m * 16) * DM + bj * HALF) * 2u;
;                     float hv[8]; unpack8(hin[ai][m], hv);
;                     float y[8]; float t = 0.f;
; #pragma unroll
;                     for (int i = 0; i < 4; ++i) { const float a0 = hv[i] * r0[i] + g0[i] * acc[ai][bj][m][0][i], a1 = hv[4 + i] * r1[i] + g1[i] * acc[ai][bj][m][1][i];
;                         t += a0 * a0 + a1 * a1; y[i] = a0 * c0[i]; y[4 + i] = a1 * c1[i]; }
;                     ss[ai][m] += t;
;                     *(u32x4*)(sb + off) = pack8(y); }
	v_lshlrev_b32_e32 v60, 16, v187
	v_and_b32_e32 v61, 0xffff0000, v187
	v_lshlrev_b32_e32 v168, 16, v186
	v_and_b32_e32 v169, 0xffff0000, v186
	v_pk_fma_f32 v[60:61], v[158:159], v[60:61], v[64:65]
	v_pk_add_f32 v[64:65], v[96:97], 1.0 op_sel_hi:[1,0]
	v_pk_fma_f32 v[62:63], v[160:161], v[168:169], v[62:63]
	v_lshlrev_b32_e32 v168, 16, v188
	v_and_b32_e32 v169, 0xffff0000, v188
	v_pk_mul_f32 v[86:87], v[92:93], v[64:65]
	v_lshlrev_b32_e32 v64, 16, v189
	v_and_b32_e32 v65, 0xffff0000, v189
	v_pk_fma_f32 v[58:59], v[116:117], v[168:169], v[58:59]
	v_pk_fma_f32 v[64:65], v[114:115], v[64:65], v[170:171]
	v_pk_mul_f32 v[94:95], v[90:91], v[62:63]
	v_pk_mul_f32 v[168:169], v[78:79], v[58:59]
	v_pk_mul_f32 v[96:97], v[86:87], v[60:61]
	v_pk_mul_f32 v[88:89], v[80:81], v[64:65]
	v_add_u32_e32 v170, 0x100, v174
	v_cvt_pk_bf16_f32 v92, v94, v95
	v_cvt_pk_bf16_f32 v93, v96, v97
	v_cvt_pk_bf16_f32 v94, v168, v169
	v_cvt_pk_bf16_f32 v95, v88, v89
	global_store_dwordx4 v170, v[92:95], s[46:47]
	s_waitcnt vmcnt(7)
	v_lshlrev_b32_e32 v88, 16, v190
	v_and_b32_e32 v89, 0xffff0000, v190
	v_pk_mul_f32 v[94:95], v[52:53], v[68:69]
	v_lshlrev_b32_e32 v52, 16, v191
	v_and_b32_e32 v53, 0xffff0000, v191
	v_lshlrev_b32_e32 v92, 16, v192
	v_and_b32_e32 v93, 0xffff0000, v192
	v_pk_fma_f32 v[52:53], v[158:159], v[52:53], v[56:57]
	v_lshlrev_b32_e32 v56, 16, v193
	v_and_b32_e32 v57, 0xffff0000, v193
	v_pk_fma_f32 v[54:55], v[160:161], v[88:89], v[54:55]
	v_pk_fma_f32 v[50:51], v[116:117], v[92:93], v[50:51]
	v_pk_fma_f32 v[56:57], v[114:115], v[56:57], v[94:95]
	v_pk_mul_f32 v[88:89], v[90:91], v[54:55]
	v_pk_mul_f32 v[96:97], v[78:79], v[50:51]
	v_pk_mul_f32 v[168:169], v[86:87], v[52:53]
	v_pk_mul_f32 v[170:171], v[80:81], v[56:57]
	v_cvt_pk_bf16_f32 v92, v88, v89
	v_cvt_pk_bf16_f32 v93, v168, v169
	v_cvt_pk_bf16_f32 v94, v96, v97
	v_cvt_pk_bf16_f32 v95, v170, v171
	global_store_dwordx4 v172, v[92:95], s[46:47]
	s_waitcnt vmcnt(7)
	v_lshlrev_b32_e32 v88, 16, v182
	v_and_b32_e32 v89, 0xffff0000, v182
	v_pk_mul_f32 v[94:95], v[44:45], v[68:69]
	v_lshlrev_b32_e32 v44, 16, v183
	v_and_b32_e32 v45, 0xffff0000, v183
	v_lshlrev_b32_e32 v92, 16, v184
	v_and_b32_e32 v93, 0xffff0000, v184
	v_pk_fma_f32 v[44:45], v[158:159], v[44:45], v[48:49]
	v_lshlrev_b32_e32 v48, 16, v185
	v_and_b32_e32 v49, 0xffff0000, v185
	v_pk_fma_f32 v[46:47], v[160:161], v[88:89], v[46:47]
	v_pk_fma_f32 v[42:43], v[116:117], v[92:93], v[42:43]
	v_pk_fma_f32 v[48:49], v[114:115], v[48:49], v[94:95]
	v_pk_mul_f32 v[88:89], v[90:91], v[46:47]
	v_pk_mul_f32 v[96:97], v[78:79], v[42:43]
	v_pk_mul_f32 v[168:169], v[86:87], v[44:45]
	v_pk_mul_f32 v[170:171], v[80:81], v[48:49]
	v_add_u32_e32 v172, 0x20100, v174
	v_cvt_pk_bf16_f32 v92, v88, v89
	v_cvt_pk_bf16_f32 v93, v168, v169
	v_cvt_pk_bf16_f32 v94, v96, v97
	v_cvt_pk_bf16_f32 v95, v170, v171
	global_store_dwordx4 v172, v[92:95], s[46:47]
	s_waitcnt vmcnt(7)
	v_lshlrev_b32_e32 v88, 16, v194
	v_and_b32_e32 v89, 0xffff0000, v194
	v_pk_mul_f32 v[94:95], v[36:37], v[68:69]
	v_lshlrev_b32_e32 v36, 16, v195
	v_and_b32_e32 v37, 0xffff0000, v195
	v_lshlrev_b32_e32 v92, 16, v196
	v_and_b32_e32 v93, 0xffff0000, v196
	v_pk_fma_f32 v[36:37], v[158:159], v[36:37], v[40:41]
	v_lshlrev_b32_e32 v40, 16, v197
	v_and_b32_e32 v41, 0xffff0000, v197
	v_pk_fma_f32 v[38:39], v[160:161], v[88:89], v[38:39]
	v_pk_fma_f32 v[34:35], v[116:117], v[92:93], v[34:35]
	v_pk_fma_f32 v[40:41], v[114:115], v[40:41], v[94:95]
	v_pk_mul_f32 v[88:89], v[90:91], v[38:39]
	v_pk_mul_f32 v[96:97], v[78:79], v[34:35]
	v_pk_mul_f32 v[168:169], v[86:87], v[36:37]
	v_pk_mul_f32 v[170:171], v[80:81], v[40:41]
	v_add_u32_e32 v172, 0x30100, v174
	v_cvt_pk_bf16_f32 v92, v88, v89
	v_cvt_pk_bf16_f32 v93, v168, v169
	v_cvt_pk_bf16_f32 v94, v96, v97
	v_cvt_pk_bf16_f32 v95, v170, v171
	global_store_dwordx4 v172, v[92:95], s[46:47]
	s_waitcnt vmcnt(7)
	v_lshlrev_b32_e32 v88, 16, v164
	v_and_b32_e32 v89, 0xffff0000, v164
	v_pk_mul_f32 v[94:95], v[28:29], v[68:69]
	v_lshlrev_b32_e32 v28, 16, v165
	v_and_b32_e32 v29, 0xffff0000, v165
	v_lshlrev_b32_e32 v92, 16, v166
	v_and_b32_e32 v93, 0xffff0000, v166
	v_pk_fma_f32 v[28:29], v[158:159], v[28:29], v[32:33]
	v_lshlrev_b32_e32 v32, 16, v167
	v_and_b32_e32 v33, 0xffff0000, v167
	v_pk_fma_f32 v[30:31], v[160:161], v[88:89], v[30:31]
	v_pk_fma_f32 v[26:27], v[116:117], v[92:93], v[26:27]
	v_pk_fma_f32 v[32:33], v[114:115], v[32:33], v[94:95]
	v_pk_mul_f32 v[58:59], v[58:59], v[58:59]
	v_pk_mul_f32 v[88:89], v[90:91], v[30:31]
	v_pk_mul_f32 v[96:97], v[78:79], v[26:27]
	v_pk_mul_f32 v[164:165], v[86:87], v[28:29]
	v_pk_mul_f32 v[166:167], v[80:81], v[32:33]
	v_pk_mul_f32 v[64:65], v[64:65], v[64:65]
	v_pk_fma_f32 v[58:59], v[62:63], v[62:63], v[58:59]
	v_add_u32_e32 v168, 0x80100, v174
	v_cvt_pk_bf16_f32 v92, v88, v89
	v_cvt_pk_bf16_f32 v93, v164, v165
	v_cvt_pk_bf16_f32 v94, v96, v97
	v_cvt_pk_bf16_f32 v95, v166, v167
	v_pk_fma_f32 v[60:61], v[60:61], v[60:61], v[64:65]
	v_add_f32_e32 v58, v58, v59
	global_store_dwordx4 v168, v[92:95], s[46:47]
	v_add_f32_e32 v62, v154, v155
	v_add_f32_e32 v58, v60, v58
	v_pk_mul_f32 v[94:95], v[20:21], v[68:69]
	s_waitcnt vmcnt(7)
; __device__ __forceinline__ void unpack8(const u32x4 w, float (&f)[8]) { f[0] = bflo(w.x); f[1] = bfhi(w.x); f[2] = bflo(w.y); f[3] = bfhi(w.y); f[4] = bflo(w.z); f[5] = bfhi(w.z); f[6] = bflo(w.w); f[7] = bfhi(w.w); }
; __device__ __forceinline__ u32x4 pack8(const float (&f)[8]) { u32x4 w; w.x = pk2(f[0], f[1]); w.y = pk2(f[2], f[3]); w.z = pk2(f[4], f[5]); w.w = pk2(f[6], f[7]); return w; }
;     template <int QVV> __device__ __forceinline__ void run(f32x4 (&acc)[2][2][4][2], const Unit& u, int wr, int wc, int fr, int fq) const {
;     ...
;             for (int ai = 0; ai < 2; ++ai)
; #pragma unroll
;                 for (int m = 0; m < 4; ++m) { if (ai == 1 && qm) continue;
;                     const unsigned off = lo + (unsigned)((ai * HALF + m * 16) * DM + bj * HALF) * 2u;
;                     float hv[8]; unpack8(hin[ai][m], hv);
;                     float y[8]; float t = 0.f;
; #pragma unroll
;                     for (int i = 0; i < 4; ++i) { const float a0 = hv[i] * r0[i] + g0[i] * acc[ai][bj][m][0][i], a1 = hv[4 + i] * r1[i] + g1[i] * acc[ai][bj][m][1][i];
;                         t += a0 * a0 + a1 * a1; y[i] = a0 * c0[i]; y[4 + i] = a1 * c1[i]; }
;                     ss[ai][m] += t;
;                     *(u32x4*)(sb + off) = pack8(y); }
;             asm volatile("" ::: "memory");
;         }
;         if (hasn) {
;             unsigned long long* sp = ssq + u.pm * BM + rq + wr * 64 + fr;
; #pragma unroll
;             for (int ai = 0; ai < 2; ++ai)
; #pragma unroll
;                 for (int m = 0; m < 4; ++m) { if (ai == 1 && qm) continue; float t = ss[ai][m]; t += __shfl_xor(t, 16); t += __shfl_xor(t, 32);
;                     const float xs = t * SSQ_SCALE; const unsigned xh = (unsigned)(xs * 2.3283064365386963e-10f), xl = (unsigned)__builtin_fmaf(-(float)xh, 4294967296.0f, xs);
;                     if (fq == 0) atomicAdd(sp + ai * HALF + m * 16, ((unsigned long long)xh << 32) | xl); }
	v_lshlrev_b32_e32 v20, 16, v99
	v_and_b32_e32 v21, 0xffff0000, v99
	v_xor_b32_e32 v60, 16, v230
	v_lshlrev_b32_e32 v88, 16, v98
	v_and_b32_e32 v89, 0xffff0000, v98
	v_lshlrev_b32_e32 v92, 16, v100
	v_and_b32_e32 v93, 0xffff0000, v100
	v_pk_fma_f32 v[20:21], v[158:159], v[20:21], v[24:25]
	v_lshlrev_b32_e32 v24, 16, v101
	v_and_b32_e32 v25, 0xffff0000, v101
	v_add_f32_e32 v62, v156, v62
	v_cmp_lt_i32_e32 vcc, v60, v232
	v_pk_fma_f32 v[22:23], v[160:161], v[88:89], v[22:23]
	v_pk_fma_f32 v[18:19], v[116:117], v[92:93], v[18:19]
	v_pk_fma_f32 v[24:25], v[114:115], v[24:25], v[94:95]
	v_add_f32_e32 v62, v157, v62
	v_add_f32_e32 v58, v61, v58
	v_cndmask_b32_e32 v60, v230, v60, vcc
	v_pk_mul_f32 v[88:89], v[90:91], v[22:23]
	v_pk_mul_f32 v[96:97], v[78:79], v[18:19]
	v_pk_mul_f32 v[98:99], v[86:87], v[20:21]
	v_pk_mul_f32 v[100:101], v[80:81], v[24:25]
	v_add_f32_e32 v61, v62, v58
	v_lshlrev_b32_e32 v60, 2, v60
	v_add_u32_e32 v164, 0x90100, v174
	v_cvt_pk_bf16_f32 v92, v88, v89
	v_cvt_pk_bf16_f32 v93, v98, v99
	v_cvt_pk_bf16_f32 v94, v96, v97
	v_cvt_pk_bf16_f32 v95, v100, v101
	v_mov_b32_e32 v62, v61
	s_nop 1
	v_permlane16_swap_b32 v61, v62
	global_store_dwordx4 v164, v[92:95], s[46:47]
	s_waitcnt vmcnt(7)
	v_lshlrev_b32_e32 v88, 16, v82
	v_and_b32_e32 v89, 0xffff0000, v82
	v_pk_mul_f32 v[94:95], v[12:13], v[68:69]
	v_lshlrev_b32_e32 v12, 16, v83
	v_and_b32_e32 v13, 0xffff0000, v83
	v_lshlrev_b32_e32 v92, 16, v84
	v_and_b32_e32 v93, 0xffff0000, v84
	v_pk_fma_f32 v[12:13], v[158:159], v[12:13], v[16:17]
	v_lshlrev_b32_e32 v16, 16, v85
	v_and_b32_e32 v17, 0xffff0000, v85
	v_pk_fma_f32 v[14:15], v[160:161], v[88:89], v[14:15]
	v_pk_fma_f32 v[10:11], v[116:117], v[92:93], v[10:11]
	v_pk_fma_f32 v[16:17], v[114:115], v[16:17], v[94:95]
	v_pk_mul_f32 v[88:89], v[90:91], v[14:15]
	v_pk_mul_f32 v[92:93], v[78:79], v[10:11]
	v_pk_mul_f32 v[96:97], v[86:87], v[12:13]
	v_pk_mul_f32 v[94:95], v[80:81], v[16:17]
	v_add_u32_e32 v98, 0xa0100, v174
	v_cvt_pk_bf16_f32 v82, v88, v89
	v_cvt_pk_bf16_f32 v83, v96, v97
	v_cvt_pk_bf16_f32 v84, v92, v93
	v_cvt_pk_bf16_f32 v85, v94, v95
	v_pk_mul_f32 v[68:69], v[4:5], v[68:69]
	s_waitcnt vmcnt(6)
	v_lshlrev_b32_e32 v4, 16, v75
	v_and_b32_e32 v5, 0xffff0000, v75
	s_waitcnt lgkmcnt(0)
	v_add_f32_e32 v62, v61, v62
	v_xor_b32_e32 v61, 32, v230
	global_store_dwordx4 v98, v[82:85], s[46:47]
	v_lshlrev_b32_e32 v72, 16, v76
	v_and_b32_e32 v73, 0xffff0000, v76
	v_lshlrev_b32_e32 v82, 16, v74
	v_and_b32_e32 v83, 0xffff0000, v74
	v_pk_fma_f32 v[4:5], v[158:159], v[4:5], v[8:9]
	v_lshlrev_b32_e32 v8, 16, v77
	v_and_b32_e32 v9, 0xffff0000, v77
	v_cmp_lt_i32_e32 vcc, v61, v232
	v_pk_fma_f32 v[6:7], v[160:161], v[82:83], v[6:7]
	v_pk_fma_f32 v[2:3], v[116:117], v[72:73], v[2:3]
	v_pk_fma_f32 v[8:9], v[114:115], v[8:9], v[68:69]
	v_cndmask_b32_e32 v61, v230, v61, vcc
	v_pk_mul_f32 v[70:71], v[90:91], v[6:7]
	v_pk_mul_f32 v[72:73], v[78:79], v[2:3]
	v_pk_mul_f32 v[74:75], v[86:87], v[4:5]
	v_pk_mul_f32 v[76:77], v[80:81], v[8:9]
	v_lshlrev_b32_e32 v61, 2, v61
	v_add_u32_e32 v78, 0xb0100, v174
	v_cvt_pk_bf16_f32 v66, v70, v71
	v_cvt_pk_bf16_f32 v67, v74, v75
	v_cvt_pk_bf16_f32 v68, v72, v73
	v_cvt_pk_bf16_f32 v69, v76, v77
	v_mov_b32_e32 v63, v62
	s_nop 1
	v_permlane32_swap_b32 v62, v63
	global_store_dwordx4 v78, v[66:69], s[46:47]
	v_lshl_add_u64 v[58:59], s[30:31], 3, v[162:163]
	s_and_saveexec_b64 s[30:31], s[38:39]
	s_cbranch_execz .LBB0_1536
	s_waitcnt lgkmcnt(0)
	v_add_f32_e32 v62, v62, v63
	v_mul_f32_e32 v62, 0x49800000, v62
	v_mul_f32_e32 v63, 0x2f800000, v62
	v_cvt_u32_f32_e32 v63, v63
	v_cvt_f32_u32_e32 v64, v63
	v_fmac_f32_e32 v62, 0xcf800000, v64
	v_cvt_u32_f32_e32 v62, v62
	global_atomic_add_x2 v[58:59], v[62:63], off
.LBB0_1536:
	s_or_b64 exec, exec, s[30:31]
	s_waitcnt lgkmcnt(0)
	v_pk_mul_f32 v[62:63], v[146:147], v[146:147]
	v_pk_mul_f32 v[50:51], v[50:51], v[50:51]
	v_pk_fma_f32 v[62:63], v[150:151], v[150:151], v[62:63]
	v_pk_mul_f32 v[64:65], v[152:153], v[152:153]
	v_pk_fma_f32 v[50:51], v[54:55], v[54:55], v[50:51]
	v_pk_mul_f32 v[54:55], v[56:57], v[56:57]
	v_pk_fma_f32 v[64:65], v[148:149], v[148:149], v[64:65]
	v_pk_fma_f32 v[52:53], v[52:53], v[52:53], v[54:55]
	v_add_f32_e32 v50, v50, v51
	v_add_f32_e32 v51, v62, v63
	v_add_f32_e32 v50, v52, v50
	v_add_f32_e32 v51, v64, v51
	v_add_f32_e32 v50, v53, v50
	v_add_f32_e32 v51, v65, v51
	v_add_f32_e32 v50, v51, v50
	v_mov_b32_e32 v51, v50
	s_nop 1
	v_permlane16_swap_b32 v50, v51
	s_waitcnt lgkmcnt(0)
	v_add_f32_e32 v50, v50, v51
	v_mov_b32_e32 v51, v50
	s_nop 1
	v_permlane32_swap_b32 v50, v51
	s_and_saveexec_b64 s[30:31], s[38:39]
	s_cbranch_execz .LBB0_1538
	s_waitcnt lgkmcnt(0)
	v_add_f32_e32 v50, v50, v51
	v_mul_f32_e32 v50, 0x49800000, v50
	v_mul_f32_e32 v51, 0x2f800000, v50
	v_cvt_u32_f32_e32 v51, v51
	v_cvt_f32_u32_e32 v52, v51
	v_fmac_f32_e32 v50, 0xcf800000, v52
	v_cvt_u32_f32_e32 v50, v50
	global_atomic_add_x2 v[58:59], v[50:51], off offset:128
.LBB0_1538:
	s_or_b64 exec, exec, s[30:31]
	s_waitcnt lgkmcnt(0)
	v_pk_mul_f32 v[50:51], v[134:135], v[134:135]
	v_pk_mul_f32 v[42:43], v[42:43], v[42:43]
	v_pk_fma_f32 v[50:51], v[138:139], v[138:139], v[50:51]
	v_pk_mul_f32 v[52:53], v[140:141], v[140:141]
	v_pk_fma_f32 v[42:43], v[46:47], v[46:47], v[42:43]
	v_pk_mul_f32 v[46:47], v[48:49], v[48:49]
	v_pk_fma_f32 v[52:53], v[136:137], v[136:137], v[52:53]
	v_pk_fma_f32 v[44:45], v[44:45], v[44:45], v[46:47]
	v_add_f32_e32 v42, v42, v43
	v_add_f32_e32 v43, v50, v51
	v_add_f32_e32 v42, v44, v42
	v_add_f32_e32 v43, v52, v43
	v_add_f32_e32 v42, v45, v42
	v_add_f32_e32 v43, v53, v43
	v_add_f32_e32 v42, v43, v42
	v_mov_b32_e32 v43, v42
	s_nop 1
	v_permlane16_swap_b32 v42, v43
	s_waitcnt lgkmcnt(0)
	v_add_f32_e32 v42, v42, v43
	v_mov_b32_e32 v43, v42
	s_nop 1
	v_permlane32_swap_b32 v42, v43
	s_and_saveexec_b64 s[30:31], s[38:39]
	s_cbranch_execz .LBB0_1540
	s_waitcnt lgkmcnt(0)
	v_add_f32_e32 v42, v42, v43
	v_mul_f32_e32 v42, 0x49800000, v42
	v_mul_f32_e32 v43, 0x2f800000, v42
	v_cvt_u32_f32_e32 v43, v43
	v_cvt_f32_u32_e32 v44, v43
	v_fmac_f32_e32 v42, 0xcf800000, v44
	v_cvt_u32_f32_e32 v42, v42
	global_atomic_add_x2 v[58:59], v[42:43], off offset:256
;     template <int QVV> __device__ __forceinline__ void run(f32x4 (&acc)[2][2][4][2], const Unit& u, int wr, int wc, int fr, int fq) const {
;     ...
;         if (hasn) {
;             unsigned long long* sp = ssq + u.pm * BM + rq + wr * 64 + fr;
; #pragma unroll
;             for (int ai = 0; ai < 2; ++ai)
; #pragma unroll
;                 for (int m = 0; m < 4; ++m) { if (ai == 1 && qm) continue; float t = ss[ai][m]; t += __shfl_xor(t, 16); t += __shfl_xor(t, 32);
;                     const float xs = t * SSQ_SCALE; const unsigned xh = (unsigned)(xs * 2.3283064365386963e-10f), xl = (unsigned)__builtin_fmaf(-(float)xh, 4294967296.0f, xs);
;                     if (fq == 0) atomicAdd(sp + ai * HALF + m * 16, ((unsigned long long)xh << 32) | xl); }
.LBB0_1540:
	s_or_b64 exec, exec, s[30:31]
	s_waitcnt lgkmcnt(0)
	v_pk_mul_f32 v[42:43], v[142:143], v[142:143]
	v_pk_mul_f32 v[34:35], v[34:35], v[34:35]
	v_pk_fma_f32 v[42:43], v[102:103], v[102:103], v[42:43]
	v_pk_mul_f32 v[44:45], v[198:199], v[198:199]
	v_pk_fma_f32 v[34:35], v[38:39], v[38:39], v[34:35]
	v_pk_mul_f32 v[38:39], v[40:41], v[40:41]
	v_pk_fma_f32 v[44:45], v[130:131], v[130:131], v[44:45]
	v_pk_fma_f32 v[36:37], v[36:37], v[36:37], v[38:39]
	v_add_f32_e32 v34, v34, v35
	v_add_f32_e32 v35, v42, v43
	v_add_f32_e32 v34, v36, v34
	v_add_f32_e32 v35, v44, v35
	v_add_f32_e32 v34, v37, v34
	v_add_f32_e32 v35, v45, v35
	v_add_f32_e32 v34, v35, v34
	v_mov_b32_e32 v35, v34
	s_nop 1
	v_permlane16_swap_b32 v34, v35
	s_waitcnt lgkmcnt(0)
	v_add_f32_e32 v34, v34, v35
	v_mov_b32_e32 v35, v34
	s_nop 1
	v_permlane32_swap_b32 v34, v35
	s_and_saveexec_b64 s[30:31], s[38:39]
	s_cbranch_execz .LBB0_1542
	s_waitcnt lgkmcnt(0)
	v_add_f32_e32 v34, v34, v35
	v_mul_f32_e32 v34, 0x49800000, v34
	v_mul_f32_e32 v35, 0x2f800000, v34
	v_cvt_u32_f32_e32 v35, v35
	v_cvt_f32_u32_e32 v36, v35
	v_fmac_f32_e32 v34, 0xcf800000, v36
	v_cvt_u32_f32_e32 v34, v34
	global_atomic_add_x2 v[58:59], v[34:35], off offset:384
.LBB0_1542:
	s_or_b64 exec, exec, s[30:31]
	s_waitcnt lgkmcnt(0)
	v_pk_mul_f32 v[34:35], v[132:133], v[132:133]
	v_pk_mul_f32 v[26:27], v[26:27], v[26:27]
	v_pk_fma_f32 v[34:35], v[104:105], v[104:105], v[34:35]
	v_pk_mul_f32 v[36:37], v[202:203], v[202:203]
	v_pk_fma_f32 v[26:27], v[30:31], v[30:31], v[26:27]
	v_pk_mul_f32 v[30:31], v[32:33], v[32:33]
	v_pk_fma_f32 v[36:37], v[144:145], v[144:145], v[36:37]
	v_pk_fma_f32 v[28:29], v[28:29], v[28:29], v[30:31]
	v_add_f32_e32 v26, v26, v27
	v_add_f32_e32 v27, v34, v35
	v_add_f32_e32 v26, v28, v26
	v_add_f32_e32 v27, v36, v27
	v_add_f32_e32 v26, v29, v26
	v_add_f32_e32 v27, v37, v27
	v_add_f32_e32 v26, v27, v26
	v_mov_b32_e32 v27, v26
	s_nop 1
	v_permlane16_swap_b32 v26, v27
	s_waitcnt lgkmcnt(0)
	v_add_f32_e32 v26, v26, v27
	v_mov_b32_e32 v27, v26
	s_nop 1
	v_permlane32_swap_b32 v26, v27
	s_and_saveexec_b64 s[30:31], s[38:39]
	s_cbranch_execz .LBB0_1544
	s_waitcnt lgkmcnt(0)
	v_add_f32_e32 v26, v26, v27
	v_mul_f32_e32 v26, 0x49800000, v26
	v_mul_f32_e32 v27, 0x2f800000, v26
	v_cvt_u32_f32_e32 v27, v27
	v_cvt_f32_u32_e32 v28, v27
	v_fmac_f32_e32 v26, 0xcf800000, v28
	v_cvt_u32_f32_e32 v26, v26
	global_atomic_add_x2 v[58:59], v[26:27], off offset:1024
.LBB0_1544:
	s_or_b64 exec, exec, s[30:31]
	s_waitcnt lgkmcnt(0)
	v_pk_mul_f32 v[26:27], v[128:129], v[128:129]
	v_pk_mul_f32 v[18:19], v[18:19], v[18:19]
	v_pk_fma_f32 v[26:27], v[126:127], v[126:127], v[26:27]
	v_pk_mul_f32 v[28:29], v[204:205], v[204:205]
	v_pk_fma_f32 v[18:19], v[22:23], v[22:23], v[18:19]
	v_pk_mul_f32 v[22:23], v[24:25], v[24:25]
	v_pk_fma_f32 v[28:29], v[200:201], v[200:201], v[28:29]
	v_pk_fma_f32 v[20:21], v[20:21], v[20:21], v[22:23]
	v_add_f32_e32 v18, v18, v19
	v_add_f32_e32 v19, v26, v27
	v_add_f32_e32 v18, v20, v18
	v_add_f32_e32 v19, v28, v19
	v_add_f32_e32 v18, v21, v18
	v_add_f32_e32 v19, v29, v19
	v_add_f32_e32 v18, v19, v18
	v_mov_b32_e32 v19, v18
	s_nop 1
	v_permlane16_swap_b32 v18, v19
	s_waitcnt lgkmcnt(0)
	v_add_f32_e32 v18, v18, v19
	v_mov_b32_e32 v19, v18
	s_nop 1
	v_permlane32_swap_b32 v18, v19
	s_and_saveexec_b64 s[30:31], s[38:39]
	s_cbranch_execz .LBB0_1546
	s_waitcnt lgkmcnt(0)
	v_add_f32_e32 v18, v18, v19
	v_mul_f32_e32 v18, 0x49800000, v18
	v_mul_f32_e32 v19, 0x2f800000, v18
	v_cvt_u32_f32_e32 v19, v19
	v_cvt_f32_u32_e32 v20, v19
	v_fmac_f32_e32 v18, 0xcf800000, v20
	v_cvt_u32_f32_e32 v18, v18
	global_atomic_add_x2 v[58:59], v[18:19], off offset:1152
.LBB0_1546:
	s_or_b64 exec, exec, s[30:31]
	s_waitcnt lgkmcnt(0)
	v_pk_mul_f32 v[18:19], v[124:125], v[124:125]
	v_pk_mul_f32 v[10:11], v[10:11], v[10:11]
	v_pk_fma_f32 v[18:19], v[122:123], v[122:123], v[18:19]
	v_pk_mul_f32 v[20:21], v[120:121], v[120:121]
	v_pk_fma_f32 v[10:11], v[14:15], v[14:15], v[10:11]
	v_pk_mul_f32 v[14:15], v[16:17], v[16:17]
	v_pk_fma_f32 v[20:21], v[118:119], v[118:119], v[20:21]
	v_pk_fma_f32 v[12:13], v[12:13], v[12:13], v[14:15]
	v_add_f32_e32 v10, v10, v11
	v_add_f32_e32 v11, v18, v19
	v_add_f32_e32 v10, v12, v10
	v_add_f32_e32 v11, v20, v11
	v_add_f32_e32 v10, v13, v10
	v_add_f32_e32 v11, v21, v11
	v_add_f32_e32 v10, v11, v10
	v_mov_b32_e32 v11, v10
	s_nop 1
	v_permlane16_swap_b32 v10, v11
	s_waitcnt lgkmcnt(0)
	v_add_f32_e32 v10, v10, v11
	v_mov_b32_e32 v11, v10
	s_nop 1
	v_permlane32_swap_b32 v10, v11
	s_and_saveexec_b64 s[30:31], s[38:39]
	s_cbranch_execz .LBB0_1548
	s_waitcnt lgkmcnt(0)
	v_add_f32_e32 v10, v10, v11
	v_mul_f32_e32 v10, 0x49800000, v10
	v_mul_f32_e32 v11, 0x2f800000, v10
	v_cvt_u32_f32_e32 v11, v11
	v_cvt_f32_u32_e32 v12, v11
	v_fmac_f32_e32 v10, 0xcf800000, v12
	v_cvt_u32_f32_e32 v10, v10
	global_atomic_add_x2 v[58:59], v[10:11], off offset:1280
.LBB0_1548:
	s_or_b64 exec, exec, s[30:31]
	s_waitcnt lgkmcnt(0)
	v_pk_mul_f32 v[10:11], v[106:107], v[106:107]
	v_pk_mul_f32 v[2:3], v[2:3], v[2:3]
	v_pk_fma_f32 v[10:11], v[110:111], v[110:111], v[10:11]
	v_pk_mul_f32 v[12:13], v[112:113], v[112:113]
	v_pk_fma_f32 v[2:3], v[6:7], v[6:7], v[2:3]
	v_pk_mul_f32 v[6:7], v[8:9], v[8:9]
	v_pk_fma_f32 v[12:13], v[108:109], v[108:109], v[12:13]
	v_pk_fma_f32 v[4:5], v[4:5], v[4:5], v[6:7]
	v_add_f32_e32 v2, v2, v3
	v_add_f32_e32 v3, v10, v11
	v_add_f32_e32 v2, v4, v2
	v_add_f32_e32 v3, v12, v3
	v_add_f32_e32 v2, v5, v2
	v_add_f32_e32 v3, v13, v3
	v_add_f32_e32 v2, v3, v2
	v_mov_b32_e32 v3, v2
	s_nop 1
	v_permlane16_swap_b32 v2, v3
	s_waitcnt lgkmcnt(0)
	v_add_f32_e32 v2, v2, v3
	v_mov_b32_e32 v3, v2
	s_nop 1
	v_permlane32_swap_b32 v2, v3
	s_and_saveexec_b64 s[30:31], s[38:39]
	s_cbranch_execz .LBB0_1550
	s_waitcnt lgkmcnt(0)
	v_add_f32_e32 v2, v2, v3
	v_mul_f32_e32 v2, 0x49800000, v2
	v_mul_f32_e32 v3, 0x2f800000, v2
	v_cvt_u32_f32_e32 v3, v3
	v_cvt_f32_u32_e32 v4, v3
	v_fmac_f32_e32 v2, 0xcf800000, v4
	v_cvt_u32_f32_e32 v2, v2
	global_atomic_add_x2 v[58:59], v[2:3], off offset:1408

;     template <int QVV> __device__ __forceinline__ void run(f32x4 (&acc)[2][2][4][2], const Unit& u, int wr, int wc, int fr, int fq) const {
;         const bool qm = u.seg != 0; const int rq = qm ? 64 * (u.seg - 1) : 0;
;         const bool active = !(qm && wr == 1);
;         const int v = u.pm < 4 ? 4 : ((u.pm - 4) >> 5);
;         char* sb = (char*)(S + ((size_t)u.pm * BM + rq) * DM + u.pn * BM);
;         const char* gp = (const char*)(gate + (size_t)v * (NMOD * DM) + u.pn * BM);
;         const bool hasn = ng != nullptr;
;         const char* pgp = (const char*)(pg + u.pn * BM); const char* psp = (const char*)(psc + (size_t)v * (NMOD * DM) + u.pn * BM);
;         const char* ngp = (const char*)(ng + u.pn * BM); const char* nsp = (const char*)(nsc + (size_t)v * (NMOD * DM) + u.pn * BM);
;         unsigned co = (unsigned)(wc * 32 + 8 * fq);
;         asm volatile("" : "+v"(co));
;         unsigned lo = ((unsigned)((wr * 64 + fr) * DM) + co) * 2u;
;         asm volatile("" : "+v"(lo));
;         if (active) {
;         float ss[2][4];
; #pragma unroll
;         for (int ai = 0; ai < 2; ++ai)
; #pragma unroll
;             for (int m = 0; m < 4; ++m) ss[ai][m] = 0.f;
; #pragma unroll
;         for (int bj = 0; bj < 2; ++bj) {
;             const unsigned cb4 = (co + bj * HALF) * 4u;
;             f32x4 vg0 = *(const f32x4*)(gp + cb4), vg1 = *(const f32x4*)(gp + cb4 + 16), vp0 = *(const f32x4*)(pgp + cb4), vp1 = *(const f32x4*)(pgp + cb4 + 16), vs0 = *(const f32x4*)(psp + cb4), vs1 = *(const f32x4*)(psp + cb4 + 16);
;             f32x4 vn0 = {1.f, 1.f, 1.f, 1.f}, vn1 = vn0, vt0 = {0.f, 0.f, 0.f, 0.f}, vt1 = vt0;
;             if (hasn) { vn0 = *(const f32x4*)(ngp + cb4); vn1 = *(const f32x4*)(ngp + cb4 + 16); vt0 = *(const f32x4*)(nsp + cb4); vt1 = *(const f32x4*)(nsp + cb4 + 16); }
;             asm volatile("" : "+v"(vg0), "+v"(vg1), "+v"(vp0), "+v"(vp1), "+v"(vs0), "+v"(vs1), "+v"(vn0), "+v"(vn1), "+v"(vt0), "+v"(vt1));
;             const f32x4 g0 = vg0 * fac, g1 = vg1 * fac;
;             const f32x4 p0 = vp0 * (vs0 + 1.0f), p1 = vp1 * (vs1 + 1.0f);
;             f32x4 r0, r1;
; #pragma unroll
;             for (int i = 0; i < 4; ++i) { r0[i] = __builtin_amdgcn_rcpf(p0[i]); r1[i] = __builtin_amdgcn_rcpf(p1[i]); }
;             const f32x4 c0 = vn0 * (vt0 + 1.0f), c1 = vn1 * (vt1 + 1.0f);
;             u32x4 hin[2][4];
; #pragma unroll
.LBB0_1569:
	s_waitcnt lgkmcnt(14)
	v_lshl_or_b32 v66, v131, 3, s26
	v_lshlrev_b32_e32 v67, 12, v136
	s_andn2_b64 vcc, exec, s[30:31]
	v_lshl_add_u32 v174, v66, 1, v67
	s_movk_i32 s22, 0x25ff
	s_mov_b32 s26, 0xffff
	s_mov_b32 s27, 0xac00
	s_mov_b32 s28, 0x70000
	s_cbranch_vccnz .LBB0_1579
	v_readlane_b32 s15, v253, 22
	s_ashr_i32 s35, s34, 31
	s_lshl_b32 s14, s15, 2
	s_add_u32 s10, s10, s14
	s_addc_u32 s11, s11, 0
	s_add_u32 s38, s10, 0x56000
	s_addc_u32 s39, s11, 0
	s_add_u32 s40, s12, s14
	s_addc_u32 s41, s13, 0
	s_add_u32 s42, s10, 0x50000
	s_addc_u32 s43, s11, 0
	s_add_u32 s44, s8, s14
	s_addc_u32 s45, s9, 0
	s_add_u32 s46, s10, 0x52000
	v_lshlrev_b32_e32 v134, 2, v66
	s_addc_u32 s47, s11, 0
	global_load_dwordx4 v[66:69], v134, s[44:45] offset:16
	s_waitcnt lgkmcnt(13)
	global_load_dwordx4 v[74:77], v134, s[44:45]
	s_waitcnt lgkmcnt(6)
	global_load_dwordx4 v[100:103], v134, s[42:43] offset:16
	s_waitcnt lgkmcnt(5)
	global_load_dwordx4 v[104:107], v134, s[42:43]
	global_load_dwordx4 v[70:73], v134, s[40:41] offset:16
	global_load_dwordx4 v[78:81], v134, s[40:41]
	s_waitcnt lgkmcnt(4)
	global_load_dwordx4 v[108:111], v134, s[38:39] offset:16
	s_waitcnt lgkmcnt(3)
	global_load_dwordx4 v[112:115], v134, s[38:39]
	global_load_dwordx4 v[82:85], v134, s[46:47] offset:16
	global_load_dwordx4 v[90:93], v134, s[46:47]
	v_readlane_b32 s8, v253, 24
	v_readlane_b32 s9, v253, 25
	s_add_u32 s5, s5, s8
	s_addc_u32 s7, s7, s9
	v_readlane_b32 s8, v253, 46
	s_add_u32 s5, s5, s8
	s_addc_u32 s7, s7, 0
	s_lshl_b32 s8, s15, 1
	s_add_u32 s30, s5, s8
	s_addc_u32 s31, s7, 0
	v_lshl_add_u64 v[86:87], s[30:31], 0, v[174:175]
	s_mov_b32 s5, 0x10000
	v_add_co_u32_e32 v96, vcc, s5, v86
	s_mov_b32 s5, 0x30000
	s_nop 0
	v_addc_co_u32_e32 v97, vcc, 0, v87, vcc
	v_add_co_u32_e32 v98, vcc, s79, v86
	v_add_u32_e32 v135, 0x10000, v174
	s_nop 0
	v_addc_co_u32_e32 v99, vcc, 0, v87, vcc
	v_add_co_u32_e32 v94, vcc, s5, v86
	v_add_u32_e32 v136, 0x20000, v174
	s_nop 0
	v_addc_co_u32_e32 v95, vcc, 0, v87, vcc
	v_cmp_eq_u32_e32 vcc, 0, v131
	v_readlane_b32 s8, v253, 13
	v_readlane_b32 s9, v253, 14
	s_lshl_b64 s[8:9], s[8:9], 3
	s_add_u32 s2, s2, s8
	v_readlane_b32 s5, v253, 45
	s_addc_u32 s3, s3, s9
	s_lshl_b32 s5, s5, 3
	s_add_u32 s5, s2, s5
	s_addc_u32 s7, s3, 0
	s_lshl_b64 s[2:3], s[34:35], 3
	s_add_u32 s2, s5, s2
	s_addc_u32 s3, s7, s3
	s_waitcnt vmcnt(0)
	s_waitcnt lgkmcnt(2)
	global_load_dwordx4 v[116:119], v174, s[30:31]
	global_load_dwordx4 v[86:89], v[94:95], off
	s_waitcnt lgkmcnt(1)
	global_load_dwordx4 v[120:123], v[96:97], off
	s_waitcnt lgkmcnt(0)
	global_load_dwordx4 v[124:127], v[98:99], off
	v_add_f32_e32 v128, 1.0, v104
	v_add_f32_e32 v129, 1.0, v100
	v_add_f32_e32 v132, 1.0, v105
	v_add_f32_e32 v133, 1.0, v101
	v_add_f32_e32 v137, 1.0, v106
	v_add_f32_e32 v138, 1.0, v102
	v_add_f32_e32 v139, 1.0, v107
	v_add_f32_e32 v140, 1.0, v103
	v_pk_mul_f32 v[60:61], v[60:61], v[84:85]
	v_pk_mul_f32 v[58:59], v[58:59], v[82:83]
	v_pk_add_f32 v[102:103], v[108:109], 1.0 op_sel_hi:[1,0]
	v_pk_add_f32 v[106:107], v[110:111], 1.0 op_sel_hi:[1,0]
	v_pk_mul_f32 v[52:53], v[52:53], v[84:85]
	v_pk_mul_f32 v[50:51], v[50:51], v[82:83]
	v_pk_mul_f32 v[44:45], v[44:45], v[84:85]
	v_pk_mul_f32 v[42:43], v[42:43], v[82:83]
	v_pk_mul_f32 v[36:37], v[36:37], v[84:85]
	v_pk_mul_f32 v[34:35], v[34:35], v[82:83]
	v_mul_f32_e32 v74, v74, v128
	v_mul_f32_e32 v82, v66, v129
	v_mul_f32_e32 v75, v75, v132
	v_mul_f32_e32 v83, v67, v133
	v_mul_f32_e32 v76, v76, v137
	v_mul_f32_e32 v84, v68, v138
	v_mul_f32_e32 v77, v77, v139
	v_mul_f32_e32 v85, v69, v140
	v_pk_add_f32 v[100:101], v[112:113], 1.0 op_sel_hi:[1,0]
	v_pk_mul_f32 v[68:69], v[70:71], v[102:103]
	v_pk_mul_f32 v[110:111], v[72:73], v[106:107]
	v_rcp_f32_e32 v70, v74
	v_rcp_f32_e32 v72, v82
	v_rcp_f32_e32 v71, v75
	v_rcp_f32_e32 v73, v83
	v_rcp_f32_e32 v76, v76
	v_rcp_f32_e32 v112, v84
	v_rcp_f32_e32 v77, v77
	v_rcp_f32_e32 v113, v85
	v_pk_add_f32 v[104:105], v[114:115], 1.0 op_sel_hi:[1,0]
	v_pk_mul_f32 v[64:65], v[64:65], v[92:93]
	v_pk_mul_f32 v[62:63], v[62:63], v[90:91]
	v_pk_mul_f32 v[56:57], v[56:57], v[92:93]
	v_pk_mul_f32 v[54:55], v[54:55], v[90:91]
	v_pk_mul_f32 v[48:49], v[48:49], v[92:93]
	v_pk_mul_f32 v[40:41], v[40:41], v[92:93]
	v_pk_mul_f32 v[66:67], v[78:79], v[100:101]
	v_pk_mul_f32 v[108:109], v[80:81], v[104:105]
	v_pk_mul_f32 v[46:47], v[46:47], v[90:91]
	v_pk_mul_f32 v[38:39], v[38:39], v[90:91]
	s_waitcnt vmcnt(3)
	v_lshlrev_b32_e32 v74, 16, v116
	v_and_b32_e32 v75, 0xffff0000, v116
	v_lshlrev_b32_e32 v78, 16, v118
	v_and_b32_e32 v79, 0xffff0000, v118
	v_lshlrev_b32_e32 v80, 16, v117
	v_and_b32_e32 v81, 0xffff0000, v117
	v_lshlrev_b32_e32 v82, 16, v119
	v_and_b32_e32 v83, 0xffff0000, v119
	s_waitcnt vmcnt(1)
	v_lshlrev_b32_e32 v84, 16, v120
	v_and_b32_e32 v85, 0xffff0000, v120
	v_lshlrev_b32_e32 v92, 16, v121
	v_and_b32_e32 v93, 0xffff0000, v121
	v_lshlrev_b32_e32 v90, 16, v122
	v_and_b32_e32 v91, 0xffff0000, v122
	v_lshlrev_b32_e32 v114, 16, v123
	v_and_b32_e32 v115, 0xffff0000, v123
	s_waitcnt vmcnt(0)
;     template <int QVV> __device__ __forceinline__ void run(f32x4 (&acc)[2][2][4][2], const Unit& u, int wr, int wc, int fr, int fq) const {
;     ...
;         for (int bj = 0; bj < 2; ++bj) {
;             const unsigned cb4 = (co + bj * HALF) * 4u;
;             f32x4 vg0 = *(const f32x4*)(gp + cb4), vg1 = *(const f32x4*)(gp + cb4 + 16), vp0 = *(const f32x4*)(pgp + cb4), vp1 = *(const f32x4*)(pgp + cb4 + 16), vs0 = *(const f32x4*)(psp + cb4), vs1 = *(const f32x4*)(psp + cb4 + 16);
;             f32x4 vn0 = {1.f, 1.f, 1.f, 1.f}, vn1 = vn0, vt0 = {0.f, 0.f, 0.f, 0.f}, vt1 = vt0;
;             if (hasn) { vn0 = *(const f32x4*)(ngp + cb4); vn1 = *(const f32x4*)(ngp + cb4 + 16); vt0 = *(const f32x4*)(nsp + cb4); vt1 = *(const f32x4*)(nsp + cb4 + 16); }
;             asm volatile("" : "+v"(vg0), "+v"(vg1), "+v"(vp0), "+v"(vp1), "+v"(vs0), "+v"(vs1), "+v"(vn0), "+v"(vn1), "+v"(vt0), "+v"(vt1));
;             const f32x4 g0 = vg0 * fac, g1 = vg1 * fac;
;             const f32x4 p0 = vp0 * (vs0 + 1.0f), p1 = vp1 * (vs1 + 1.0f);
;             f32x4 r0, r1;
; #pragma unroll
;             for (int i = 0; i < 4; ++i) { r0[i] = __builtin_amdgcn_rcpf(p0[i]); r1[i] = __builtin_amdgcn_rcpf(p1[i]); }
;             const f32x4 c0 = vn0 * (vt0 + 1.0f), c1 = vn1 * (vt1 + 1.0f);
;             u32x4 hin[2][4];
; #pragma unroll
;             for (int ai = 0; ai < 2; ++ai)
; #pragma unroll
;                 for (int m = 0; m < 4; ++m) { if (ai == 1 && qm) continue; hin[ai][m] = *(const u32x4*)(sb + lo + (unsigned)((ai * HALF + m * 16) * DM + bj * HALF) * 2u); }
; #pragma unroll
;             for (int ai = 0; ai < 2; ++ai)
; #pragma unroll
;                 for (int m = 0; m < 4; ++m) { if (ai == 1 && qm) continue;
;                     const unsigned off = lo + (unsigned)((ai * HALF + m * 16) * DM + bj * HALF) * 2u;
;                     float hv[8]; unpack8(hin[ai][m], hv);
;                     float y[8]; float t = 0.f;
; #pragma unroll
;                     for (int i = 0; i < 4; ++i) { const float a0 = hv[i] * r0[i] + g0[i] * acc[ai][bj][m][0][i], a1 = hv[4 + i] * r1[i] + g1[i] * acc[ai][bj][m][1][i];
;                         t += a0 * a0 + a1 * a1; y[i] = a0 * c0[i]; y[4 + i] = a1 * c1[i]; }
;                     ss[ai][m] += t;
;                     *(u32x4*)(sb + off) = pack8(y); }
	v_lshlrev_b32_e32 v116, 16, v124
	v_and_b32_e32 v117, 0xffff0000, v124
	v_lshlrev_b32_e32 v118, 16, v126
	v_and_b32_e32 v119, 0xffff0000, v126
	v_lshlrev_b32_e32 v120, 16, v125
	v_and_b32_e32 v121, 0xffff0000, v125
	v_lshlrev_b32_e32 v122, 16, v127
	v_and_b32_e32 v123, 0xffff0000, v127
	v_lshlrev_b32_e32 v124, 16, v86
	v_and_b32_e32 v125, 0xffff0000, v86
	v_lshlrev_b32_e32 v126, 16, v88
	v_and_b32_e32 v127, 0xffff0000, v88
	v_lshlrev_b32_e32 v128, 16, v87
	v_and_b32_e32 v129, 0xffff0000, v87
	v_lshlrev_b32_e32 v132, 16, v89
	v_and_b32_e32 v133, 0xffff0000, v89
	v_pk_fma_f32 v[100:101], v[70:71], v[74:75], v[62:63]
	v_pk_fma_f32 v[104:105], v[72:73], v[78:79], v[58:59]
	v_pk_fma_f32 v[102:103], v[76:77], v[80:81], v[64:65]
	v_pk_fma_f32 v[106:107], v[112:113], v[82:83], v[60:61]
	v_pk_fma_f32 v[86:87], v[70:71], v[84:85], v[54:55]
	v_pk_fma_f32 v[88:89], v[76:77], v[92:93], v[56:57]
	v_pk_fma_f32 v[90:91], v[72:73], v[90:91], v[50:51]
	v_pk_fma_f32 v[92:93], v[112:113], v[114:115], v[52:53]
	v_pk_fma_f32 v[78:79], v[70:71], v[116:117], v[46:47]
	v_pk_fma_f32 v[82:83], v[72:73], v[118:119], v[42:43]
	v_pk_fma_f32 v[80:81], v[76:77], v[120:121], v[48:49]
	v_pk_fma_f32 v[84:85], v[112:113], v[122:123], v[44:45]
	v_pk_fma_f32 v[70:71], v[70:71], v[124:125], v[38:39]
	v_pk_fma_f32 v[74:75], v[72:73], v[126:127], v[34:35]
	v_pk_fma_f32 v[72:73], v[76:77], v[128:129], v[40:41]
	v_pk_fma_f32 v[76:77], v[112:113], v[132:133], v[36:37]
	v_pk_mul_f32 v[34:35], v[66:67], v[100:101]
	v_pk_mul_f32 v[36:37], v[68:69], v[104:105]
	v_pk_mul_f32 v[38:39], v[108:109], v[102:103]
	v_pk_mul_f32 v[40:41], v[110:111], v[106:107]
	v_pk_mul_f32 v[42:43], v[66:67], v[86:87]
	v_pk_mul_f32 v[46:47], v[108:109], v[88:89]
	v_pk_mul_f32 v[44:45], v[68:69], v[90:91]
	v_pk_mul_f32 v[48:49], v[110:111], v[92:93]
	v_pk_mul_f32 v[50:51], v[66:67], v[78:79]
	v_pk_mul_f32 v[52:53], v[68:69], v[82:83]
	v_pk_mul_f32 v[54:55], v[108:109], v[80:81]
	v_pk_mul_f32 v[56:57], v[110:111], v[84:85]
	v_cvt_pk_bf16_f32 v34, v34, v35
	v_cvt_pk_bf16_f32 v35, v38, v39
	v_cvt_pk_bf16_f32 v36, v36, v37
	v_cvt_pk_bf16_f32 v37, v40, v41
	v_cvt_pk_bf16_f32 v38, v42, v43
	v_cvt_pk_bf16_f32 v39, v46, v47
	v_pk_mul_f32 v[58:59], v[66:67], v[70:71]
	v_pk_mul_f32 v[60:61], v[68:69], v[74:75]
	v_pk_mul_f32 v[62:63], v[108:109], v[72:73]
	v_cvt_pk_bf16_f32 v40, v44, v45
	v_cvt_pk_bf16_f32 v41, v48, v49
	v_cvt_pk_bf16_f32 v42, v50, v51
	v_cvt_pk_bf16_f32 v43, v54, v55
	v_cvt_pk_bf16_f32 v44, v52, v53
	v_cvt_pk_bf16_f32 v45, v56, v57
	global_store_dwordx4 v174, v[34:37], s[30:31]
	global_store_dwordx4 v135, v[38:41], s[30:31]
	global_store_dwordx4 v136, v[42:45], s[30:31]
	v_cvt_pk_bf16_f32 v34, v58, v59
	v_pk_mul_f32 v[38:39], v[110:111], v[76:77]
	v_add_u32_e32 v40, 0x30000, v174
	v_cvt_pk_bf16_f32 v35, v62, v63
	v_cvt_pk_bf16_f32 v36, v60, v61
	v_cvt_pk_bf16_f32 v37, v38, v39
	global_store_dwordx4 v40, v[34:37], s[30:31]
	v_add_u32_e32 v58, 0x200, v134
	global_load_dwordx4 v[50:53], v58, s[46:47] offset:16
	global_load_dwordx4 v[54:57], v58, s[46:47]
	global_load_dwordx4 v[34:37], v58, s[44:45] offset:16
	global_load_dwordx4 v[42:45], v58, s[44:45]
	global_load_dwordx4 v[108:111], v58, s[42:43] offset:16
	global_load_dwordx4 v[112:115], v58, s[42:43]
	global_load_dwordx4 v[38:41], v58, s[40:41] offset:16
	global_load_dwordx4 v[46:49], v58, s[40:41]
	global_load_dwordx4 v[116:119], v58, s[38:39] offset:16
	global_load_dwordx4 v[120:123], v58, s[38:39]
	s_waitcnt vmcnt(0)
	global_load_dwordx4 v[66:69], v174, s[30:31] offset:256
	global_load_dwordx4 v[62:65], v[96:97], off offset:256
	global_load_dwordx4 v[58:61], v[98:99], off offset:256
	v_pk_mul_f32 v[98:99], v[104:105], v[104:105]
	global_load_dwordx4 v[94:97], v[94:95], off offset:256
	v_pk_mul_f32 v[104:105], v[106:107], v[106:107]
	v_add_f32_e32 v128, 1.0, v112
	v_add_f32_e32 v129, 1.0, v108
	v_add_f32_e32 v131, 1.0, v113
	v_add_f32_e32 v132, 1.0, v109
	v_add_f32_e32 v114, 1.0, v114
	v_add_f32_e32 v133, 1.0, v110
	v_add_f32_e32 v115, 1.0, v115
	v_add_f32_e32 v134, 1.0, v111
	v_pk_fma_f32 v[98:99], v[100:101], v[100:101], v[98:99]
	v_pk_fma_f32 v[100:101], v[102:103], v[102:103], v[104:105]
	v_pk_add_f32 v[102:103], v[120:121], 1.0 op_sel_hi:[1,0]
	v_pk_mul_f32 v[28:29], v[28:29], v[52:53]
	v_pk_mul_f32 v[26:27], v[26:27], v[50:51]
	v_pk_mul_f32 v[110:111], v[20:21], v[52:53]
	v_pk_mul_f32 v[20:21], v[18:19], v[50:51]
	v_pk_mul_f32 v[112:113], v[12:13], v[52:53]
	v_pk_mul_f32 v[12:13], v[10:11], v[50:51]
	v_pk_mul_f32 v[52:53], v[4:5], v[52:53]
	v_pk_mul_f32 v[4:5], v[2:3], v[50:51]
	v_mul_f32_e32 v2, v42, v128
	v_mul_f32_e32 v3, v34, v129
	v_mul_f32_e32 v10, v43, v131
	v_mul_f32_e32 v11, v35, v132
	v_mul_f32_e32 v18, v44, v114
	v_mul_f32_e32 v19, v36, v133
	v_mul_f32_e32 v45, v45, v115
	v_mul_f32_e32 v50, v37, v134
	v_pk_mul_f32 v[34:35], v[46:47], v[102:103]
	v_rcp_f32_e32 v2, v2
	v_rcp_f32_e32 v42, v3
	v_rcp_f32_e32 v3, v10
	v_rcp_f32_e32 v43, v11
	v_rcp_f32_e32 v44, v18
	v_rcp_f32_e32 v46, v19
	v_rcp_f32_e32 v45, v45
	v_rcp_f32_e32 v47, v50
	v_pk_add_f32 v[104:105], v[116:117], 1.0 op_sel_hi:[1,0]
	v_pk_add_f32 v[106:107], v[122:123], 1.0 op_sel_hi:[1,0]
	v_pk_mul_f32 v[32:33], v[32:33], v[56:57]
	v_pk_mul_f32 v[30:31], v[30:31], v[54:55]
	v_pk_add_f32 v[108:109], v[118:119], 1.0 op_sel_hi:[1,0]
	v_pk_mul_f32 v[36:37], v[38:39], v[104:105]
	v_pk_mul_f32 v[38:39], v[48:49], v[106:107]
	v_pk_mul_f32 v[24:25], v[24:25], v[56:57]
	v_pk_mul_f32 v[22:23], v[22:23], v[54:55]
	v_pk_mul_f32 v[16:17], v[16:17], v[56:57]
	v_pk_mul_f32 v[14:15], v[14:15], v[54:55]
	v_pk_mul_f32 v[8:9], v[8:9], v[56:57]
	v_pk_mul_f32 v[6:7], v[6:7], v[54:55]
	v_pk_mul_f32 v[40:41], v[40:41], v[108:109]
	v_add_u32_e32 v124, 0x100, v174
	v_add_u32_e32 v125, 0x10100, v174
	v_add_u32_e32 v126, 0x20100, v174
	v_add_u32_e32 v127, 0x30100, v174
	v_lshlrev_b32_e32 v174, 3, v130
	s_waitcnt vmcnt(3)
; __device__ __forceinline__ void unpack8(const u32x4 w, float (&f)[8]) { f[0] = bflo(w.x); f[1] = bfhi(w.x); f[2] = bflo(w.y); f[3] = bfhi(w.y); f[4] = bflo(w.z); f[5] = bfhi(w.z); f[6] = bflo(w.w); f[7] = bfhi(w.w); }
; __device__ __forceinline__ u32x4 pack8(const float (&f)[8]) { u32x4 w; w.x = pk2(f[0], f[1]); w.y = pk2(f[2], f[3]); w.z = pk2(f[4], f[5]); w.w = pk2(f[6], f[7]); return w; }
;     template <int QVV> __device__ __forceinline__ void run(f32x4 (&acc)[2][2][4][2], const Unit& u, int wr, int wc, int fr, int fq) const {
;     ...
;             for (int ai = 0; ai < 2; ++ai)
; #pragma unroll
;                 for (int m = 0; m < 4; ++m) { if (ai == 1 && qm) continue;
;                     const unsigned off = lo + (unsigned)((ai * HALF + m * 16) * DM + bj * HALF) * 2u;
;                     float hv[8]; unpack8(hin[ai][m], hv);
;                     float y[8]; float t = 0.f;
; #pragma unroll
;                     for (int i = 0; i < 4; ++i) { const float a0 = hv[i] * r0[i] + g0[i] * acc[ai][bj][m][0][i], a1 = hv[4 + i] * r1[i] + g1[i] * acc[ai][bj][m][1][i];
;                         t += a0 * a0 + a1 * a1; y[i] = a0 * c0[i]; y[4 + i] = a1 * c1[i]; }
;                     ss[ai][m] += t;
;                     *(u32x4*)(sb + off) = pack8(y); }
;             asm volatile("" ::: "memory");
;         }
;         if (hasn) {
;             unsigned long long* sp = ssq + u.pm * BM + rq + wr * 64 + fr;
; #pragma unroll
;             for (int ai = 0; ai < 2; ++ai)
; #pragma unroll
;                 for (int m = 0; m < 4; ++m) { if (ai == 1 && qm) continue; float t = ss[ai][m]; t += __shfl_xor(t, 16); t += __shfl_xor(t, 32);
;                     const float xs = t * SSQ_SCALE; const unsigned xh = (unsigned)(xs * 2.3283064365386963e-10f), xl = (unsigned)__builtin_fmaf(-(float)xh, 4294967296.0f, xs);
;                     if (fq == 0) atomicAdd(sp + ai * HALF + m * 16, ((unsigned long long)xh << 32) | xl); }
	v_lshlrev_b32_e32 v10, 16, v66
	v_and_b32_e32 v11, 0xffff0000, v66
	v_lshlrev_b32_e32 v18, 16, v68
	v_and_b32_e32 v19, 0xffff0000, v68
	v_lshlrev_b32_e32 v48, 16, v67
	v_and_b32_e32 v49, 0xffff0000, v67
	v_lshlrev_b32_e32 v50, 16, v69
	v_and_b32_e32 v51, 0xffff0000, v69
	s_waitcnt vmcnt(2)
	v_lshlrev_b32_e32 v54, 16, v62
	v_and_b32_e32 v55, 0xffff0000, v62
	v_lshlrev_b32_e32 v56, 16, v64
	v_and_b32_e32 v57, 0xffff0000, v64
	v_lshlrev_b32_e32 v62, 16, v63
	v_and_b32_e32 v63, 0xffff0000, v63
	v_lshlrev_b32_e32 v64, 16, v65
	v_and_b32_e32 v65, 0xffff0000, v65
	s_waitcnt vmcnt(1)
	v_lshlrev_b32_e32 v66, 16, v58
	v_and_b32_e32 v67, 0xffff0000, v58
	v_lshlrev_b32_e32 v68, 16, v60
	v_and_b32_e32 v69, 0xffff0000, v60
	v_lshlrev_b32_e32 v58, 16, v59
	v_and_b32_e32 v59, 0xffff0000, v59
	v_lshlrev_b32_e32 v60, 16, v61
	v_and_b32_e32 v61, 0xffff0000, v61
	s_waitcnt vmcnt(0)
	v_lshlrev_b32_e32 v102, 16, v94
	v_and_b32_e32 v103, 0xffff0000, v94
	v_lshlrev_b32_e32 v104, 16, v96
	v_and_b32_e32 v105, 0xffff0000, v96
	v_lshlrev_b32_e32 v94, 16, v95
	v_and_b32_e32 v95, 0xffff0000, v95
	v_lshlrev_b32_e32 v96, 16, v97
	v_and_b32_e32 v97, 0xffff0000, v97
	v_pk_fma_f32 v[106:107], v[2:3], v[10:11], v[30:31]
	v_pk_fma_f32 v[108:109], v[42:43], v[18:19], v[26:27]
	v_pk_fma_f32 v[48:49], v[44:45], v[48:49], v[32:33]
	v_pk_fma_f32 v[26:27], v[46:47], v[50:51], v[28:29]
	v_pk_fma_f32 v[18:19], v[2:3], v[54:55], v[22:23]
	v_pk_fma_f32 v[22:23], v[42:43], v[56:57], v[20:21]
	v_pk_fma_f32 v[20:21], v[44:45], v[62:63], v[24:25]
	v_pk_fma_f32 v[24:25], v[46:47], v[64:65], v[110:111]
	v_pk_fma_f32 v[10:11], v[2:3], v[66:67], v[14:15]
	v_pk_fma_f32 v[14:15], v[42:43], v[68:69], v[12:13]
	v_pk_fma_f32 v[12:13], v[44:45], v[58:59], v[16:17]
	v_pk_fma_f32 v[16:17], v[46:47], v[60:61], v[112:113]
	v_pk_fma_f32 v[2:3], v[2:3], v[102:103], v[6:7]
	v_pk_fma_f32 v[6:7], v[42:43], v[104:105], v[4:5]
	v_pk_fma_f32 v[4:5], v[44:45], v[94:95], v[8:9]
	v_pk_fma_f32 v[8:9], v[46:47], v[96:97], v[52:53]
	v_pk_mul_f32 v[28:29], v[34:35], v[106:107]
	v_pk_mul_f32 v[30:31], v[36:37], v[108:109]
	v_pk_mul_f32 v[32:33], v[38:39], v[48:49]
	v_pk_mul_f32 v[42:43], v[40:41], v[26:27]
	v_pk_mul_f32 v[44:45], v[34:35], v[18:19]
	v_pk_mul_f32 v[46:47], v[36:37], v[22:23]
	v_pk_mul_f32 v[50:51], v[38:39], v[20:21]
	v_pk_mul_f32 v[52:53], v[40:41], v[24:25]
	v_pk_mul_f32 v[54:55], v[34:35], v[10:11]
	v_pk_mul_f32 v[56:57], v[36:37], v[14:15]
	v_pk_mul_f32 v[58:59], v[38:39], v[12:13]
	v_pk_mul_f32 v[60:61], v[40:41], v[16:17]
	v_pk_mul_f32 v[62:63], v[34:35], v[2:3]
	v_pk_mul_f32 v[64:65], v[36:37], v[6:7]
	v_pk_mul_f32 v[66:67], v[38:39], v[4:5]
	v_pk_mul_f32 v[68:69], v[40:41], v[8:9]
	v_pk_mul_f32 v[94:95], v[26:27], v[26:27]
	v_cvt_pk_bf16_f32 v26, v28, v29
	v_cvt_pk_bf16_f32 v27, v32, v33
	v_cvt_pk_bf16_f32 v28, v30, v31
	v_cvt_pk_bf16_f32 v29, v42, v43
	v_cvt_pk_bf16_f32 v30, v44, v45
	v_cvt_pk_bf16_f32 v31, v50, v51
	v_cvt_pk_bf16_f32 v32, v46, v47
	v_cvt_pk_bf16_f32 v33, v52, v53
	v_cvt_pk_bf16_f32 v34, v54, v55
	v_cvt_pk_bf16_f32 v35, v58, v59
	v_cvt_pk_bf16_f32 v36, v56, v57
	v_cvt_pk_bf16_f32 v37, v60, v61
	v_cvt_pk_bf16_f32 v38, v62, v63
	v_cvt_pk_bf16_f32 v39, v66, v67
	v_cvt_pk_bf16_f32 v40, v64, v65
	v_cvt_pk_bf16_f32 v41, v68, v69
	global_store_dwordx4 v124, v[26:29], s[30:31]
	global_store_dwordx4 v125, v[30:33], s[30:31]
	global_store_dwordx4 v126, v[34:37], s[30:31]
	global_store_dwordx4 v127, v[38:41], s[30:31]
	v_pk_mul_f32 v[28:29], v[108:109], v[108:109]
	v_pk_fma_f32 v[26:27], v[48:49], v[48:49], v[94:95]
	v_pk_fma_f32 v[28:29], v[106:107], v[106:107], v[28:29]
	v_add_f32_e32 v30, v98, v99
	v_add_f32_e32 v28, v28, v29
	v_add_f32_e32 v26, v26, v28
	v_add_f32_e32 v26, v27, v26
	v_xor_b32_e32 v27, 16, v230
	v_add_f32_e32 v30, v100, v30
	v_cmp_lt_i32_e64 s[38:39], v27, v232
	v_add_f32_e32 v30, v101, v30
	v_add_f32_e32 v26, v30, v26
	v_cndmask_b32_e64 v27, v230, v27, s[38:39]
	v_lshlrev_b32_e32 v28, 2, v27
	v_mov_b32_e32 v27, v26
	s_nop 1
	v_permlane16_swap_b32 v26, v27
	s_waitcnt lgkmcnt(0)
	v_add_f32_e32 v30, v26, v27
	v_xor_b32_e32 v26, 32, v230
	v_cmp_lt_i32_e64 s[38:39], v26, v232
	s_nop 1
	v_cndmask_b32_e64 v26, v230, v26, s[38:39]
	v_lshlrev_b32_e32 v29, 2, v26
	v_mov_b32_e32 v31, v30
	s_nop 1
	v_permlane32_swap_b32 v30, v31
	v_lshl_add_u64 v[26:27], s[2:3], 0, v[174:175]
	s_and_saveexec_b64 s[30:31], vcc
	s_cbranch_execz .LBB0_1572
	s_waitcnt lgkmcnt(0)
	v_add_f32_e32 v30, v30, v31
	v_mul_f32_e32 v30, 0x49800000, v30
	v_mul_f32_e32 v31, 0x2f800000, v30
	v_cvt_u32_f32_e32 v31, v31
	v_cvt_f32_u32_e32 v32, v31
	v_fmac_f32_e32 v30, 0xcf800000, v32
	v_cvt_u32_f32_e32 v30, v30
	global_atomic_add_x2 v[26:27], v[30:31], off
;     template <int QVV> __device__ __forceinline__ void run(f32x4 (&acc)[2][2][4][2], const Unit& u, int wr, int wc, int fr, int fq) const {
;     ...
;         if (hasn) {
;             unsigned long long* sp = ssq + u.pm * BM + rq + wr * 64 + fr;
; #pragma unroll
;             for (int ai = 0; ai < 2; ++ai)
; #pragma unroll
;                 for (int m = 0; m < 4; ++m) { if (ai == 1 && qm) continue; float t = ss[ai][m]; t += __shfl_xor(t, 16); t += __shfl_xor(t, 32);
;                     const float xs = t * SSQ_SCALE; const unsigned xh = (unsigned)(xs * 2.3283064365386963e-10f), xl = (unsigned)__builtin_fmaf(-(float)xh, 4294967296.0f, xs);
;                     if (fq == 0) atomicAdd(sp + ai * HALF + m * 16, ((unsigned long long)xh << 32) | xl); }
.LBB0_1572:
	s_or_b64 exec, exec, s[30:31]
	s_waitcnt lgkmcnt(0)
	v_pk_mul_f32 v[30:31], v[90:91], v[90:91]
	v_pk_mul_f32 v[22:23], v[22:23], v[22:23]
	v_pk_fma_f32 v[30:31], v[86:87], v[86:87], v[30:31]
	v_pk_mul_f32 v[32:33], v[92:93], v[92:93]
	v_pk_fma_f32 v[18:19], v[18:19], v[18:19], v[22:23]
	v_pk_mul_f32 v[22:23], v[24:25], v[24:25]
	v_pk_fma_f32 v[32:33], v[88:89], v[88:89], v[32:33]
	v_pk_fma_f32 v[20:21], v[20:21], v[20:21], v[22:23]
	v_add_f32_e32 v18, v18, v19
	v_add_f32_e32 v19, v30, v31
	v_add_f32_e32 v18, v20, v18
	v_add_f32_e32 v19, v32, v19
	v_add_f32_e32 v18, v21, v18
	v_add_f32_e32 v19, v33, v19
	v_add_f32_e32 v18, v19, v18
	v_mov_b32_e32 v19, v18
	s_nop 1
	v_permlane16_swap_b32 v18, v19
	s_waitcnt lgkmcnt(0)
	v_add_f32_e32 v18, v18, v19
	v_mov_b32_e32 v19, v18
	s_nop 1
	v_permlane32_swap_b32 v18, v19
	s_and_saveexec_b64 s[30:31], vcc
	s_cbranch_execz .LBB0_1574
	s_waitcnt lgkmcnt(0)
	v_add_f32_e32 v18, v18, v19
	v_mul_f32_e32 v18, 0x49800000, v18
	v_mul_f32_e32 v19, 0x2f800000, v18
	v_cvt_u32_f32_e32 v19, v19
	v_cvt_f32_u32_e32 v20, v19
	v_fmac_f32_e32 v18, 0xcf800000, v20
	v_cvt_u32_f32_e32 v18, v18
	global_atomic_add_x2 v[26:27], v[18:19], off offset:128
.LBB0_1574:
	s_or_b64 exec, exec, s[30:31]
	s_waitcnt lgkmcnt(0)
	v_pk_mul_f32 v[18:19], v[82:83], v[82:83]
	v_pk_mul_f32 v[14:15], v[14:15], v[14:15]
	v_pk_fma_f32 v[18:19], v[78:79], v[78:79], v[18:19]
	v_pk_mul_f32 v[20:21], v[84:85], v[84:85]
	v_pk_fma_f32 v[10:11], v[10:11], v[10:11], v[14:15]
	v_pk_mul_f32 v[14:15], v[16:17], v[16:17]
	v_pk_fma_f32 v[20:21], v[80:81], v[80:81], v[20:21]
	v_pk_fma_f32 v[12:13], v[12:13], v[12:13], v[14:15]
	v_add_f32_e32 v10, v10, v11
	v_add_f32_e32 v11, v18, v19
	v_add_f32_e32 v10, v12, v10
	v_add_f32_e32 v11, v20, v11
	v_add_f32_e32 v10, v13, v10
	v_add_f32_e32 v11, v21, v11
	v_add_f32_e32 v10, v11, v10
	v_mov_b32_e32 v11, v10
	s_nop 1
	v_permlane16_swap_b32 v10, v11
	s_waitcnt lgkmcnt(0)
	v_add_f32_e32 v10, v10, v11
	v_mov_b32_e32 v11, v10
	s_nop 1
	v_permlane32_swap_b32 v10, v11
	s_and_saveexec_b64 s[30:31], vcc
	s_cbranch_execz .LBB0_1576
	s_waitcnt lgkmcnt(0)
	v_add_f32_e32 v10, v10, v11
	v_mul_f32_e32 v10, 0x49800000, v10
	v_mul_f32_e32 v11, 0x2f800000, v10
	v_cvt_u32_f32_e32 v11, v11
	v_cvt_f32_u32_e32 v12, v11
	v_fmac_f32_e32 v10, 0xcf800000, v12
	v_cvt_u32_f32_e32 v10, v10
	global_atomic_add_x2 v[26:27], v[10:11], off offset:256
.LBB0_1576:
	s_or_b64 exec, exec, s[30:31]
	s_waitcnt lgkmcnt(0)
	v_pk_mul_f32 v[10:11], v[74:75], v[74:75]
	v_pk_mul_f32 v[6:7], v[6:7], v[6:7]
	v_pk_fma_f32 v[10:11], v[70:71], v[70:71], v[10:11]
	v_pk_mul_f32 v[12:13], v[76:77], v[76:77]
	v_pk_fma_f32 v[2:3], v[2:3], v[2:3], v[6:7]
	v_pk_mul_f32 v[6:7], v[8:9], v[8:9]
	v_pk_fma_f32 v[12:13], v[72:73], v[72:73], v[12:13]
	v_pk_fma_f32 v[4:5], v[4:5], v[4:5], v[6:7]
	v_add_f32_e32 v2, v2, v3
	v_add_f32_e32 v3, v10, v11
	v_add_f32_e32 v2, v4, v2
	v_add_f32_e32 v3, v12, v3
	v_add_f32_e32 v2, v5, v2
	v_add_f32_e32 v3, v13, v3
	v_add_f32_e32 v2, v3, v2
	v_mov_b32_e32 v3, v2
	s_nop 1
	v_permlane16_swap_b32 v2, v3
	s_waitcnt lgkmcnt(0)
	v_add_f32_e32 v2, v2, v3
	v_mov_b32_e32 v3, v2
	s_nop 1
	v_permlane32_swap_b32 v2, v3
	s_and_saveexec_b64 s[30:31], vcc
	s_cbranch_execz .LBB0_1578
	s_waitcnt lgkmcnt(0)
	v_add_f32_e32 v2, v2, v3
	v_mul_f32_e32 v2, 0x49800000, v2
	v_mul_f32_e32 v3, 0x2f800000, v2
	v_cvt_u32_f32_e32 v3, v3
	v_cvt_f32_u32_e32 v4, v3
	v_fmac_f32_e32 v2, 0xcf800000, v4
	v_cvt_u32_f32_e32 v2, v2
	global_atomic_add_x2 v[26:27], v[2:3], off offset:384

; __device__ __forceinline__ void unpack8(const u32x4 w, float (&f)[8]) { f[0] = bflo(w.x); f[1] = bfhi(w.x); f[2] = bflo(w.y); f[3] = bfhi(w.y); f[4] = bflo(w.z); f[5] = bfhi(w.z); f[6] = bflo(w.w); f[7] = bfhi(w.w); }
; __device__ __forceinline__ u32x4 pack8(const float (&f)[8]) { u32x4 w; w.x = pk2(f[0], f[1]); w.y = pk2(f[2], f[3]); w.z = pk2(f[4], f[5]); w.w = pk2(f[6], f[7]); return w; }
;     template <int QVV> __device__ __forceinline__ void run(f32x4 (&acc)[2][2][4][2], const Unit& u, int wr, int wc, int fr, int fq) const {
;     ...
;             const f32x4 g0 = vg0 * fac, g1 = vg1 * fac;
;             const f32x4 p0 = vp0 * (vs0 + 1.0f), p1 = vp1 * (vs1 + 1.0f);
;             f32x4 r0, r1;
; #pragma unroll
;             for (int i = 0; i < 4; ++i) { r0[i] = __builtin_amdgcn_rcpf(p0[i]); r1[i] = __builtin_amdgcn_rcpf(p1[i]); }
;             const f32x4 c0 = vn0 * (vt0 + 1.0f), c1 = vn1 * (vt1 + 1.0f);
;             u32x4 hin[2][4];
; #pragma unroll
;             for (int ai = 0; ai < 2; ++ai)
; #pragma unroll
;                 for (int m = 0; m < 4; ++m) { if (ai == 1 && qm) continue; hin[ai][m] = *(const u32x4*)(sb + lo + (unsigned)((ai * HALF + m * 16) * DM + bj * HALF) * 2u); }
; #pragma unroll
;             for (int ai = 0; ai < 2; ++ai)
; #pragma unroll
;                 for (int m = 0; m < 4; ++m) { if (ai == 1 && qm) continue;
;                     const unsigned off = lo + (unsigned)((ai * HALF + m * 16) * DM + bj * HALF) * 2u;
;                     float hv[8]; unpack8(hin[ai][m], hv);
;                     float y[8]; float t = 0.f;
; #pragma unroll
;                     for (int i = 0; i < 4; ++i) { const float a0 = hv[i] * r0[i] + g0[i] * acc[ai][bj][m][0][i], a1 = hv[4 + i] * r1[i] + g1[i] * acc[ai][bj][m][1][i];
;                         t += a0 * a0 + a1 * a1; y[i] = a0 * c0[i]; y[4 + i] = a1 * c1[i]; }
;                     ss[ai][m] += t;
;                     *(u32x4*)(sb + off) = pack8(y); }
.LBB0_1759:
	s_waitcnt vmcnt(0)
	v_add_u32_e32 v174, 0x100, v184
	v_add_f32_e32 v80, 1.0, v80
	v_mul_f32_e32 v66, v66, v80
	v_rcp_f32_e32 v192, v66
	v_add_f32_e32 v66, 1.0, v89
	v_mul_f32_e32 v66, v85, v66
	v_rcp_f32_e32 v201, v66
	v_add_f32_e32 v66, 1.0, v81
	v_mul_f32_e32 v66, v67, v66
	v_rcp_f32_e32 v193, v66
	v_add_f32_e32 v66, 1.0, v90
	v_mul_f32_e32 v66, v86, v66
	v_rcp_f32_e32 v194, v66
	v_add_f32_e32 v66, 1.0, v82
	v_mul_f32_e32 v66, v68, v66
	v_rcp_f32_e32 v190, v66
	v_add_f32_e32 v66, 1.0, v91
	v_mul_f32_e32 v66, v87, v66
	v_add_f32_e32 v88, 1.0, v88
	v_rcp_f32_e32 v195, v66
	v_add_f32_e32 v66, 1.0, v83
	v_mul_f32_e32 v84, v84, v88
	v_mul_f32_e32 v66, v69, v66
	v_pk_mul_f32 v[196:197], v[94:95], 0.5 op_sel_hi:[1,0]
	v_pk_mul_f32 v[198:199], v[92:93], 0.5 op_sel_hi:[1,0]
	v_rcp_f32_e32 v200, v84
	v_rcp_f32_e32 v191, v66
	global_load_dwordx4 v[180:183], v[202:203], off offset:256
	global_load_dwordx4 v[100:103], v[204:205], off offset:256
	global_load_dwordx4 v[96:99], v[206:207], off offset:256
	global_load_dwordx4 v[92:95], v[208:209], off offset:256
	global_load_dwordx4 v[88:91], v[210:211], off offset:256
	global_load_dwordx4 v[84:87], v[212:213], off offset:256
	global_load_dwordx4 v[80:83], v[214:215], off offset:256
	global_load_dwordx4 v[66:69], v[216:217], off offset:256
	v_pk_mul_f32 v[106:107], v[106:107], 0.5 op_sel_hi:[1,0]
	v_pk_mul_f32 v[104:105], v[104:105], 0.5 op_sel_hi:[1,0]
	v_pk_mul_f32 v[204:205], v[60:61], v[106:107]
	v_pk_add_f32 v[60:61], v[108:109], 1.0 op_sel_hi:[1,0]
	v_pk_mul_f32 v[64:65], v[64:65], v[196:197]
	v_pk_add_f32 v[76:77], v[76:77], 1.0 op_sel_hi:[1,0]
	v_pk_mul_f32 v[70:71], v[70:71], v[60:61]
	v_pk_mul_f32 v[112:113], v[112:113], v[76:77]
	v_pk_mul_f32 v[58:59], v[58:59], v[104:105]
	v_pk_mul_f32 v[62:63], v[62:63], v[198:199]
	v_pk_add_f32 v[108:109], v[110:111], 1.0 op_sel_hi:[1,0]
	v_pk_mul_f32 v[56:57], v[56:57], v[196:197]
	v_pk_mul_f32 v[72:73], v[72:73], v[108:109]
	v_pk_mul_f32 v[54:55], v[54:55], v[198:199]
	v_pk_mul_f32 v[50:51], v[50:51], v[104:105]
	v_pk_mul_f32 v[48:49], v[48:49], v[196:197]
	v_pk_mul_f32 v[46:47], v[46:47], v[198:199]
	v_pk_mul_f32 v[42:43], v[42:43], v[104:105]
	v_pk_mul_f32 v[40:41], v[40:41], v[196:197]
	v_pk_mul_f32 v[38:39], v[38:39], v[198:199]
	v_pk_mul_f32 v[34:35], v[34:35], v[104:105]
	v_pk_mul_f32 v[32:33], v[32:33], v[196:197]
	v_pk_mul_f32 v[30:31], v[30:31], v[198:199]
	v_pk_mul_f32 v[26:27], v[26:27], v[104:105]
	v_pk_mul_f32 v[24:25], v[24:25], v[196:197]
	v_pk_mul_f32 v[22:23], v[22:23], v[198:199]
	v_pk_mul_f32 v[18:19], v[18:19], v[104:105]
	v_pk_mul_f32 v[16:17], v[16:17], v[196:197]
	v_pk_mul_f32 v[14:15], v[14:15], v[198:199]
	v_pk_mul_f32 v[10:11], v[10:11], v[104:105]
	v_pk_mul_f32 v[8:9], v[8:9], v[196:197]
	v_pk_mul_f32 v[6:7], v[6:7], v[198:199]
	v_pk_mul_f32 v[2:3], v[2:3], v[104:105]
	s_and_b64 vcc, exec, s[40:41]
	s_mov_b32 s62, 0xff61b1e6
	s_mov_b32 s63, 0x41000000
	s_waitcnt vmcnt(7)
	v_lshlrev_b32_e32 v60, 16, v181
	v_and_b32_e32 v61, 0xffff0000, v181
	v_lshlrev_b32_e32 v76, 16, v182
	v_and_b32_e32 v77, 0xffff0000, v182
	v_pk_fma_f32 v[60:61], v[194:195], v[60:61], v[64:65]
	v_pk_add_f32 v[64:65], v[78:79], 1.0 op_sel_hi:[1,0]
	v_lshlrev_b32_e32 v202, 16, v180
	v_and_b32_e32 v203, 0xffff0000, v180
	v_pk_fma_f32 v[58:59], v[192:193], v[76:77], v[58:59]
	v_pk_mul_f32 v[76:77], v[114:115], v[64:65]
	v_lshlrev_b32_e32 v64, 16, v183
	v_and_b32_e32 v65, 0xffff0000, v183
	v_pk_fma_f32 v[62:63], v[200:201], v[202:203], v[62:63]
	v_pk_fma_f32 v[64:65], v[190:191], v[64:65], v[204:205]
	v_pk_mul_f32 v[202:203], v[112:113], v[62:63]
	v_pk_mul_f32 v[206:207], v[70:71], v[58:59]
	v_pk_mul_f32 v[78:79], v[76:77], v[60:61]
	v_pk_mul_f32 v[114:115], v[72:73], v[64:65]
	v_cvt_pk_bf16_f32 v108, v202, v203
	v_cvt_pk_bf16_f32 v109, v78, v79
	v_cvt_pk_bf16_f32 v110, v206, v207
	v_cvt_pk_bf16_f32 v111, v114, v115
	global_store_dwordx4 v174, v[108:111], s[46:47]
	s_waitcnt vmcnt(7)
	v_lshlrev_b32_e32 v78, 16, v100
	v_and_b32_e32 v79, 0xffff0000, v100
	v_pk_mul_f32 v[110:111], v[52:53], v[106:107]
	v_lshlrev_b32_e32 v52, 16, v101
	v_and_b32_e32 v53, 0xffff0000, v101
	v_lshlrev_b32_e32 v108, 16, v102
	v_and_b32_e32 v109, 0xffff0000, v102
	v_pk_fma_f32 v[52:53], v[194:195], v[52:53], v[56:57]
	v_lshlrev_b32_e32 v56, 16, v103
	v_and_b32_e32 v57, 0xffff0000, v103
	v_pk_fma_f32 v[54:55], v[200:201], v[78:79], v[54:55]
	v_pk_fma_f32 v[50:51], v[192:193], v[108:109], v[50:51]
	v_pk_fma_f32 v[56:57], v[190:191], v[56:57], v[110:111]
	v_pk_mul_f32 v[78:79], v[112:113], v[54:55]
	v_pk_mul_f32 v[108:109], v[70:71], v[50:51]
	v_pk_mul_f32 v[114:115], v[76:77], v[52:53]
	v_pk_mul_f32 v[110:111], v[72:73], v[56:57]
	v_add_u32_e32 v174, 0x10100, v184
	v_cvt_pk_bf16_f32 v100, v78, v79
	v_cvt_pk_bf16_f32 v101, v114, v115
	v_cvt_pk_bf16_f32 v102, v108, v109
	v_cvt_pk_bf16_f32 v103, v110, v111
	global_store_dwordx4 v174, v[100:103], s[46:47]
	s_waitcnt vmcnt(7)
	v_lshlrev_b32_e32 v78, 16, v96
	v_and_b32_e32 v79, 0xffff0000, v96
	v_pk_mul_f32 v[102:103], v[44:45], v[106:107]
	v_lshlrev_b32_e32 v44, 16, v97
	v_and_b32_e32 v45, 0xffff0000, v97
	v_lshlrev_b32_e32 v100, 16, v98
	v_and_b32_e32 v101, 0xffff0000, v98
	v_pk_fma_f32 v[44:45], v[194:195], v[44:45], v[48:49]
	v_lshlrev_b32_e32 v48, 16, v99
	v_and_b32_e32 v49, 0xffff0000, v99
	v_pk_fma_f32 v[46:47], v[200:201], v[78:79], v[46:47]
	v_pk_fma_f32 v[42:43], v[192:193], v[100:101], v[42:43]
	v_pk_fma_f32 v[48:49], v[190:191], v[48:49], v[102:103]
	v_pk_mul_f32 v[78:79], v[112:113], v[46:47]
	v_pk_mul_f32 v[100:101], v[70:71], v[42:43]
	v_pk_mul_f32 v[108:109], v[76:77], v[44:45]
	v_pk_mul_f32 v[102:103], v[72:73], v[48:49]
	v_add_u32_e32 v110, 0x20100, v184
	v_cvt_pk_bf16_f32 v96, v78, v79
	v_cvt_pk_bf16_f32 v97, v108, v109
	v_cvt_pk_bf16_f32 v98, v100, v101
	v_cvt_pk_bf16_f32 v99, v102, v103
	global_store_dwordx4 v110, v[96:99], s[46:47]
	s_waitcnt vmcnt(7)
; __device__ __forceinline__ void unpack8(const u32x4 w, float (&f)[8]) { f[0] = bflo(w.x); f[1] = bfhi(w.x); f[2] = bflo(w.y); f[3] = bfhi(w.y); f[4] = bflo(w.z); f[5] = bfhi(w.z); f[6] = bflo(w.w); f[7] = bfhi(w.w); }
; __device__ __forceinline__ u32x4 pack8(const float (&f)[8]) { u32x4 w; w.x = pk2(f[0], f[1]); w.y = pk2(f[2], f[3]); w.z = pk2(f[4], f[5]); w.w = pk2(f[6], f[7]); return w; }
;     template <int QVV> __device__ __forceinline__ void run(f32x4 (&acc)[2][2][4][2], const Unit& u, int wr, int wc, int fr, int fq) const {
;     ...
;                 for (int m = 0; m < 4; ++m) { if (ai == 1 && qm) continue;
;                     const unsigned off = lo + (unsigned)((ai * HALF + m * 16) * DM + bj * HALF) * 2u;
;                     float hv[8]; unpack8(hin[ai][m], hv);
;                     float y[8]; float t = 0.f;
; #pragma unroll
;                     for (int i = 0; i < 4; ++i) { const float a0 = hv[i] * r0[i] + g0[i] * acc[ai][bj][m][0][i], a1 = hv[4 + i] * r1[i] + g1[i] * acc[ai][bj][m][1][i];
;                         t += a0 * a0 + a1 * a1; y[i] = a0 * c0[i]; y[4 + i] = a1 * c1[i]; }
;                     ss[ai][m] += t;
;                     *(u32x4*)(sb + off) = pack8(y); }
;             asm volatile("" ::: "memory");
;         }
;         if (hasn) {
;             unsigned long long* sp = ssq + u.pm * BM + rq + wr * 64 + fr;
; #pragma unroll
;             for (int ai = 0; ai < 2; ++ai)
; #pragma unroll
;                 for (int m = 0; m < 4; ++m) { if (ai == 1 && qm) continue; float t = ss[ai][m]; t += __shfl_xor(t, 16); t += __shfl_xor(t, 32);
;                     const float xs = t * SSQ_SCALE; const unsigned xh = (unsigned)(xs * 2.3283064365386963e-10f), xl = (unsigned)__builtin_fmaf(-(float)xh, 4294967296.0f, xs);
;                     if (fq == 0) atomicAdd(sp + ai * HALF + m * 16, ((unsigned long long)xh << 32) | xl); }
	v_lshlrev_b32_e32 v78, 16, v92
	v_and_b32_e32 v79, 0xffff0000, v92
	v_pk_mul_f32 v[98:99], v[36:37], v[106:107]
	v_lshlrev_b32_e32 v36, 16, v93
	v_and_b32_e32 v37, 0xffff0000, v93
	v_lshlrev_b32_e32 v96, 16, v94
	v_and_b32_e32 v97, 0xffff0000, v94
	v_pk_fma_f32 v[36:37], v[194:195], v[36:37], v[40:41]
	v_lshlrev_b32_e32 v40, 16, v95
	v_and_b32_e32 v41, 0xffff0000, v95
	v_pk_fma_f32 v[38:39], v[200:201], v[78:79], v[38:39]
	v_pk_fma_f32 v[34:35], v[192:193], v[96:97], v[34:35]
	v_pk_fma_f32 v[40:41], v[190:191], v[40:41], v[98:99]
	v_pk_mul_f32 v[78:79], v[112:113], v[38:39]
	v_pk_mul_f32 v[96:97], v[70:71], v[34:35]
	v_pk_mul_f32 v[100:101], v[76:77], v[36:37]
	v_pk_mul_f32 v[98:99], v[72:73], v[40:41]
	v_add_u32_e32 v102, 0x30100, v184
	v_cvt_pk_bf16_f32 v92, v78, v79
	v_cvt_pk_bf16_f32 v93, v100, v101
	v_cvt_pk_bf16_f32 v94, v96, v97
	v_cvt_pk_bf16_f32 v95, v98, v99
	global_store_dwordx4 v102, v[92:95], s[46:47]
	s_waitcnt vmcnt(7)
	v_lshlrev_b32_e32 v78, 16, v88
	v_and_b32_e32 v79, 0xffff0000, v88
	v_pk_mul_f32 v[94:95], v[28:29], v[106:107]
	v_lshlrev_b32_e32 v28, 16, v89
	v_and_b32_e32 v29, 0xffff0000, v89
	v_lshlrev_b32_e32 v92, 16, v90
	v_and_b32_e32 v93, 0xffff0000, v90
	v_pk_fma_f32 v[28:29], v[194:195], v[28:29], v[32:33]
	v_lshlrev_b32_e32 v32, 16, v91
	v_and_b32_e32 v33, 0xffff0000, v91
	v_pk_fma_f32 v[30:31], v[200:201], v[78:79], v[30:31]
	v_pk_fma_f32 v[26:27], v[192:193], v[92:93], v[26:27]
	v_pk_fma_f32 v[32:33], v[190:191], v[32:33], v[94:95]
	v_pk_mul_f32 v[78:79], v[112:113], v[30:31]
	v_pk_mul_f32 v[92:93], v[70:71], v[26:27]
	v_pk_mul_f32 v[96:97], v[76:77], v[28:29]
	v_pk_mul_f32 v[94:95], v[72:73], v[32:33]
	v_add_u32_e32 v98, 0x80100, v184
	v_cvt_pk_bf16_f32 v88, v78, v79
	v_cvt_pk_bf16_f32 v89, v96, v97
	v_cvt_pk_bf16_f32 v90, v92, v93
	v_cvt_pk_bf16_f32 v91, v94, v95
	global_store_dwordx4 v98, v[88:91], s[46:47]
	s_waitcnt vmcnt(7)
	v_lshlrev_b32_e32 v78, 16, v84
	v_and_b32_e32 v79, 0xffff0000, v84
	v_pk_mul_f32 v[90:91], v[20:21], v[106:107]
	v_lshlrev_b32_e32 v20, 16, v85
	v_and_b32_e32 v21, 0xffff0000, v85
	v_lshlrev_b32_e32 v88, 16, v86
	v_and_b32_e32 v89, 0xffff0000, v86
	v_pk_fma_f32 v[20:21], v[194:195], v[20:21], v[24:25]
	v_lshlrev_b32_e32 v24, 16, v87
	v_and_b32_e32 v25, 0xffff0000, v87
	v_pk_fma_f32 v[22:23], v[200:201], v[78:79], v[22:23]
	v_pk_fma_f32 v[18:19], v[192:193], v[88:89], v[18:19]
	v_pk_fma_f32 v[24:25], v[190:191], v[24:25], v[90:91]
	v_pk_mul_f32 v[78:79], v[112:113], v[22:23]
	v_pk_mul_f32 v[88:89], v[70:71], v[18:19]
	v_pk_mul_f32 v[92:93], v[76:77], v[20:21]
	v_pk_mul_f32 v[90:91], v[72:73], v[24:25]
	v_add_u32_e32 v94, 0x90100, v184
	v_cvt_pk_bf16_f32 v84, v78, v79
	v_cvt_pk_bf16_f32 v85, v92, v93
	v_cvt_pk_bf16_f32 v86, v88, v89
	v_cvt_pk_bf16_f32 v87, v90, v91
	global_store_dwordx4 v94, v[84:87], s[46:47]
	s_waitcnt vmcnt(7)
	v_lshlrev_b32_e32 v78, 16, v80
	v_and_b32_e32 v79, 0xffff0000, v80
	v_pk_mul_f32 v[86:87], v[12:13], v[106:107]
	v_lshlrev_b32_e32 v12, 16, v81
	v_and_b32_e32 v13, 0xffff0000, v81
	v_lshlrev_b32_e32 v84, 16, v82
	v_and_b32_e32 v85, 0xffff0000, v82
	v_pk_fma_f32 v[12:13], v[194:195], v[12:13], v[16:17]
	v_lshlrev_b32_e32 v16, 16, v83
	v_and_b32_e32 v17, 0xffff0000, v83
	v_pk_fma_f32 v[14:15], v[200:201], v[78:79], v[14:15]
	v_pk_fma_f32 v[10:11], v[192:193], v[84:85], v[10:11]
	v_pk_fma_f32 v[16:17], v[190:191], v[16:17], v[86:87]
	v_pk_mul_f32 v[78:79], v[112:113], v[14:15]
	v_pk_mul_f32 v[84:85], v[70:71], v[10:11]
	v_pk_mul_f32 v[80:81], v[76:77], v[12:13]
	v_pk_mul_f32 v[82:83], v[72:73], v[16:17]
	v_add_u32_e32 v86, 0xa0100, v184
	v_cvt_pk_bf16_f32 v78, v78, v79
	v_cvt_pk_bf16_f32 v79, v80, v81
	v_cvt_pk_bf16_f32 v80, v84, v85
	v_cvt_pk_bf16_f32 v81, v82, v83
	v_pk_mul_f32 v[82:83], v[4:5], v[106:107]
	s_waitcnt vmcnt(6)
	v_lshlrev_b32_e32 v4, 16, v67
	v_and_b32_e32 v5, 0xffff0000, v67
	global_store_dwordx4 v86, v[78:81], s[46:47]
	v_pk_fma_f32 v[4:5], v[194:195], v[4:5], v[8:9]
	v_lshlrev_b32_e32 v8, 16, v69
	v_lshlrev_b32_e32 v78, 16, v66
	v_and_b32_e32 v79, 0xffff0000, v66
	v_lshlrev_b32_e32 v80, 16, v68
	v_and_b32_e32 v81, 0xffff0000, v68
	v_and_b32_e32 v9, 0xffff0000, v69
	v_pk_fma_f32 v[6:7], v[200:201], v[78:79], v[6:7]
	v_pk_fma_f32 v[2:3], v[192:193], v[80:81], v[2:3]
	v_pk_fma_f32 v[8:9], v[190:191], v[8:9], v[82:83]
	v_pk_mul_f32 v[78:79], v[112:113], v[6:7]
	v_pk_mul_f32 v[70:71], v[70:71], v[2:3]
	v_pk_mul_f32 v[76:77], v[76:77], v[4:5]
	v_pk_mul_f32 v[72:73], v[72:73], v[8:9]
	v_add_u32_e32 v80, 0xb0100, v184
	v_cvt_pk_bf16_f32 v66, v78, v79
	v_cvt_pk_bf16_f32 v67, v76, v77
	v_cvt_pk_bf16_f32 v68, v70, v71
	v_cvt_pk_bf16_f32 v69, v72, v73
	global_store_dwordx4 v80, v[66:69], s[46:47]
	s_cbranch_vccnz .LBB0_1777
	v_pk_mul_f32 v[58:59], v[58:59], v[58:59]
	v_pk_mul_f32 v[66:67], v[156:157], v[156:157]
	v_pk_mul_f32 v[64:65], v[64:65], v[64:65]
	v_pk_fma_f32 v[58:59], v[62:63], v[62:63], v[58:59]
	v_pk_fma_f32 v[66:67], v[150:151], v[150:151], v[66:67]
	v_pk_mul_f32 v[68:69], v[188:189], v[188:189]
	v_pk_fma_f32 v[60:61], v[60:61], v[60:61], v[64:65]
	v_add_f32_e32 v58, v58, v59
	v_pk_fma_f32 v[68:69], v[164:165], v[164:165], v[68:69]
	v_add_f32_e32 v58, v60, v58
	v_add_f32_e32 v59, v66, v67
	v_xor_b32_e32 v60, 16, v230
	v_add_f32_e32 v59, v68, v59
	v_cmp_lt_i32_e32 vcc, v60, v232
	v_add_f32_e32 v58, v61, v58
	v_add_f32_e32 v59, v69, v59
	v_cndmask_b32_e32 v60, v230, v60, vcc
	v_add_f32_e32 v61, v59, v58
	v_lshlrev_b32_e32 v60, 2, v60
	v_mov_b32_e32 v62, v61
	s_nop 1
	v_permlane16_swap_b32 v61, v62
	s_lshl_b32 s30, s52, 8
	s_ashr_i32 s31, s30, 31
	v_lshl_add_u64 v[58:59], s[30:31], 3, v[250:251]
	s_waitcnt lgkmcnt(0)
	v_add_f32_e32 v62, v61, v62
	v_xor_b32_e32 v61, 32, v230
	v_cmp_lt_i32_e32 vcc, v61, v232
	s_nop 1
	v_cndmask_b32_e32 v61, v230, v61, vcc
	v_lshlrev_b32_e32 v61, 2, v61
	v_mov_b32_e32 v63, v62
	s_nop 1
	v_permlane32_swap_b32 v62, v63
	s_and_saveexec_b64 s[30:31], s[38:39]
	s_cbranch_execz .LBB0_1762
	s_waitcnt lgkmcnt(0)
	v_add_f32_e32 v62, v62, v63
	v_mul_f32_e32 v62, 0x49800000, v62
	v_mul_f32_e32 v63, 0x2f800000, v62
	v_cvt_u32_f32_e32 v63, v63
	v_cvt_f32_u32_e32 v64, v63
	v_fmac_f32_e32 v62, 0xcf800000, v64
	v_cvt_u32_f32_e32 v62, v62
	global_atomic_add_x2 v[58:59], v[62:63], off
;     template <int QVV> __device__ __forceinline__ void run(f32x4 (&acc)[2][2][4][2], const Unit& u, int wr, int wc, int fr, int fq) const {
;     ...
;         if (hasn) {
;             unsigned long long* sp = ssq + u.pm * BM + rq + wr * 64 + fr;
; #pragma unroll
;             for (int ai = 0; ai < 2; ++ai)
; #pragma unroll
;                 for (int m = 0; m < 4; ++m) { if (ai == 1 && qm) continue; float t = ss[ai][m]; t += __shfl_xor(t, 16); t += __shfl_xor(t, 32);
;                     const float xs = t * SSQ_SCALE; const unsigned xh = (unsigned)(xs * 2.3283064365386963e-10f), xl = (unsigned)__builtin_fmaf(-(float)xh, 4294967296.0f, xs);
;                     if (fq == 0) atomicAdd(sp + ai * HALF + m * 16, ((unsigned long long)xh << 32) | xl); }
.LBB0_1762:
	s_or_b64 exec, exec, s[30:31]
	s_waitcnt lgkmcnt(0)
	v_pk_mul_f32 v[62:63], v[120:121], v[120:121]
	v_pk_mul_f32 v[50:51], v[50:51], v[50:51]
	v_pk_fma_f32 v[62:63], v[122:123], v[122:123], v[62:63]
	v_pk_mul_f32 v[64:65], v[142:143], v[142:143]
	v_pk_fma_f32 v[50:51], v[54:55], v[54:55], v[50:51]
	v_pk_mul_f32 v[54:55], v[56:57], v[56:57]
	v_pk_fma_f32 v[64:65], v[124:125], v[124:125], v[64:65]
	v_pk_fma_f32 v[52:53], v[52:53], v[52:53], v[54:55]
	v_add_f32_e32 v50, v50, v51
	v_add_f32_e32 v51, v62, v63
	v_add_f32_e32 v50, v52, v50
	v_add_f32_e32 v51, v64, v51
	v_add_f32_e32 v50, v53, v50
	v_add_f32_e32 v51, v65, v51
	v_add_f32_e32 v50, v51, v50
	v_mov_b32_e32 v51, v50
	s_nop 1
	v_permlane16_swap_b32 v50, v51
	s_waitcnt lgkmcnt(0)
	v_add_f32_e32 v50, v50, v51
	v_mov_b32_e32 v51, v50
	s_nop 1
	v_permlane32_swap_b32 v50, v51
	s_and_saveexec_b64 s[30:31], s[38:39]
	s_cbranch_execz .LBB0_1764
	s_waitcnt lgkmcnt(0)
	v_add_f32_e32 v50, v50, v51
	v_mul_f32_e32 v50, 0x49800000, v50
	v_mul_f32_e32 v51, 0x2f800000, v50
	v_cvt_u32_f32_e32 v51, v51
	v_cvt_f32_u32_e32 v52, v51
	v_fmac_f32_e32 v50, 0xcf800000, v52
	v_cvt_u32_f32_e32 v50, v50
	global_atomic_add_x2 v[58:59], v[50:51], off offset:128
.LBB0_1764:
	s_or_b64 exec, exec, s[30:31]
	s_waitcnt lgkmcnt(0)
	v_pk_mul_f32 v[50:51], v[136:137], v[136:137]
	v_pk_mul_f32 v[42:43], v[42:43], v[42:43]
	v_pk_fma_f32 v[50:51], v[116:117], v[116:117], v[50:51]
	v_pk_mul_f32 v[52:53], v[152:153], v[152:153]
	v_pk_fma_f32 v[42:43], v[46:47], v[46:47], v[42:43]
	v_pk_mul_f32 v[46:47], v[48:49], v[48:49]
	v_pk_fma_f32 v[52:53], v[138:139], v[138:139], v[52:53]
	v_pk_fma_f32 v[44:45], v[44:45], v[44:45], v[46:47]
	v_add_f32_e32 v42, v42, v43
	v_add_f32_e32 v43, v50, v51
	v_add_f32_e32 v42, v44, v42
	v_add_f32_e32 v43, v52, v43
	v_add_f32_e32 v42, v45, v42
	v_add_f32_e32 v43, v53, v43
	v_add_f32_e32 v42, v43, v42
	v_mov_b32_e32 v43, v42
	s_nop 1
	v_permlane16_swap_b32 v42, v43
	s_waitcnt lgkmcnt(0)
	v_add_f32_e32 v42, v42, v43
	v_mov_b32_e32 v43, v42
	s_nop 1
	v_permlane32_swap_b32 v42, v43
	s_and_saveexec_b64 s[30:31], s[38:39]
	s_cbranch_execz .LBB0_1766
	s_waitcnt lgkmcnt(0)
	v_add_f32_e32 v42, v42, v43
	v_mul_f32_e32 v42, 0x49800000, v42
	v_mul_f32_e32 v43, 0x2f800000, v42
	v_cvt_u32_f32_e32 v43, v43
	v_cvt_f32_u32_e32 v44, v43
	v_fmac_f32_e32 v42, 0xcf800000, v44
	v_cvt_u32_f32_e32 v42, v42
	global_atomic_add_x2 v[58:59], v[42:43], off offset:256
.LBB0_1766:
	s_or_b64 exec, exec, s[30:31]
	s_waitcnt lgkmcnt(0)
	v_pk_mul_f32 v[42:43], v[144:145], v[144:145]
	v_pk_mul_f32 v[34:35], v[34:35], v[34:35]
	v_pk_fma_f32 v[42:43], v[118:119], v[118:119], v[42:43]
	v_pk_mul_f32 v[44:45], v[160:161], v[160:161]
	v_pk_fma_f32 v[34:35], v[38:39], v[38:39], v[34:35]
	v_pk_mul_f32 v[38:39], v[40:41], v[40:41]
	v_pk_fma_f32 v[44:45], v[146:147], v[146:147], v[44:45]
	v_pk_fma_f32 v[36:37], v[36:37], v[36:37], v[38:39]
	v_add_f32_e32 v34, v34, v35
	v_add_f32_e32 v35, v42, v43
	v_add_f32_e32 v34, v36, v34
	v_add_f32_e32 v35, v44, v35
	v_add_f32_e32 v34, v37, v34
	v_add_f32_e32 v35, v45, v35
	v_add_f32_e32 v34, v35, v34
	v_mov_b32_e32 v35, v34
	s_nop 1
	v_permlane16_swap_b32 v34, v35
	s_waitcnt lgkmcnt(0)
	v_add_f32_e32 v34, v34, v35
	v_mov_b32_e32 v35, v34
	s_nop 1
	v_permlane32_swap_b32 v34, v35
	s_and_saveexec_b64 s[30:31], s[38:39]
	s_cbranch_execz .LBB0_1768
	s_waitcnt lgkmcnt(0)
	v_add_f32_e32 v34, v34, v35
	v_mul_f32_e32 v34, 0x49800000, v34
	v_mul_f32_e32 v35, 0x2f800000, v34
	v_cvt_u32_f32_e32 v35, v35
	v_cvt_f32_u32_e32 v36, v35
	v_fmac_f32_e32 v34, 0xcf800000, v36
	v_cvt_u32_f32_e32 v34, v34
	global_atomic_add_x2 v[58:59], v[34:35], off offset:384
;     template <int QVV> __device__ __forceinline__ void run(f32x4 (&acc)[2][2][4][2], const Unit& u, int wr, int wc, int fr, int fq) const {
;     ...
;         if (hasn) {
;             unsigned long long* sp = ssq + u.pm * BM + rq + wr * 64 + fr;
; #pragma unroll
;             for (int ai = 0; ai < 2; ++ai)
; #pragma unroll
;                 for (int m = 0; m < 4; ++m) { if (ai == 1 && qm) continue; float t = ss[ai][m]; t += __shfl_xor(t, 16); t += __shfl_xor(t, 32);
;                     const float xs = t * SSQ_SCALE; const unsigned xh = (unsigned)(xs * 2.3283064365386963e-10f), xl = (unsigned)__builtin_fmaf(-(float)xh, 4294967296.0f, xs);
;                     if (fq == 0) atomicAdd(sp + ai * HALF + m * 16, ((unsigned long long)xh << 32) | xl); }
.LBB0_1768:
	s_or_b64 exec, exec, s[30:31]
	s_waitcnt lgkmcnt(0)
	v_pk_mul_f32 v[34:35], v[154:155], v[154:155]
	v_pk_mul_f32 v[26:27], v[26:27], v[26:27]
	v_pk_fma_f32 v[34:35], v[134:135], v[134:135], v[34:35]
	v_pk_mul_f32 v[36:37], v[168:169], v[168:169]
	v_pk_fma_f32 v[26:27], v[30:31], v[30:31], v[26:27]
	v_pk_mul_f32 v[30:31], v[32:33], v[32:33]
	v_pk_fma_f32 v[36:37], v[158:159], v[158:159], v[36:37]
	v_pk_fma_f32 v[28:29], v[28:29], v[28:29], v[30:31]
	v_add_f32_e32 v26, v26, v27
	v_add_f32_e32 v27, v34, v35
	v_add_f32_e32 v26, v28, v26
	v_add_f32_e32 v27, v36, v27
	v_add_f32_e32 v26, v29, v26
	v_add_f32_e32 v27, v37, v27
	v_add_f32_e32 v26, v27, v26
	v_mov_b32_e32 v27, v26
	s_nop 1
	v_permlane16_swap_b32 v26, v27
	s_waitcnt lgkmcnt(0)
	v_add_f32_e32 v26, v26, v27
	v_mov_b32_e32 v27, v26
	s_nop 1
	v_permlane32_swap_b32 v26, v27
	s_and_saveexec_b64 s[30:31], s[38:39]
	s_cbranch_execz .LBB0_1770
	s_waitcnt lgkmcnt(0)
	v_add_f32_e32 v26, v26, v27
	v_mul_f32_e32 v26, 0x49800000, v26
	v_mul_f32_e32 v27, 0x2f800000, v26
	v_cvt_u32_f32_e32 v27, v27
	v_cvt_f32_u32_e32 v28, v27
	v_fmac_f32_e32 v26, 0xcf800000, v28
	v_cvt_u32_f32_e32 v26, v26
	global_atomic_add_x2 v[58:59], v[26:27], off offset:1024
.LBB0_1770:
	s_or_b64 exec, exec, s[30:31]
	s_waitcnt lgkmcnt(0)
	v_pk_mul_f32 v[26:27], v[162:163], v[162:163]
	v_pk_mul_f32 v[18:19], v[18:19], v[18:19]
	v_pk_fma_f32 v[26:27], v[140:141], v[140:141], v[26:27]
	v_pk_mul_f32 v[28:29], v[172:173], v[172:173]
	v_pk_fma_f32 v[18:19], v[22:23], v[22:23], v[18:19]
	v_pk_mul_f32 v[22:23], v[24:25], v[24:25]
	v_pk_fma_f32 v[28:29], v[166:167], v[166:167], v[28:29]
	v_pk_fma_f32 v[20:21], v[20:21], v[20:21], v[22:23]
	v_add_f32_e32 v18, v18, v19
	v_add_f32_e32 v19, v26, v27
	v_add_f32_e32 v18, v20, v18
	v_add_f32_e32 v19, v28, v19
	v_add_f32_e32 v18, v21, v18
	v_add_f32_e32 v19, v29, v19
	v_add_f32_e32 v18, v19, v18
	v_mov_b32_e32 v19, v18
	s_nop 1
	v_permlane16_swap_b32 v18, v19
	s_waitcnt lgkmcnt(0)
	v_add_f32_e32 v18, v18, v19
	v_mov_b32_e32 v19, v18
	s_nop 1
	v_permlane32_swap_b32 v18, v19
	s_and_saveexec_b64 s[30:31], s[38:39]
	s_cbranch_execz .LBB0_1772
	s_waitcnt lgkmcnt(0)
	v_add_f32_e32 v18, v18, v19
	v_mul_f32_e32 v18, 0x49800000, v18
	v_mul_f32_e32 v19, 0x2f800000, v18
	v_cvt_u32_f32_e32 v19, v19
	v_cvt_f32_u32_e32 v20, v19
	v_fmac_f32_e32 v18, 0xcf800000, v20
	v_cvt_u32_f32_e32 v18, v18
	global_atomic_add_x2 v[58:59], v[18:19], off offset:1152
.LBB0_1772:
	s_or_b64 exec, exec, s[30:31]
	s_waitcnt lgkmcnt(0)
	v_pk_mul_f32 v[18:19], v[170:171], v[170:171]
	v_pk_mul_f32 v[10:11], v[10:11], v[10:11]
	v_pk_fma_f32 v[18:19], v[148:149], v[148:149], v[18:19]
	v_pk_mul_f32 v[20:21], v[186:187], v[186:187]
	v_pk_fma_f32 v[10:11], v[14:15], v[14:15], v[10:11]
	v_pk_mul_f32 v[14:15], v[16:17], v[16:17]
	v_pk_fma_f32 v[20:21], v[130:131], v[130:131], v[20:21]
	v_pk_fma_f32 v[12:13], v[12:13], v[12:13], v[14:15]
	v_add_f32_e32 v10, v10, v11
	v_add_f32_e32 v11, v18, v19
	v_add_f32_e32 v10, v12, v10
	v_add_f32_e32 v11, v20, v11
	v_add_f32_e32 v10, v13, v10
	v_add_f32_e32 v11, v21, v11
	v_add_f32_e32 v10, v11, v10
	v_mov_b32_e32 v11, v10
	s_nop 1
	v_permlane16_swap_b32 v10, v11
	s_waitcnt lgkmcnt(0)
	v_add_f32_e32 v10, v10, v11
	v_mov_b32_e32 v11, v10
	s_nop 1
	v_permlane32_swap_b32 v10, v11
	s_and_saveexec_b64 s[30:31], s[38:39]
	s_cbranch_execz .LBB0_1774
	s_waitcnt lgkmcnt(0)
	v_add_f32_e32 v10, v10, v11
	v_mul_f32_e32 v10, 0x49800000, v10
	v_mul_f32_e32 v11, 0x2f800000, v10
	v_cvt_u32_f32_e32 v11, v11
	v_cvt_f32_u32_e32 v12, v11
	v_fmac_f32_e32 v10, 0xcf800000, v12
	v_cvt_u32_f32_e32 v10, v10
	global_atomic_add_x2 v[58:59], v[10:11], off offset:1280
.LBB0_1774:
	s_or_b64 exec, exec, s[30:31]
	s_waitcnt lgkmcnt(0)
	v_pk_mul_f32 v[10:11], v[132:133], v[132:133]
	v_pk_mul_f32 v[2:3], v[2:3], v[2:3]
	v_pk_fma_f32 v[10:11], v[74:75], v[74:75], v[10:11]
	v_pk_mul_f32 v[12:13], v[128:129], v[128:129]
	v_pk_fma_f32 v[2:3], v[6:7], v[6:7], v[2:3]
	v_pk_mul_f32 v[6:7], v[8:9], v[8:9]
	v_pk_fma_f32 v[12:13], v[126:127], v[126:127], v[12:13]
	v_pk_fma_f32 v[4:5], v[4:5], v[4:5], v[6:7]
	v_add_f32_e32 v2, v2, v3
	v_add_f32_e32 v3, v10, v11
	v_add_f32_e32 v2, v4, v2
	v_add_f32_e32 v3, v12, v3
	v_add_f32_e32 v2, v5, v2
	v_add_f32_e32 v3, v13, v3
	v_add_f32_e32 v2, v3, v2
	v_mov_b32_e32 v3, v2
	s_nop 1
	v_permlane16_swap_b32 v2, v3
	s_waitcnt lgkmcnt(0)
	v_add_f32_e32 v2, v2, v3
	v_mov_b32_e32 v3, v2
	s_nop 1
	v_permlane32_swap_b32 v2, v3
	s_and_saveexec_b64 s[30:31], s[38:39]
	s_cbranch_execz .LBB0_1776
	s_waitcnt lgkmcnt(0)
	v_add_f32_e32 v2, v2, v3
	v_mul_f32_e32 v2, 0x49800000, v2
	v_mul_f32_e32 v3, 0x2f800000, v2
	v_cvt_u32_f32_e32 v3, v3
	v_cvt_f32_u32_e32 v4, v3
	v_fmac_f32_e32 v2, 0xcf800000, v4
	v_cvt_u32_f32_e32 v2, v2
	global_atomic_add_x2 v[58:59], v[2:3], off offset:1408

;     template <int QVV> __device__ __forceinline__ void run(f32x4 (&acc)[2][2][4][2], const Unit& u, int wr, int wc, int fr, int fq) const {
;         const bool qm = u.seg != 0; const int rq = qm ? 64 * (u.seg - 1) : 0;
;         const bool active = !(qm && wr == 1);
;         const int v = u.pm < 4 ? 4 : ((u.pm - 4) >> 5);
;         char* sb = (char*)(S + ((size_t)u.pm * BM + rq) * DM + u.pn * BM);
;         const char* gp = (const char*)(gate + (size_t)v * (NMOD * DM) + u.pn * BM);
;         const bool hasn = ng != nullptr;
;         const char* pgp = (const char*)(pg + u.pn * BM); const char* psp = (const char*)(psc + (size_t)v * (NMOD * DM) + u.pn * BM);
;         const char* ngp = (const char*)(ng + u.pn * BM); const char* nsp = (const char*)(nsc + (size_t)v * (NMOD * DM) + u.pn * BM);
;         unsigned co = (unsigned)(wc * 32 + 8 * fq);
;         asm volatile("" : "+v"(co));
;         unsigned lo = ((unsigned)((wr * 64 + fr) * DM) + co) * 2u;
;         asm volatile("" : "+v"(lo));
;         if (active) {
;         float ss[2][4];
; #pragma unroll
;         for (int ai = 0; ai < 2; ++ai)
; #pragma unroll
;             for (int m = 0; m < 4; ++m) ss[ai][m] = 0.f;
; #pragma unroll
;         for (int bj = 0; bj < 2; ++bj) {
;             const unsigned cb4 = (co + bj * HALF) * 4u;
;             f32x4 vg0 = *(const f32x4*)(gp + cb4), vg1 = *(const f32x4*)(gp + cb4 + 16), vp0 = *(const f32x4*)(pgp + cb4), vp1 = *(const f32x4*)(pgp + cb4 + 16), vs0 = *(const f32x4*)(psp + cb4), vs1 = *(const f32x4*)(psp + cb4 + 16);
;             f32x4 vn0 = {1.f, 1.f, 1.f, 1.f}, vn1 = vn0, vt0 = {0.f, 0.f, 0.f, 0.f}, vt1 = vt0;
;             if (hasn) { vn0 = *(const f32x4*)(ngp + cb4); vn1 = *(const f32x4*)(ngp + cb4 + 16); vt0 = *(const f32x4*)(nsp + cb4); vt1 = *(const f32x4*)(nsp + cb4 + 16); }
;             asm volatile("" : "+v"(vg0), "+v"(vg1), "+v"(vp0), "+v"(vp1), "+v"(vs0), "+v"(vs1), "+v"(vn0), "+v"(vn1), "+v"(vt0), "+v"(vt1));
;             const f32x4 g0 = vg0 * fac, g1 = vg1 * fac;
;             const f32x4 p0 = vp0 * (vs0 + 1.0f), p1 = vp1 * (vs1 + 1.0f);
;             f32x4 r0, r1;
; #pragma unroll
;             for (int i = 0; i < 4; ++i) { r0[i] = __builtin_amdgcn_rcpf(p0[i]); r1[i] = __builtin_amdgcn_rcpf(p1[i]); }
;             const f32x4 c0 = vn0 * (vt0 + 1.0f), c1 = vn1 * (vt1 + 1.0f);
;             u32x4 hin[2][4];
; #pragma unroll
.LBB0_1796:
	s_waitcnt lgkmcnt(14)
	v_lshl_or_b32 v66, v131, 3, s26
	v_lshlrev_b32_e32 v67, 12, v136
	s_andn2_b64 vcc, exec, s[30:31]
	v_lshl_add_u32 v174, v66, 1, v67
	s_movk_i32 s22, 0x25ff
	s_mov_b32 s26, 0xffff
	s_mov_b32 s27, 0xac00
	s_mov_b32 s28, 0x70000
	s_cbranch_vccnz .LBB0_1806
	v_readlane_b32 s15, v253, 22
	s_ashr_i32 s35, s34, 31
	s_lshl_b32 s14, s15, 2
	s_add_u32 s10, s10, s14
	s_addc_u32 s11, s11, 0
	s_add_u32 s38, s10, 0xa4000
	s_addc_u32 s39, s11, 0
	s_add_u32 s40, s13, s14
	s_addc_u32 s41, s12, 0
	s_add_u32 s42, s10, 0x56000
	s_addc_u32 s43, s11, 0
	s_add_u32 s44, s8, s14
	s_addc_u32 s45, s9, 0
	s_add_u32 s46, s10, 0x58000
	s_waitcnt lgkmcnt(0)
	v_lshlrev_b32_e32 v128, 2, v66
	s_addc_u32 s47, s11, 0
	global_load_dwordx4 v[82:85], v128, s[44:45] offset:16
	global_load_dwordx4 v[92:95], v128, s[44:45]
	global_load_dwordx4 v[96:99], v128, s[42:43] offset:16
	global_load_dwordx4 v[100:103], v128, s[42:43]
	global_load_dwordx4 v[70:73], v128, s[40:41] offset:16
	global_load_dwordx4 v[74:77], v128, s[40:41]
	global_load_dwordx4 v[104:107], v128, s[38:39] offset:16
	global_load_dwordx4 v[108:111], v128, s[38:39]
	global_load_dwordx4 v[112:115], v128, s[46:47] offset:16
	global_load_dwordx4 v[116:119], v128, s[46:47]
	v_readlane_b32 s8, v253, 24
	v_readlane_b32 s9, v253, 25
	s_add_u32 s5, s5, s8
	s_addc_u32 s7, s7, s9
	v_readlane_b32 s8, v253, 46
	s_add_u32 s5, s5, s8
	s_addc_u32 s7, s7, 0
	s_lshl_b32 s8, s15, 1
	s_add_u32 s30, s5, s8
	s_addc_u32 s31, s7, 0
	v_lshl_add_u64 v[66:67], s[30:31], 0, v[174:175]
	s_mov_b32 s5, 0x10000
	v_add_co_u32_e32 v88, vcc, s5, v66
	s_mov_b32 s5, 0x30000
	s_nop 0
	v_addc_co_u32_e32 v89, vcc, 0, v67, vcc
	v_add_co_u32_e32 v90, vcc, s79, v66
	v_add_u32_e32 v129, 0x10000, v174
	s_nop 0
	v_addc_co_u32_e32 v91, vcc, 0, v67, vcc
	v_add_co_u32_e32 v86, vcc, s5, v66
	v_add_u32_e32 v132, 0x20000, v174
	s_nop 0
	v_addc_co_u32_e32 v87, vcc, 0, v67, vcc
	v_cmp_eq_u32_e32 vcc, 0, v131
	v_add_u32_e32 v131, 0x20100, v174
	v_readlane_b32 s8, v253, 13
	v_readlane_b32 s9, v253, 14
	s_lshl_b64 s[8:9], s[8:9], 3
	s_add_u32 s2, s2, s8
	v_readlane_b32 s5, v253, 45
	s_addc_u32 s3, s3, s9
	s_lshl_b32 s5, s5, 3
	s_add_u32 s5, s2, s5
	s_addc_u32 s7, s3, 0
	s_lshl_b64 s[2:3], s[34:35], 3
	s_add_u32 s2, s5, s2
	s_addc_u32 s3, s7, s3
	s_waitcnt vmcnt(0)
	global_load_dwordx4 v[120:123], v174, s[30:31]
	global_load_dwordx4 v[66:69], v[86:87], off
	global_load_dwordx4 v[124:127], v[88:89], off
	global_load_dwordx4 v[78:81], v[90:91], off
	v_add_f32_e32 v133, 1.0, v100
	v_add_f32_e32 v134, 1.0, v96
	v_add_f32_e32 v135, 1.0, v101
	v_add_f32_e32 v136, 1.0, v97
	v_add_f32_e32 v137, 1.0, v102
	v_add_f32_e32 v138, 1.0, v98
	v_add_f32_e32 v139, 1.0, v103
	v_add_f32_e32 v140, 1.0, v99
	v_pk_mul_f32 v[118:119], v[118:119], 0.5 op_sel_hi:[1,0]
	v_pk_mul_f32 v[96:97], v[114:115], 0.5 op_sel_hi:[1,0]
	v_pk_mul_f32 v[98:99], v[112:113], 0.5 op_sel_hi:[1,0]
	v_pk_add_f32 v[100:101], v[108:109], 1.0 op_sel_hi:[1,0]
	v_pk_add_f32 v[102:103], v[104:105], 1.0 op_sel_hi:[1,0]
	v_pk_add_f32 v[104:105], v[110:111], 1.0 op_sel_hi:[1,0]
	v_mul_f32_e32 v108, v92, v133
	v_mul_f32_e32 v109, v82, v134
	v_mul_f32_e32 v110, v93, v135
	v_mul_f32_e32 v111, v83, v136
	v_mul_f32_e32 v112, v94, v137
	v_mul_f32_e32 v113, v84, v138
	v_mul_f32_e32 v114, v95, v139
	v_mul_f32_e32 v115, v85, v140
	v_pk_mul_f32 v[74:75], v[74:75], v[100:101]
	v_pk_mul_f32 v[60:61], v[60:61], v[96:97]
	v_pk_mul_f32 v[58:59], v[58:59], v[98:99]
	v_pk_mul_f32 v[84:85], v[76:77], v[104:105]
	v_pk_mul_f32 v[52:53], v[52:53], v[96:97]
	v_pk_mul_f32 v[50:51], v[50:51], v[98:99]
	v_pk_mul_f32 v[76:77], v[44:45], v[96:97]
	v_pk_mul_f32 v[42:43], v[42:43], v[98:99]
	v_pk_mul_f32 v[94:95], v[40:41], v[118:119]
	v_pk_mul_f32 v[96:97], v[36:37], v[96:97]
	v_pk_mul_f32 v[34:35], v[34:35], v[98:99]
	v_rcp_f32_e32 v36, v108
	v_rcp_f32_e32 v40, v109
	v_rcp_f32_e32 v37, v110
	v_rcp_f32_e32 v41, v111
	v_rcp_f32_e32 v98, v112
	v_rcp_f32_e32 v100, v113
	v_rcp_f32_e32 v99, v114
	v_rcp_f32_e32 v101, v115
	v_pk_mul_f32 v[116:117], v[116:117], 0.5 op_sel_hi:[1,0]
	v_pk_add_f32 v[106:107], v[106:107], 1.0 op_sel_hi:[1,0]
	v_pk_mul_f32 v[64:65], v[64:65], v[118:119]
	v_pk_mul_f32 v[62:63], v[62:63], v[116:117]
	v_pk_mul_f32 v[82:83], v[70:71], v[102:103]
	v_pk_mul_f32 v[92:93], v[72:73], v[106:107]
	v_pk_mul_f32 v[72:73], v[48:49], v[118:119]
	v_pk_mul_f32 v[56:57], v[56:57], v[118:119]
	v_pk_mul_f32 v[54:55], v[54:55], v[116:117]
	v_pk_mul_f32 v[46:47], v[46:47], v[116:117]
	v_pk_mul_f32 v[38:39], v[38:39], v[116:117]
	s_waitcnt vmcnt(3)
	v_lshlrev_b32_e32 v44, 16, v120
	v_and_b32_e32 v45, 0xffff0000, v120
	v_lshlrev_b32_e32 v48, 16, v122
	v_and_b32_e32 v49, 0xffff0000, v122
	v_lshlrev_b32_e32 v70, 16, v121
	v_and_b32_e32 v71, 0xffff0000, v121
	v_lshlrev_b32_e32 v102, 16, v123
	v_and_b32_e32 v103, 0xffff0000, v123
	s_waitcnt vmcnt(1)
	v_lshlrev_b32_e32 v104, 16, v124
	v_and_b32_e32 v105, 0xffff0000, v124
	v_lshlrev_b32_e32 v106, 16, v126
	v_and_b32_e32 v107, 0xffff0000, v126
	v_lshlrev_b32_e32 v108, 16, v125
	v_and_b32_e32 v109, 0xffff0000, v125
	v_lshlrev_b32_e32 v110, 16, v127
	v_and_b32_e32 v111, 0xffff0000, v127
	s_waitcnt vmcnt(0)
;     template <int QVV> __device__ __forceinline__ void run(f32x4 (&acc)[2][2][4][2], const Unit& u, int wr, int wc, int fr, int fq) const {
;     ...
;         for (int bj = 0; bj < 2; ++bj) {
;             const unsigned cb4 = (co + bj * HALF) * 4u;
;             f32x4 vg0 = *(const f32x4*)(gp + cb4), vg1 = *(const f32x4*)(gp + cb4 + 16), vp0 = *(const f32x4*)(pgp + cb4), vp1 = *(const f32x4*)(pgp + cb4 + 16), vs0 = *(const f32x4*)(psp + cb4), vs1 = *(const f32x4*)(psp + cb4 + 16);
;             f32x4 vn0 = {1.f, 1.f, 1.f, 1.f}, vn1 = vn0, vt0 = {0.f, 0.f, 0.f, 0.f}, vt1 = vt0;
;             if (hasn) { vn0 = *(const f32x4*)(ngp + cb4); vn1 = *(const f32x4*)(ngp + cb4 + 16); vt0 = *(const f32x4*)(nsp + cb4); vt1 = *(const f32x4*)(nsp + cb4 + 16); }
;             asm volatile("" : "+v"(vg0), "+v"(vg1), "+v"(vp0), "+v"(vp1), "+v"(vs0), "+v"(vs1), "+v"(vn0), "+v"(vn1), "+v"(vt0), "+v"(vt1));
;             const f32x4 g0 = vg0 * fac, g1 = vg1 * fac;
;             const f32x4 p0 = vp0 * (vs0 + 1.0f), p1 = vp1 * (vs1 + 1.0f);
;             f32x4 r0, r1;
; #pragma unroll
;             for (int i = 0; i < 4; ++i) { r0[i] = __builtin_amdgcn_rcpf(p0[i]); r1[i] = __builtin_amdgcn_rcpf(p1[i]); }
;             const f32x4 c0 = vn0 * (vt0 + 1.0f), c1 = vn1 * (vt1 + 1.0f);
;             u32x4 hin[2][4];
; #pragma unroll
;             for (int ai = 0; ai < 2; ++ai)
; #pragma unroll
;                 for (int m = 0; m < 4; ++m) { if (ai == 1 && qm) continue; hin[ai][m] = *(const u32x4*)(sb + lo + (unsigned)((ai * HALF + m * 16) * DM + bj * HALF) * 2u); }
; #pragma unroll
;             for (int ai = 0; ai < 2; ++ai)
; #pragma unroll
;                 for (int m = 0; m < 4; ++m) { if (ai == 1 && qm) continue;
;                     const unsigned off = lo + (unsigned)((ai * HALF + m * 16) * DM + bj * HALF) * 2u;
;                     float hv[8]; unpack8(hin[ai][m], hv);
;                     float y[8]; float t = 0.f;
; #pragma unroll
;                     for (int i = 0; i < 4; ++i) { const float a0 = hv[i] * r0[i] + g0[i] * acc[ai][bj][m][0][i], a1 = hv[4 + i] * r1[i] + g1[i] * acc[ai][bj][m][1][i];
;                         t += a0 * a0 + a1 * a1; y[i] = a0 * c0[i]; y[4 + i] = a1 * c1[i]; }
;                     ss[ai][m] += t;
;                     *(u32x4*)(sb + off) = pack8(y); }
	v_lshlrev_b32_e32 v112, 16, v78
	v_and_b32_e32 v113, 0xffff0000, v78
	v_lshlrev_b32_e32 v114, 16, v80
	v_and_b32_e32 v115, 0xffff0000, v80
	v_lshlrev_b32_e32 v78, 16, v79
	v_and_b32_e32 v79, 0xffff0000, v79
	v_lshlrev_b32_e32 v80, 16, v81
	v_and_b32_e32 v81, 0xffff0000, v81
	v_lshlrev_b32_e32 v116, 16, v66
	v_and_b32_e32 v117, 0xffff0000, v66
	v_lshlrev_b32_e32 v118, 16, v68
	v_and_b32_e32 v119, 0xffff0000, v68
	v_lshlrev_b32_e32 v120, 16, v67
	v_and_b32_e32 v121, 0xffff0000, v67
	v_pk_fma_f32 v[62:63], v[36:37], v[44:45], v[62:63]
	v_pk_fma_f32 v[66:67], v[40:41], v[48:49], v[58:59]
	v_pk_fma_f32 v[64:65], v[98:99], v[70:71], v[64:65]
	v_pk_fma_f32 v[70:71], v[100:101], v[102:103], v[60:61]
	v_pk_fma_f32 v[54:55], v[36:37], v[104:105], v[54:55]
	v_pk_fma_f32 v[58:59], v[40:41], v[106:107], v[50:51]
	v_pk_fma_f32 v[56:57], v[98:99], v[108:109], v[56:57]
	v_pk_fma_f32 v[60:61], v[100:101], v[110:111], v[52:53]
	v_pk_fma_f32 v[44:45], v[36:37], v[112:113], v[46:47]
	v_pk_fma_f32 v[48:49], v[40:41], v[114:115], v[42:43]
	v_pk_fma_f32 v[46:47], v[98:99], v[78:79], v[72:73]
	v_pk_fma_f32 v[50:51], v[100:101], v[80:81], v[76:77]
	v_pk_fma_f32 v[38:39], v[36:37], v[116:117], v[38:39]
	v_pk_fma_f32 v[40:41], v[40:41], v[118:119], v[34:35]
	v_pk_mul_f32 v[34:35], v[74:75], v[62:63]
	v_pk_mul_f32 v[36:37], v[82:83], v[66:67]
	v_pk_mul_f32 v[52:53], v[84:85], v[64:65]
	v_pk_mul_f32 v[72:73], v[92:93], v[70:71]
	v_pk_fma_f32 v[42:43], v[98:99], v[120:121], v[94:95]
	v_pk_mul_f32 v[76:77], v[74:75], v[54:55]
	v_pk_mul_f32 v[78:79], v[82:83], v[58:59]
	v_pk_mul_f32 v[80:81], v[84:85], v[56:57]
	v_pk_mul_f32 v[94:95], v[92:93], v[60:61]
	v_pk_mul_f32 v[98:99], v[74:75], v[44:45]
	v_pk_mul_f32 v[102:103], v[82:83], v[48:49]
	v_pk_mul_f32 v[104:105], v[84:85], v[46:47]
	v_pk_mul_f32 v[106:107], v[92:93], v[50:51]
	v_cvt_pk_bf16_f32 v34, v34, v35
	v_cvt_pk_bf16_f32 v35, v52, v53
	v_cvt_pk_bf16_f32 v36, v36, v37
	v_cvt_pk_bf16_f32 v37, v72, v73
	v_pk_mul_f32 v[108:109], v[74:75], v[38:39]
	v_cvt_pk_bf16_f32 v72, v76, v77
	v_cvt_pk_bf16_f32 v73, v80, v81
	v_cvt_pk_bf16_f32 v74, v78, v79
	v_cvt_pk_bf16_f32 v75, v94, v95
	v_cvt_pk_bf16_f32 v76, v98, v99
	v_cvt_pk_bf16_f32 v77, v104, v105
	v_cvt_pk_bf16_f32 v78, v102, v103
	v_cvt_pk_bf16_f32 v79, v106, v107
	global_store_dwordx4 v174, v[34:37], s[30:31]
	global_store_dwordx4 v129, v[72:75], s[30:31]
	global_store_dwordx4 v132, v[76:79], s[30:31]
	v_lshlrev_b32_e32 v34, 16, v69
	v_and_b32_e32 v35, 0xffff0000, v69
	v_pk_fma_f32 v[52:53], v[100:101], v[34:35], v[96:97]
	v_pk_mul_f32 v[82:83], v[82:83], v[40:41]
	v_pk_mul_f32 v[36:37], v[84:85], v[42:43]
	v_pk_mul_f32 v[68:69], v[92:93], v[52:53]
	v_add_u32_e32 v72, 0x30000, v174
	v_cvt_pk_bf16_f32 v34, v108, v109
	v_cvt_pk_bf16_f32 v35, v36, v37
	v_cvt_pk_bf16_f32 v36, v82, v83
	v_cvt_pk_bf16_f32 v37, v68, v69
	global_store_dwordx4 v72, v[34:37], s[30:31]
	v_pk_mul_f32 v[84:85], v[66:67], v[66:67]
	v_pk_mul_f32 v[70:71], v[70:71], v[70:71]
	v_add_u32_e32 v34, 0x200, v128
	global_load_dwordx4 v[72:75], v34, s[46:47] offset:16
	global_load_dwordx4 v[76:79], v34, s[46:47]
	global_load_dwordx4 v[80:83], v34, s[44:45] offset:16
	global_load_dwordx4 v[92:95], v34, s[44:45]
	global_load_dwordx4 v[96:99], v34, s[42:43] offset:16
	global_load_dwordx4 v[100:103], v34, s[42:43]
	global_load_dwordx4 v[104:107], v34, s[40:41] offset:16
	global_load_dwordx4 v[108:111], v34, s[40:41]
	global_load_dwordx4 v[112:115], v34, s[38:39] offset:16
	global_load_dwordx4 v[116:119], v34, s[38:39]
	s_waitcnt vmcnt(0)
	global_load_dwordx4 v[120:123], v174, s[30:31] offset:256
	global_load_dwordx4 v[124:127], v[88:89], off offset:256
	global_load_dwordx4 v[34:37], v[90:91], off offset:256
	global_load_dwordx4 v[66:69], v[86:87], off offset:256
	v_add_f32_e32 v90, 1.0, v100
	v_add_f32_e32 v91, 1.0, v96
	v_add_f32_e32 v96, 1.0, v101
	v_add_f32_e32 v97, 1.0, v97
	v_add_f32_e32 v100, 1.0, v102
	v_add_f32_e32 v98, 1.0, v98
	v_add_f32_e32 v101, 1.0, v103
	v_add_f32_e32 v99, 1.0, v99
	v_pk_fma_f32 v[84:85], v[62:63], v[62:63], v[84:85]
	v_pk_fma_f32 v[70:71], v[64:65], v[64:65], v[70:71]
	v_pk_mul_f32 v[62:63], v[78:79], 0.5 op_sel_hi:[1,0]
	v_pk_mul_f32 v[64:65], v[76:77], 0.5 op_sel_hi:[1,0]
	v_pk_mul_f32 v[74:75], v[74:75], 0.5 op_sel_hi:[1,0]
	v_pk_mul_f32 v[72:73], v[72:73], 0.5 op_sel_hi:[1,0]
	v_pk_add_f32 v[86:87], v[118:119], 1.0 op_sel_hi:[1,0]
	v_pk_add_f32 v[88:89], v[114:115], 1.0 op_sel_hi:[1,0]
	v_mul_f32_e32 v92, v92, v90
	v_mul_f32_e32 v102, v80, v91
	v_mul_f32_e32 v93, v93, v96
	v_mul_f32_e32 v96, v81, v97
	v_mul_f32_e32 v94, v94, v100
	v_mul_f32_e32 v97, v82, v98
	v_mul_f32_e32 v95, v95, v101
	v_mul_f32_e32 v98, v83, v99
	v_pk_mul_f32 v[32:33], v[32:33], v[62:63]
	v_pk_mul_f32 v[30:31], v[30:31], v[64:65]
	v_pk_mul_f32 v[28:29], v[28:29], v[74:75]
	v_pk_mul_f32 v[26:27], v[26:27], v[72:73]
	v_pk_mul_f32 v[80:81], v[110:111], v[86:87]
	v_pk_mul_f32 v[82:83], v[106:107], v[88:89]
	v_pk_mul_f32 v[86:87], v[24:25], v[62:63]
	v_pk_mul_f32 v[22:23], v[22:23], v[64:65]
	v_pk_mul_f32 v[88:89], v[20:21], v[74:75]
	v_pk_mul_f32 v[20:21], v[18:19], v[72:73]
	v_pk_mul_f32 v[16:17], v[16:17], v[62:63]
	v_pk_mul_f32 v[14:15], v[14:15], v[64:65]
	v_pk_mul_f32 v[90:91], v[12:13], v[74:75]
	v_pk_mul_f32 v[12:13], v[10:11], v[72:73]
	v_pk_mul_f32 v[8:9], v[8:9], v[62:63]
	v_pk_mul_f32 v[6:7], v[6:7], v[64:65]
	v_pk_mul_f32 v[62:63], v[4:5], v[74:75]
	v_pk_mul_f32 v[4:5], v[2:3], v[72:73]
	v_rcp_f32_e32 v2, v92
	v_rcp_f32_e32 v64, v102
	v_rcp_f32_e32 v3, v93
	v_rcp_f32_e32 v65, v96
	v_rcp_f32_e32 v72, v94
	v_rcp_f32_e32 v74, v97
	v_rcp_f32_e32 v73, v95
	v_rcp_f32_e32 v75, v98
	v_pk_add_f32 v[76:77], v[116:117], 1.0 op_sel_hi:[1,0]
	v_pk_add_f32 v[78:79], v[112:113], 1.0 op_sel_hi:[1,0]
	v_pk_mul_f32 v[76:77], v[108:109], v[76:77]
	v_pk_mul_f32 v[78:79], v[104:105], v[78:79]
	v_add_u32_e32 v128, 0x100, v174
	v_add_u32_e32 v129, 0x10100, v174
	s_waitcnt vmcnt(3)
; __device__ __forceinline__ void unpack8(const u32x4 w, float (&f)[8]) { f[0] = bflo(w.x); f[1] = bfhi(w.x); f[2] = bflo(w.y); f[3] = bfhi(w.y); f[4] = bflo(w.z); f[5] = bfhi(w.z); f[6] = bflo(w.w); f[7] = bfhi(w.w); }
; __device__ __forceinline__ u32x4 pack8(const float (&f)[8]) { u32x4 w; w.x = pk2(f[0], f[1]); w.y = pk2(f[2], f[3]); w.z = pk2(f[4], f[5]); w.w = pk2(f[6], f[7]); return w; }
;     template <int QVV> __device__ __forceinline__ void run(f32x4 (&acc)[2][2][4][2], const Unit& u, int wr, int wc, int fr, int fq) const {
;     ...
;                 for (int m = 0; m < 4; ++m) { if (ai == 1 && qm) continue;
;                     const unsigned off = lo + (unsigned)((ai * HALF + m * 16) * DM + bj * HALF) * 2u;
;                     float hv[8]; unpack8(hin[ai][m], hv);
;                     float y[8]; float t = 0.f;
; #pragma unroll
;                     for (int i = 0; i < 4; ++i) { const float a0 = hv[i] * r0[i] + g0[i] * acc[ai][bj][m][0][i], a1 = hv[4 + i] * r1[i] + g1[i] * acc[ai][bj][m][1][i];
;                         t += a0 * a0 + a1 * a1; y[i] = a0 * c0[i]; y[4 + i] = a1 * c1[i]; }
;                     ss[ai][m] += t;
;                     *(u32x4*)(sb + off) = pack8(y); }
;             asm volatile("" ::: "memory");
;         }
;         if (hasn) {
;             unsigned long long* sp = ssq + u.pm * BM + rq + wr * 64 + fr;
; #pragma unroll
;             for (int ai = 0; ai < 2; ++ai)
; #pragma unroll
;                 for (int m = 0; m < 4; ++m) { if (ai == 1 && qm) continue; float t = ss[ai][m]; t += __shfl_xor(t, 16); t += __shfl_xor(t, 32);
;                     const float xs = t * SSQ_SCALE; const unsigned xh = (unsigned)(xs * 2.3283064365386963e-10f), xl = (unsigned)__builtin_fmaf(-(float)xh, 4294967296.0f, xs);
;                     if (fq == 0) atomicAdd(sp + ai * HALF + m * 16, ((unsigned long long)xh << 32) | xl); }
	v_lshlrev_b32_e32 v10, 16, v120
	v_and_b32_e32 v11, 0xffff0000, v120
	v_lshlrev_b32_e32 v18, 16, v122
	v_and_b32_e32 v19, 0xffff0000, v122
	v_lshlrev_b32_e32 v24, 16, v121
	v_and_b32_e32 v25, 0xffff0000, v121
	v_lshlrev_b32_e32 v92, 16, v123
	v_and_b32_e32 v93, 0xffff0000, v123
	s_waitcnt vmcnt(2)
	v_lshlrev_b32_e32 v94, 16, v124
	v_and_b32_e32 v95, 0xffff0000, v124
	v_lshlrev_b32_e32 v96, 16, v126
	v_and_b32_e32 v97, 0xffff0000, v126
	v_lshlrev_b32_e32 v98, 16, v125
	v_and_b32_e32 v99, 0xffff0000, v125
	v_lshlrev_b32_e32 v100, 16, v127
	v_and_b32_e32 v101, 0xffff0000, v127
	s_waitcnt vmcnt(1)
	v_lshlrev_b32_e32 v102, 16, v34
	v_and_b32_e32 v103, 0xffff0000, v34
	v_lshlrev_b32_e32 v104, 16, v36
	v_and_b32_e32 v105, 0xffff0000, v36
	v_lshlrev_b32_e32 v34, 16, v35
	v_and_b32_e32 v35, 0xffff0000, v35
	v_lshlrev_b32_e32 v36, 16, v37
	v_and_b32_e32 v37, 0xffff0000, v37
	s_waitcnt vmcnt(0)
	v_lshlrev_b32_e32 v106, 16, v66
	v_and_b32_e32 v107, 0xffff0000, v66
	v_lshlrev_b32_e32 v108, 16, v68
	v_and_b32_e32 v109, 0xffff0000, v68
	v_lshlrev_b32_e32 v66, 16, v67
	v_and_b32_e32 v67, 0xffff0000, v67
	v_lshlrev_b32_e32 v68, 16, v69
	v_and_b32_e32 v69, 0xffff0000, v69
	v_pk_fma_f32 v[110:111], v[2:3], v[10:11], v[30:31]
	v_pk_fma_f32 v[112:113], v[64:65], v[18:19], v[26:27]
	v_pk_fma_f32 v[114:115], v[72:73], v[24:25], v[32:33]
	v_pk_fma_f32 v[92:93], v[74:75], v[92:93], v[28:29]
	v_pk_fma_f32 v[18:19], v[2:3], v[94:95], v[22:23]
	v_pk_fma_f32 v[24:25], v[64:65], v[96:97], v[20:21]
	v_pk_fma_f32 v[20:21], v[72:73], v[98:99], v[86:87]
	v_pk_fma_f32 v[26:27], v[74:75], v[100:101], v[88:89]
	v_pk_fma_f32 v[10:11], v[2:3], v[102:103], v[14:15]
	v_pk_fma_f32 v[14:15], v[64:65], v[104:105], v[12:13]
	v_pk_fma_f32 v[12:13], v[72:73], v[34:35], v[16:17]
	v_pk_fma_f32 v[16:17], v[74:75], v[36:37], v[90:91]
	v_pk_fma_f32 v[2:3], v[2:3], v[106:107], v[6:7]
	v_pk_fma_f32 v[6:7], v[64:65], v[108:109], v[4:5]
	v_pk_fma_f32 v[4:5], v[72:73], v[66:67], v[8:9]
	v_pk_fma_f32 v[8:9], v[74:75], v[68:69], v[62:63]
	v_pk_mul_f32 v[22:23], v[76:77], v[110:111]
	v_pk_mul_f32 v[30:31], v[78:79], v[112:113]
	v_pk_mul_f32 v[32:33], v[80:81], v[114:115]
	v_pk_mul_f32 v[34:35], v[82:83], v[92:93]
	v_pk_mul_f32 v[36:37], v[76:77], v[18:19]
	v_pk_mul_f32 v[62:63], v[78:79], v[24:25]
	v_pk_mul_f32 v[64:65], v[80:81], v[20:21]
	v_pk_mul_f32 v[66:67], v[82:83], v[26:27]
	v_pk_mul_f32 v[68:69], v[76:77], v[10:11]
	v_pk_mul_f32 v[72:73], v[78:79], v[14:15]
	v_pk_mul_f32 v[74:75], v[80:81], v[12:13]
	v_pk_mul_f32 v[86:87], v[82:83], v[16:17]
	v_pk_mul_f32 v[76:77], v[76:77], v[2:3]
	v_pk_mul_f32 v[78:79], v[78:79], v[6:7]
	v_pk_mul_f32 v[80:81], v[80:81], v[4:5]
	v_cvt_pk_bf16_f32 v28, v22, v23
	v_cvt_pk_bf16_f32 v29, v32, v33
	v_cvt_pk_bf16_f32 v30, v30, v31
	v_cvt_pk_bf16_f32 v31, v34, v35
	v_cvt_pk_bf16_f32 v32, v36, v37
	v_pk_mul_f32 v[22:23], v[82:83], v[8:9]
	v_cvt_pk_bf16_f32 v33, v64, v65
	v_cvt_pk_bf16_f32 v34, v62, v63
	v_cvt_pk_bf16_f32 v35, v66, v67
	v_cvt_pk_bf16_f32 v62, v68, v69
	v_cvt_pk_bf16_f32 v63, v74, v75
	v_cvt_pk_bf16_f32 v64, v72, v73
	v_cvt_pk_bf16_f32 v65, v86, v87
	global_store_dwordx4 v128, v[28:31], s[30:31]
	global_store_dwordx4 v129, v[32:35], s[30:31]
	global_store_dwordx4 v131, v[62:65], s[30:31]
	v_cvt_pk_bf16_f32 v28, v76, v77
	v_add_u32_e32 v32, 0x30100, v174
	v_cvt_pk_bf16_f32 v29, v80, v81
	v_cvt_pk_bf16_f32 v30, v78, v79
	v_cvt_pk_bf16_f32 v31, v22, v23
	global_store_dwordx4 v32, v[28:31], s[30:31]
	v_pk_mul_f32 v[22:23], v[92:93], v[92:93]
	v_lshlrev_b32_e32 v174, 3, v130
	v_pk_mul_f32 v[28:29], v[112:113], v[112:113]
	v_pk_fma_f32 v[22:23], v[114:115], v[114:115], v[22:23]
	v_pk_fma_f32 v[28:29], v[110:111], v[110:111], v[28:29]
	v_add_f32_e32 v30, v84, v85
	v_add_f32_e32 v28, v28, v29
	v_add_f32_e32 v22, v22, v28
	v_add_f32_e32 v22, v23, v22
	v_xor_b32_e32 v23, 16, v230
	v_add_f32_e32 v30, v70, v30
	v_cmp_lt_i32_e64 s[38:39], v23, v232
	v_add_f32_e32 v30, v71, v30
	v_add_f32_e32 v22, v30, v22
	v_cndmask_b32_e64 v23, v230, v23, s[38:39]
	v_lshlrev_b32_e32 v28, 2, v23
	v_mov_b32_e32 v23, v22
	s_nop 1
	v_permlane16_swap_b32 v22, v23
	s_waitcnt lgkmcnt(0)
	v_add_f32_e32 v30, v22, v23
	v_xor_b32_e32 v22, 32, v230
	v_cmp_lt_i32_e64 s[38:39], v22, v232
	s_nop 1
	v_cndmask_b32_e64 v22, v230, v22, s[38:39]
	v_lshlrev_b32_e32 v29, 2, v22
	v_mov_b32_e32 v31, v30
	s_nop 1
	v_permlane32_swap_b32 v30, v31
	v_lshl_add_u64 v[22:23], s[2:3], 0, v[174:175]
	s_and_saveexec_b64 s[30:31], vcc
	s_cbranch_execz .LBB0_1799
	s_waitcnt lgkmcnt(0)
	v_add_f32_e32 v30, v30, v31
	v_mul_f32_e32 v30, 0x49800000, v30
	v_mul_f32_e32 v31, 0x2f800000, v30
	v_cvt_u32_f32_e32 v31, v31
	v_cvt_f32_u32_e32 v32, v31
	v_fmac_f32_e32 v30, 0xcf800000, v32
	v_cvt_u32_f32_e32 v30, v30
	global_atomic_add_x2 v[22:23], v[30:31], off
